# hyena FFT: removed multiply-by-one twiddle no-ops (166 per pass) and folded multiply-by-+-i into one packed op (82 per pass)
# speedup vs baseline: 1.0177x; 1.0056x over previous
; template <int R, bool INV> DEV void dft_regs(cf (&v)[R]) {
;     ...
;     for (int s = R; s >= 2; s >>= 1) {
;         const int h = s >> 1;
; #pragma unroll
;         for (int b = 0; b < R; b += s) {
; #pragma unroll
;             for (int k = 0; k < h; ++k) {
;                 const cf a = v[b + k], c = v[b + k + h];
;                 v[b + k] = a + c;
;                 const cf d = a - c;
;                 const int m = k * (32 / s);
;                 const float wr = tw_cos(m), wi = INV ? tw_sin(m) : -tw_sin(m);
;                 v[b + k + h] = cf{d.x * wr - d.y * wi, d.x * wi + d.y * wr};
;             }
; DEV void fft_i1x2(LAS cf* buf0, LAS cf* buf1, cf (&y0)[8], cf (&y1)[8], int tid) {
;     ...
;     for (int p = 0; p < 16; ++p) { v[p] = cmulc(p0[544 * p], wp); u[p] = cmulc(p1[544 * p], wp); wp = cmul(wp, w); }
;     dft_regs<16, true>(v); dft_regs<16, true>(u);
.LBB0_518:
	v_pk_add_f32 v[126:127], v[76:77], v[100:101]
	v_pk_add_f32 v[76:77], v[76:77], v[100:101] neg_lo:[0,1] neg_hi:[0,1]
	s_mov_b32 s10, s85
	s_mov_b32 s8, s97
	v_mov_b32_e32 v164, v76
	v_mov_b32_e32 v165, v77
	s_xor_b64 s[2:3], s[22:23], -1
	v_pk_add_f32 v[76:77], v[78:79], v[112:113]
	v_pk_add_f32 v[78:79], v[78:79], v[112:113] neg_lo:[0,1] neg_hi:[0,1]
	s_lshl_b64 s[6:7], s[6:7], 2
	v_pk_mul_f32 v[100:101], v[78:79], s[84:85] op_sel_hi:[1,0]
	s_add_u32 s22, s76, s6
	v_pk_fma_f32 v[112:113], v[78:79], s[10:11], v[100:101] op_sel:[0,0,1] op_sel_hi:[1,0,0] neg_lo:[0,0,1] neg_hi:[0,0,1]
	v_pk_fma_f32 v[78:79], v[78:79], s[10:11], v[100:101] op_sel:[0,0,1] op_sel_hi:[1,0,0]
	s_addc_u32 s23, s77, s7
	v_mov_b32_e32 v113, v79
	v_pk_add_f32 v[78:79], v[82:83], v[116:117]
	v_pk_add_f32 v[82:83], v[82:83], v[116:117] neg_lo:[0,1] neg_hi:[0,1]
	s_add_u32 s6, s74, s6
	v_pk_mul_f32 v[100:101], v[82:83], s[8:9] op_sel_hi:[1,0]
	s_waitcnt lgkmcnt(0)
	v_pk_fma_f32 v[116:117], v[82:83], s[8:9], v[100:101] op_sel:[0,0,1] op_sel_hi:[1,0,0] neg_lo:[0,0,1] neg_hi:[0,0,1]
	v_pk_fma_f32 v[82:83], v[82:83], s[8:9], v[100:101] op_sel_hi:[1,0,0]
	v_pk_add_f32 v[100:101], v[84:85], v[118:119]
	v_pk_add_f32 v[84:85], v[84:85], v[118:119] neg_lo:[0,1] neg_hi:[0,1]
	v_mov_b32_e32 v117, v83
	v_pk_mul_f32 v[118:119], v[84:85], s[10:11] op_sel_hi:[1,0]
	s_barrier
	v_pk_fma_f32 v[166:167], v[84:85], s[84:85], v[118:119] op_sel:[0,0,1] op_sel_hi:[1,0,0] neg_lo:[0,0,1] neg_hi:[0,0,1]
	v_pk_fma_f32 v[84:85], v[84:85], s[84:85], v[118:119] op_sel:[0,0,1] op_sel_hi:[1,0,0]
	v_mov_b32_e32 v167, v85
	v_pk_add_f32 v[84:85], v[86:87], v[120:121]
	v_pk_add_f32 v[86:87], v[86:87], v[120:121] neg_lo:[0,1] neg_hi:[0,1]
	s_addc_u32 s7, s75, s7
	v_pk_add_f32 v[118:119], v[86:87], 0 op_sel:[1,0] op_sel_hi:[0,0] neg_lo:[1,0]
	s_mov_b32 s19, 1
	v_pk_add_f32 v[86:87], v[90:91], v[122:123]
	v_pk_add_f32 v[90:91], v[90:91], v[122:123] neg_lo:[0,1] neg_hi:[0,1]
	v_pk_add_f32 v[122:123], v[98:99], v[92:93]
	v_pk_add_f32 v[92:93], v[98:99], v[92:93] neg_lo:[0,1] neg_hi:[0,1]
	v_pk_mul_f32 v[120:121], v[90:91], s[24:25] op_sel:[1,0]
	v_pk_mul_f32 v[98:99], v[92:93], s[84:85] op_sel:[1,0]
	v_pk_fma_f32 v[90:91], v[90:91], s[0:1], v[120:121] op_sel_hi:[0,1,1] neg_lo:[0,0,1] neg_hi:[0,0,1]
	v_pk_fma_f32 v[92:93], v[92:93], s[88:89], v[98:99] op_sel_hi:[0,1,1] neg_lo:[0,0,1] neg_hi:[0,0,1]
	v_pk_add_f32 v[98:99], v[126:127], v[84:85]
	v_pk_add_f32 v[84:85], v[126:127], v[84:85] neg_lo:[0,1] neg_hi:[0,1]
	v_pk_add_f32 v[120:121], v[94:95], v[124:125]
	v_pk_add_f32 v[94:95], v[94:95], v[124:125] neg_lo:[0,1] neg_hi:[0,1]
	v_mul_f32_e32 v82, 0x3f3504f3, v95
	v_mov_b32_e32 v126, v84
	v_mov_b32_e32 v127, v85
	v_pk_fma_f32 v[94:95], v[94:95], s[96:97], v[82:83] op_sel_hi:[0,1,0] neg_lo:[0,0,1] neg_hi:[0,0,1]
	v_pk_add_f32 v[84:85], v[76:77], v[86:87]
	v_pk_add_f32 v[76:77], v[76:77], v[86:87] neg_lo:[0,1] neg_hi:[0,1]
	v_pk_add_f32 v[82:83], v[116:117], v[94:95]
	v_pk_mul_f32 v[86:87], v[76:77], s[8:9] op_sel_hi:[1,0]
	s_mov_b64 s[26:27], -1
	v_pk_fma_f32 v[124:125], v[76:77], s[8:9], v[86:87] op_sel:[0,0,1] op_sel_hi:[1,0,0] neg_lo:[0,0,1] neg_hi:[0,0,1]
	v_pk_fma_f32 v[76:77], v[76:77], s[8:9], v[86:87] op_sel_hi:[1,0,0]
	v_pk_add_f32 v[86:87], v[78:79], v[120:121]
	v_pk_add_f32 v[78:79], v[78:79], v[120:121] neg_lo:[0,1] neg_hi:[0,1]
	v_mov_b32_e32 v125, v77
	v_pk_add_f32 v[120:121], v[78:79], 0 op_sel:[1,0] op_sel_hi:[0,0] neg_lo:[1,0]
	v_pk_add_f32 v[78:79], v[100:101], v[122:123]
	v_pk_add_f32 v[100:101], v[100:101], v[122:123] neg_lo:[0,1] neg_hi:[0,1]
	v_pk_add_f32 v[122:123], v[164:165], v[118:119]
	v_pk_add_f32 v[118:119], v[164:165], v[118:119] neg_lo:[0,1] neg_hi:[0,1]
	v_mul_f32_e32 v76, 0x3f3504f3, v101
	v_pk_fma_f32 v[100:101], v[100:101], s[96:97], v[76:77] op_sel_hi:[0,1,0] neg_lo:[0,0,1] neg_hi:[0,0,1]
	v_mov_b32_e32 v168, v118
	v_mov_b32_e32 v169, v119
	v_pk_add_f32 v[118:119], v[112:113], v[90:91]
	v_pk_add_f32 v[90:91], v[112:113], v[90:91] neg_lo:[0,1] neg_hi:[0,1]
	v_pk_mul_f32 v[112:113], v[90:91], s[8:9] op_sel_hi:[1,0]
	v_pk_fma_f32 v[164:165], v[90:91], s[8:9], v[112:113] op_sel:[0,0,1] op_sel_hi:[1,0,0] neg_lo:[0,0,1] neg_hi:[0,0,1]
	v_pk_fma_f32 v[90:91], v[90:91], s[8:9], v[112:113] op_sel_hi:[1,0,0]
	v_pk_add_f32 v[112:113], v[98:99], v[86:87]
	v_pk_add_f32 v[86:87], v[98:99], v[86:87] neg_lo:[0,1] neg_hi:[0,1]
	v_mov_b32_e32 v165, v91
	v_pk_add_f32 v[90:91], v[116:117], v[94:95] neg_lo:[0,1] neg_hi:[0,1]
	v_mov_b32_e32 v116, v86
	v_mov_b32_e32 v117, v87
	v_pk_add_f32 v[98:99], v[126:127], v[120:121] neg_lo:[0,1] neg_hi:[0,1]
	v_pk_add_f32 v[86:87], v[84:85], v[78:79]
	v_pk_add_f32 v[78:79], v[84:85], v[78:79] neg_lo:[0,1] neg_hi:[0,1]
	v_pk_add_f32 v[94:95], v[90:91], 0 op_sel:[1,0] op_sel_hi:[0,0] neg_lo:[1,0]
	v_pk_add_f32 v[84:85], v[78:79], 0 op_sel:[1,0] op_sel_hi:[0,0] neg_lo:[1,0]
	v_pk_add_f32 v[78:79], v[126:127], v[120:121]
	v_pk_add_f32 v[90:91], v[166:167], v[92:93]
	v_pk_add_f32 v[92:93], v[166:167], v[92:93] neg_lo:[0,1] neg_hi:[0,1]
	v_mov_b32_e32 v126, v98
	v_mov_b32_e32 v127, v99
	v_mul_f32_e32 v76, 0x3f3504f3, v93
	v_pk_add_f32 v[98:99], v[124:125], v[100:101] neg_lo:[0,1] neg_hi:[0,1]
	v_pk_fma_f32 v[92:93], v[92:93], s[96:97], v[76:77] op_sel_hi:[0,1,0] neg_lo:[0,0,1] neg_hi:[0,0,1]
	v_pk_add_f32 v[76:77], v[124:125], v[100:101]
	v_pk_add_f32 v[100:101], v[98:99], 0 op_sel:[1,0] op_sel_hi:[0,0] neg_lo:[1,0]
	v_pk_add_f32 v[120:121], v[122:123], v[82:83]
	v_pk_add_f32 v[82:83], v[122:123], v[82:83] neg_lo:[0,1] neg_hi:[0,1]
	v_pk_add_f32 v[124:125], v[168:169], v[94:95]
	v_mov_b32_e32 v122, v82
	v_mov_b32_e32 v123, v83
	v_pk_add_f32 v[98:99], v[78:79], v[76:77]
; #define SYNC() __syncthreads()
; template <int R, bool INV> DEV void dft_regs(cf (&v)[R]) {
;     ...
;     for (int s = R; s >= 2; s >>= 1) {
;         const int h = s >> 1;
; #pragma unroll
;         for (int b = 0; b < R; b += s) {
; #pragma unroll
;             for (int k = 0; k < h; ++k) {
;                 const cf a = v[b + k], c = v[b + k + h];
;                 v[b + k] = a + c;
;                 const cf d = a - c;
;                 const int m = k * (32 / s);
;                 const float wr = tw_cos(m), wi = INV ? tw_sin(m) : -tw_sin(m);
;                 v[b + k + h] = cf{d.x * wr - d.y * wi, d.x * wi + d.y * wr};
;             }
; DEV void hyena_units(int c0, int cstride, const bf16_t* UT, bf16_t* YHT, const unsigned* KF, const float* convw  , const float* convb  , const float* hyb  , LAS unsigned char* lds, int tid, bool abl = false) {
;     ...
;             SYNC();
;             const int col = (1 + o) * 1024 + c;
;             hyena_conv_rows<1>(lds, 0, convw[col], convw[3072 + col], convw[6144 + col], convb[col], z, y, hyb[o * 1024 + c], tid);
	v_pk_add_f32 v[82:83], v[118:119], v[90:91]
	v_pk_add_f32 v[90:91], v[118:119], v[90:91] neg_lo:[0,1] neg_hi:[0,1]
	v_pk_add_f32 v[76:77], v[16:17], v[88:89]
	v_pk_add_f32 v[118:119], v[90:91], 0 op_sel:[1,0] op_sel_hi:[0,0] neg_lo:[1,0]
	v_pk_add_f32 v[16:17], v[16:17], v[88:89] neg_lo:[0,1] neg_hi:[0,1]
	v_pk_add_f32 v[90:91], v[168:169], v[94:95] neg_lo:[0,1] neg_hi:[0,1]
	v_pk_add_f32 v[112:113], v[112:113], v[86:87]
	v_mov_b32_e32 v166, v90
	v_mov_b32_e32 v167, v91
	v_pk_add_f32 v[94:95], v[164:165], v[92:93]
	v_pk_add_f32 v[90:91], v[164:165], v[92:93] neg_lo:[0,1] neg_hi:[0,1]
	v_pk_add_f32 v[92:93], v[116:117], v[84:85]
	v_mov_b32_e32 v84, v16
	v_mov_b32_e32 v85, v17
	v_pk_add_f32 v[164:165], v[90:91], 0 op_sel:[1,0] op_sel_hi:[0,0] neg_lo:[1,0]
	v_pk_add_f32 v[16:17], v[18:19], v[96:97]
	v_pk_add_f32 v[18:19], v[18:19], v[96:97] neg_lo:[0,1] neg_hi:[0,1]
	v_pk_mul_f32 v[78:79], v[18:19], s[84:85] op_sel_hi:[1,0]
	v_pk_fma_f32 v[88:89], v[18:19], s[10:11], v[78:79] op_sel:[0,0,1] op_sel_hi:[1,0,0] neg_lo:[0,0,1] neg_hi:[0,0,1]
	v_pk_fma_f32 v[18:19], v[18:19], s[10:11], v[78:79] op_sel:[0,0,1] op_sel_hi:[1,0,0]
	v_pk_add_f32 v[90:91], v[122:123], v[118:119]
	v_mov_b32_e32 v89, v19
	v_pk_add_f32 v[18:19], v[66:67], v[102:103]
	v_pk_add_f32 v[66:67], v[66:67], v[102:103] neg_lo:[0,1] neg_hi:[0,1]
	v_pk_add_f32 v[86:87], v[126:127], v[100:101]
	v_pk_mul_f32 v[78:79], v[66:67], s[8:9] op_sel_hi:[1,0]
	v_pk_add_f32 v[100:101], v[120:121], v[82:83]
	v_pk_fma_f32 v[96:97], v[66:67], s[8:9], v[78:79] op_sel:[0,0,1] op_sel_hi:[1,0,0] neg_lo:[0,0,1] neg_hi:[0,0,1]
	v_pk_fma_f32 v[66:67], v[66:67], s[8:9], v[78:79] op_sel_hi:[1,0,0]
	v_pk_add_f32 v[94:95], v[124:125], v[94:95]
	v_mov_b32_e32 v97, v67
	v_pk_add_f32 v[66:67], v[68:69], v[104:105]
	v_pk_add_f32 v[68:69], v[68:69], v[104:105] neg_lo:[0,1] neg_hi:[0,1]
	v_pk_add_f32 v[82:83], v[166:167], v[164:165]
	v_pk_mul_f32 v[78:79], v[68:69], s[10:11] op_sel_hi:[1,0]
	v_pk_fma_f32 v[102:103], v[68:69], s[84:85], v[78:79] op_sel:[0,0,1] op_sel_hi:[1,0,0] neg_lo:[0,0,1] neg_hi:[0,0,1]
	v_pk_fma_f32 v[68:69], v[68:69], s[84:85], v[78:79] op_sel:[0,0,1] op_sel_hi:[1,0,0]
	v_mov_b32_e32 v103, v69
	v_pk_add_f32 v[68:69], v[70:71], v[106:107]
	v_pk_add_f32 v[70:71], v[70:71], v[106:107] neg_lo:[0,1] neg_hi:[0,1]
	v_pk_add_f32 v[78:79], v[70:71], 0 op_sel:[1,0] op_sel_hi:[0,0] neg_lo:[1,0]
	v_pk_add_f32 v[70:71], v[72:73], v[108:109]
	v_pk_add_f32 v[72:73], v[72:73], v[108:109] neg_lo:[0,1] neg_hi:[0,1]
	v_pk_add_f32 v[120:121], v[84:85], v[78:79]
	v_pk_mul_f32 v[104:105], v[72:73], s[24:25] op_sel:[1,0]
	v_pk_fma_f32 v[72:73], v[72:73], s[0:1], v[104:105] op_sel_hi:[0,1,1] neg_lo:[0,0,1] neg_hi:[0,0,1]
	v_pk_add_f32 v[104:105], v[74:75], v[110:111]
	v_pk_add_f32 v[74:75], v[74:75], v[110:111] neg_lo:[0,1] neg_hi:[0,1]
	v_pk_add_f32 v[116:117], v[18:19], v[104:105]
	v_mul_f32_e32 v106, 0x3f3504f3, v75
	v_pk_fma_f32 v[74:75], v[74:75], s[96:97], v[106:107] op_sel_hi:[0,1,0] neg_lo:[0,0,1] neg_hi:[0,0,1]
	v_pk_add_f32 v[106:107], v[80:81], v[114:115]
	v_pk_add_f32 v[80:81], v[80:81], v[114:115] neg_lo:[0,1] neg_hi:[0,1]
	v_pk_add_f32 v[118:119], v[66:67], v[106:107]
	v_pk_mul_f32 v[108:109], v[80:81], s[84:85] op_sel:[1,0]
	v_pk_fma_f32 v[80:81], v[80:81], s[88:89], v[108:109] op_sel_hi:[0,1,1] neg_lo:[0,0,1] neg_hi:[0,0,1]
	v_pk_add_f32 v[108:109], v[76:77], v[68:69]
	v_pk_add_f32 v[68:69], v[76:77], v[68:69] neg_lo:[0,1] neg_hi:[0,1]
	v_mov_b32_e32 v110, v68
	v_mov_b32_e32 v111, v69
	v_pk_add_f32 v[76:77], v[16:17], v[70:71]
	v_pk_add_f32 v[16:17], v[16:17], v[70:71] neg_lo:[0,1] neg_hi:[0,1]
	v_pk_mul_f32 v[68:69], v[16:17], s[8:9] op_sel_hi:[1,0]
	v_pk_fma_f32 v[114:115], v[16:17], s[8:9], v[68:69] op_sel:[0,0,1] op_sel_hi:[1,0,0] neg_lo:[0,0,1] neg_hi:[0,0,1]
	v_pk_fma_f32 v[16:17], v[16:17], s[8:9], v[68:69] op_sel_hi:[1,0,0]
	v_mov_b32_e32 v115, v17
	v_pk_add_f32 v[16:17], v[18:19], v[104:105] neg_lo:[0,1] neg_hi:[0,1]
	v_pk_add_f32 v[104:105], v[16:17], 0 op_sel:[1,0] op_sel_hi:[0,0] neg_lo:[1,0]
	v_pk_add_f32 v[16:17], v[66:67], v[106:107] neg_lo:[0,1] neg_hi:[0,1]
	v_mul_f32_e32 v18, 0x3f3504f3, v17
	v_pk_fma_f32 v[106:107], v[16:17], s[96:97], v[18:19] op_sel_hi:[0,1,0] neg_lo:[0,0,1] neg_hi:[0,0,1]
	v_pk_add_f32 v[16:17], v[84:85], v[78:79] neg_lo:[0,1] neg_hi:[0,1]
	v_pk_add_f32 v[84:85], v[88:89], v[72:73]
	v_mov_b32_e32 v78, v16
	v_mov_b32_e32 v79, v17
	v_pk_add_f32 v[16:17], v[88:89], v[72:73] neg_lo:[0,1] neg_hi:[0,1]
	v_pk_add_f32 v[88:89], v[96:97], v[74:75]
	v_pk_mul_f32 v[18:19], v[16:17], s[8:9] op_sel_hi:[1,0]
	v_pk_fma_f32 v[72:73], v[16:17], s[8:9], v[18:19] op_sel:[0,0,1] op_sel_hi:[1,0,0] neg_lo:[0,0,1] neg_hi:[0,0,1]
	v_pk_fma_f32 v[16:17], v[16:17], s[8:9], v[18:19] op_sel_hi:[1,0,0]
	v_mov_b32_e32 v73, v17
	v_pk_add_f32 v[16:17], v[96:97], v[74:75] neg_lo:[0,1] neg_hi:[0,1]
	v_pk_add_f32 v[96:97], v[102:103], v[80:81]
	v_pk_fma_f32 v[74:75], v[16:17], 0, v[16:17] op_sel:[0,0,1] op_sel_hi:[1,0,0] neg_lo:[0,0,1] neg_hi:[0,0,1]
	v_pk_fma_f32 v[16:17], v[16:17], 0, v[16:17] op_sel:[0,0,1] op_sel_hi:[1,0,0]
	global_load_dword v18, v20, s[22:23]
	global_load_dword v66, v245, s[22:23]
	global_load_dword v16, v206, s[22:23]
	s_add_i32 s22, s5, s78
	s_ashr_i32 s23, s22, 31
	s_lshl_b64 s[22:23], s[22:23], 2
	s_add_u32 s22, s72, s22
	s_addc_u32 s23, s73, s23
	global_load_dword v68, v20, s[6:7]
	global_load_dword v70, v20, s[22:23]
	v_pk_add_f32 v[80:81], v[102:103], v[80:81] neg_lo:[0,1] neg_hi:[0,1]
	v_mov_b32_e32 v75, v17
	v_mul_f32_e32 v102, 0x3f3504f3, v81
	v_pk_fma_f32 v[80:81], v[80:81], s[96:97], v[102:103] op_sel_hi:[0,1,0] neg_lo:[0,0,1] neg_hi:[0,0,1]
; #define LAS __attribute__((address_space(3)))
; #define U2F(x) __uint_as_float(x)
; template <int R, bool INV> DEV void dft_regs(cf (&v)[R]) {
;     ...
;     for (int s = R; s >= 2; s >>= 1) {
;         const int h = s >> 1;
; #pragma unroll
;         for (int b = 0; b < R; b += s) {
; #pragma unroll
;             for (int k = 0; k < h; ++k) {
;                 const cf a = v[b + k], c = v[b + k + h];
;                 v[b + k] = a + c;
;                 const cf d = a - c;
;                 const int m = k * (32 / s);
;                 const float wr = tw_cos(m), wi = INV ? tw_sin(m) : -tw_sin(m);
;                 v[b + k + h] = cf{d.x * wr - d.y * wi, d.x * wi + d.y * wr};
;             }
; template <int MODE> DEV void hyena_conv_rows(const LAS unsigned char* lds, int slot0, float w0, float w1, float w2, float bs, cf (&z)[2][8], const cf (&y)[2][8], float hb, int tid) {
;     ...
;     for (int b = 0; b < 4; ++b) {
;         const LAS bf16_t* row = (const LAS bf16_t*)(lds + (slot0 + b) * 8192);
; #pragma unroll
;         for (int i = 0; i < 8; ++i) {
;             const int t = tid + 512 * i, par = tid & 1, d0 = (tid >> 1) + par;
;             const LAS unsigned* rw = (const LAS unsigned*)row + d0;
;             const unsigned dw0 = (i == 0) ? rw[d0 > 0 ? -1 : 0] : rw[256 * i - 1], dw1 = rw[256 * i];
;             float um = par ? U2F(dw0 << 16) : U2F(dw0 & 0xffff0000u);
;             const float u0 = par ? U2F(dw0 & 0xffff0000u) : U2F(dw1 << 16);
;             float up = par ? U2F(dw1 << 16) : U2F(dw1 & 0xffff0000u);
;             um = (t > 0) ? um : 0.f; up = (t < 4095) ? up : 0.f;
;             const float r = um * w0 + u0 * w1 + up * w2 + bs;
;             if (MODE == 0) { if (b & 1) z[b >> 1][i].y = r; else z[b >> 1][i].x = r; }
;             else { if (b & 1) z[b >> 1][i].y = r * (y[b >> 1][i].y + hb * z[b >> 1][i].y); else z[b >> 1][i].x = r * (y[b >> 1][i].x + hb * z[b >> 1][i].x); }
	v_pk_add_f32 v[102:103], v[108:109], v[116:117]
	v_pk_add_f32 v[108:109], v[108:109], v[116:117] neg_lo:[0,1] neg_hi:[0,1]
	v_pk_add_f32 v[124:125], v[78:79], v[74:75]
	v_pk_add_f32 v[74:75], v[78:79], v[74:75] neg_lo:[0,1] neg_hi:[0,1]
	v_mov_b32_e32 v122, v108
	v_mov_b32_e32 v123, v109
	v_pk_add_f32 v[108:109], v[76:77], v[118:119]
	v_pk_add_f32 v[76:77], v[76:77], v[118:119] neg_lo:[0,1] neg_hi:[0,1]
	v_mov_b32_e32 v126, v74
	v_mov_b32_e32 v127, v75
	v_pk_add_f32 v[116:117], v[76:77], 0 op_sel:[1,0] op_sel_hi:[0,0] neg_lo:[1,0]
	v_pk_add_f32 v[76:77], v[110:111], v[104:105]
	v_pk_add_f32 v[104:105], v[110:111], v[104:105] neg_lo:[0,1] neg_hi:[0,1]
	v_pk_add_f32 v[78:79], v[122:123], v[116:117]
	v_mov_b32_e32 v118, v104
	v_mov_b32_e32 v119, v105
	v_pk_add_f32 v[164:165], v[72:73], v[80:81]
	v_pk_add_f32 v[104:105], v[114:115], v[106:107]
	v_pk_add_f32 v[106:107], v[114:115], v[106:107] neg_lo:[0,1] neg_hi:[0,1]
	v_pk_add_f32 v[72:73], v[72:73], v[80:81] neg_lo:[0,1] neg_hi:[0,1]
	v_pk_add_f32 v[110:111], v[106:107], 0 op_sel:[1,0] op_sel_hi:[0,0] neg_lo:[1,0]
	v_pk_add_f32 v[80:81], v[124:125], v[164:165]
	v_pk_add_f32 v[106:107], v[120:121], v[88:89]
	v_pk_add_f32 v[88:89], v[120:121], v[88:89] neg_lo:[0,1] neg_hi:[0,1]
	v_pk_add_f32 v[74:75], v[118:119], v[110:111]
	v_pk_fma_f32 v[166:167], v[72:73], 0, v[72:73] op_sel:[0,0,1] op_sel_hi:[1,0,0] neg_lo:[0,0,1] neg_hi:[0,0,1]
	v_mov_b32_e32 v120, v88
	v_mov_b32_e32 v121, v89
	v_pk_fma_f32 v[72:73], v[72:73], 0, v[72:73] op_sel:[0,0,1] op_sel_hi:[1,0,0]
	v_pk_add_f32 v[88:89], v[84:85], v[96:97]
	v_pk_add_f32 v[84:85], v[84:85], v[96:97] neg_lo:[0,1] neg_hi:[0,1]
	v_pk_add_f32 v[96:97], v[102:103], v[108:109]
	ds_read2st64_b32 v[102:103], v130 offset1:32
	v_pk_add_f32 v[114:115], v[84:85], 0 op_sel:[1,0] op_sel_hi:[0,0] neg_lo:[1,0]
	v_pk_add_f32 v[88:89], v[106:107], v[88:89]
	v_pk_add_f32 v[84:85], v[76:77], v[104:105]
	ds_read2st64_b32 v[104:105], v129 offset1:32
	s_waitcnt lgkmcnt(1)
	v_and_b32_e32 v17, 0xffff0000, v103
	v_and_b32_e32 v19, 0xffff0000, v102
	v_lshlrev_b32_e32 v67, 16, v103
	v_lshlrev_b32_e32 v69, 16, v102
	v_cndmask_b32_e64 v69, v69, v19, s[38:39]
	v_cndmask_b32_e64 v67, v67, v17, s[38:39]
	v_cndmask_b32_e64 v103, 0, v67, s[40:41]
	v_cndmask_b32_e64 v102, 0, v69, s[40:41]
	s_waitcnt lgkmcnt(0)
	v_lshlrev_b32_e32 v67, 16, v104
	v_lshlrev_b32_e32 v69, 16, v105
	v_cndmask_b32_e64 v107, v17, v69, s[38:39]
	v_cndmask_b32_e64 v106, v19, v67, s[38:39]
	v_and_b32_e32 v17, 0xffff0000, v105
	v_cndmask_b32_e64 v17, v69, v17, s[38:39]
	v_cndmask_b32_e64 v105, 0, v17, s[42:43]
	v_pk_add_f32 v[76:77], v[120:121], v[114:115]
	v_mov_b32_e32 v167, v73
	s_waitcnt vmcnt(3)
	v_pk_mul_f32 v[106:107], v[66:67], v[106:107] op_sel_hi:[0,1]
	v_pk_fma_f32 v[102:103], v[18:19], v[102:103], v[106:107] op_sel_hi:[0,1,1]
	v_and_b32_e32 v19, 0xffff0000, v104
	v_cndmask_b32_e64 v19, v67, v19, s[38:39]
	v_cndmask_b32_e64 v104, 0, v19, s[42:43]
	s_waitcnt vmcnt(2)
	v_pk_fma_f32 v[102:103], v[16:17], v[104:105], v[102:103] op_sel_hi:[0,1,1]
	s_waitcnt vmcnt(1)
	v_pk_add_f32 v[102:103], v[68:69], v[102:103] op_sel_hi:[0,1]
	s_waitcnt vmcnt(0)
	v_pk_fma_f32 v[24:25], v[24:25], v[70:71], v[112:113] op_sel_hi:[1,0,1]
	v_pk_fma_f32 v[30:31], v[30:31], v[70:71], v[100:101] op_sel_hi:[1,0,1]
	v_pk_mul_f32 v[24:25], v[24:25], v[102:103]
	ds_read2_b32 v[106:107], v138 offset1:1
	ds_read2_b32 v[108:109], v131 offset1:1
	ds_read2_b32 v[110:111], v135 offset1:1
	ds_read2_b32 v[102:103], v136 offset1:1
	ds_read2_b32 v[104:105], v137 offset1:1
	s_waitcnt lgkmcnt(4)
	v_and_b32_e32 v17, 0xffff0000, v106
	s_waitcnt lgkmcnt(3)
	v_and_b32_e32 v19, 0xffff0000, v108
	v_lshlrev_b32_e32 v67, 16, v106
	v_lshlrev_b32_e32 v69, 16, v108
	v_cndmask_b32_e64 v69, v69, v19, s[38:39]
	v_cndmask_b32_e64 v67, v67, v17, s[38:39]
	v_cndmask_b32_e64 v119, 0, v67, s[44:45]
	v_cndmask_b32_e64 v118, 0, v69, s[44:45]
	v_lshlrev_b32_e32 v67, 16, v109
	v_lshlrev_b32_e32 v69, 16, v107
	v_cndmask_b32_e64 v121, v17, v69, s[38:39]
	v_cndmask_b32_e64 v120, v19, v67, s[38:39]
	ds_read2_b32 v[112:113], v132 offset1:1
	ds_read2_b32 v[114:115], v133 offset1:1
	ds_read2_b32 v[116:117], v134 offset1:1
	v_pk_mul_f32 v[120:121], v[66:67], v[120:121] op_sel_hi:[0,1]
	ds_read2_b32 v[100:101], v139 offset1:1
	v_pk_fma_f32 v[118:119], v[18:19], v[118:119], v[120:121] op_sel_hi:[0,1,1]
	v_and_b32_e32 v17, 0xffff0000, v107
	v_and_b32_e32 v19, 0xffff0000, v109
	v_cndmask_b32_e64 v19, v67, v19, s[38:39]
	v_cndmask_b32_e64 v17, v69, v17, s[38:39]
	v_cndmask_b32_e64 v107, 0, v17, s[46:47]
	v_cndmask_b32_e64 v106, 0, v19, s[46:47]
	v_pk_fma_f32 v[106:107], v[16:17], v[106:107], v[118:119] op_sel_hi:[0,1,1]
	v_pk_add_f32 v[106:107], v[68:69], v[106:107] op_sel_hi:[0,1]
	s_waitcnt lgkmcnt(0)
	v_and_b32_e32 v17, 0xffff0000, v100
	v_and_b32_e32 v19, 0xffff0000, v112
	v_lshlrev_b32_e32 v67, 16, v100
	v_lshlrev_b32_e32 v69, 16, v112
	v_cndmask_b32_e64 v69, v69, v19, s[38:39]
	v_cndmask_b32_e64 v67, v67, v17, s[38:39]
	v_cndmask_b32_e64 v121, 0, v67, s[48:49]
	v_cndmask_b32_e64 v120, 0, v69, s[48:49]
	v_lshlrev_b32_e32 v67, 16, v113
	v_lshlrev_b32_e32 v69, 16, v101
	v_cndmask_b32_e64 v123, v17, v69, s[38:39]
	v_cndmask_b32_e64 v122, v19, v67, s[38:39]
	v_pk_mul_f32 v[122:123], v[66:67], v[122:123] op_sel_hi:[0,1]
	v_pk_fma_f32 v[120:121], v[18:19], v[120:121], v[122:123] op_sel_hi:[0,1,1]
	v_and_b32_e32 v17, 0xffff0000, v101
	v_and_b32_e32 v19, 0xffff0000, v113
	v_pk_mul_f32 v[30:31], v[30:31], v[106:107]
	ds_read2_b32 v[106:107], v140 offset1:1
	ds_read2_b32 v[108:109], v141 offset1:1
	ds_read2_b32 v[118:119], v142 offset1:1
	v_cndmask_b32_e64 v19, v67, v19, s[38:39]
	v_cndmask_b32_e64 v17, v69, v17, s[38:39]
	v_cndmask_b32_e64 v101, 0, v17, s[50:51]
	v_cndmask_b32_e64 v100, 0, v19, s[50:51]
	v_pk_fma_f32 v[100:101], v[16:17], v[100:101], v[120:121] op_sel_hi:[0,1,1]
	v_pk_add_f32 v[100:101], v[68:69], v[100:101] op_sel_hi:[0,1]
	s_waitcnt lgkmcnt(2)
; #define LAS __attribute__((address_space(3)))
; #define U2F(x) __uint_as_float(x)
; template <int MODE> DEV void hyena_conv_rows(const LAS unsigned char* lds, int slot0, float w0, float w1, float w2, float bs, cf (&z)[2][8], const cf (&y)[2][8], float hb, int tid) {
;     ...
;     for (int b = 0; b < 4; ++b) {
;         const LAS bf16_t* row = (const LAS bf16_t*)(lds + (slot0 + b) * 8192);
; #pragma unroll
;         for (int i = 0; i < 8; ++i) {
;             const int t = tid + 512 * i, par = tid & 1, d0 = (tid >> 1) + par;
;             const LAS unsigned* rw = (const LAS unsigned*)row + d0;
;             const unsigned dw0 = (i == 0) ? rw[d0 > 0 ? -1 : 0] : rw[256 * i - 1], dw1 = rw[256 * i];
;             float um = par ? U2F(dw0 << 16) : U2F(dw0 & 0xffff0000u);
;             const float u0 = par ? U2F(dw0 & 0xffff0000u) : U2F(dw1 << 16);
;             float up = par ? U2F(dw1 << 16) : U2F(dw1 & 0xffff0000u);
;             um = (t > 0) ? um : 0.f; up = (t < 4095) ? up : 0.f;
;             const float r = um * w0 + u0 * w1 + up * w2 + bs;
;             if (MODE == 0) { if (b & 1) z[b >> 1][i].y = r; else z[b >> 1][i].x = r; }
;             else { if (b & 1) z[b >> 1][i].y = r * (y[b >> 1][i].y + hb * z[b >> 1][i].y); else z[b >> 1][i].x = r * (y[b >> 1][i].x + hb * z[b >> 1][i].x); }
	v_and_b32_e32 v17, 0xffff0000, v106
	v_and_b32_e32 v19, 0xffff0000, v114
	v_lshlrev_b32_e32 v67, 16, v106
	v_lshlrev_b32_e32 v69, 16, v114
	v_cndmask_b32_e64 v69, v69, v19, s[38:39]
	v_cndmask_b32_e64 v67, v67, v17, s[38:39]
	v_pk_fma_f32 v[28:29], v[28:29], v[70:71], v[98:99] op_sel_hi:[1,0,1]
	v_cndmask_b32_e64 v99, 0, v67, s[52:53]
	v_cndmask_b32_e64 v98, 0, v69, s[52:53]
	v_lshlrev_b32_e32 v67, 16, v115
	v_lshlrev_b32_e32 v69, 16, v107
	v_pk_mul_f32 v[28:29], v[28:29], v[100:101]
	v_cndmask_b32_e64 v101, v17, v69, s[38:39]
	v_cndmask_b32_e64 v100, v19, v67, s[38:39]
	v_pk_mul_f32 v[100:101], v[66:67], v[100:101] op_sel_hi:[0,1]
	v_pk_fma_f32 v[98:99], v[18:19], v[98:99], v[100:101] op_sel_hi:[0,1,1]
	v_and_b32_e32 v17, 0xffff0000, v107
	v_and_b32_e32 v19, 0xffff0000, v115
	v_cndmask_b32_e64 v19, v67, v19, s[38:39]
	v_cndmask_b32_e64 v17, v69, v17, s[38:39]
	v_cndmask_b32_e64 v101, 0, v17, s[54:55]
	v_cndmask_b32_e64 v100, 0, v19, s[54:55]
	v_pk_fma_f32 v[98:99], v[16:17], v[100:101], v[98:99] op_sel_hi:[0,1,1]
	v_pk_add_f32 v[98:99], v[68:69], v[98:99] op_sel_hi:[0,1]
	s_waitcnt lgkmcnt(1)
	v_and_b32_e32 v17, 0xffff0000, v108
	v_and_b32_e32 v19, 0xffff0000, v116
	v_lshlrev_b32_e32 v67, 16, v108
	v_lshlrev_b32_e32 v69, 16, v116
	v_cndmask_b32_e64 v69, v69, v19, s[38:39]
	v_cndmask_b32_e64 v67, v67, v17, s[38:39]
	v_pk_fma_f32 v[26:27], v[26:27], v[70:71], v[94:95] op_sel_hi:[1,0,1]
	v_cndmask_b32_e64 v95, 0, v67, s[56:57]
	v_cndmask_b32_e64 v94, 0, v69, s[56:57]
	v_lshlrev_b32_e32 v67, 16, v117
	v_lshlrev_b32_e32 v69, 16, v109
	v_pk_mul_f32 v[26:27], v[26:27], v[98:99]
	v_cndmask_b32_e64 v99, v17, v69, s[38:39]
	v_cndmask_b32_e64 v98, v19, v67, s[38:39]
	v_pk_mul_f32 v[98:99], v[66:67], v[98:99] op_sel_hi:[0,1]
	v_pk_fma_f32 v[94:95], v[18:19], v[94:95], v[98:99] op_sel_hi:[0,1,1]
	v_and_b32_e32 v17, 0xffff0000, v109
	v_and_b32_e32 v19, 0xffff0000, v117
	v_cndmask_b32_e64 v19, v67, v19, s[38:39]
	v_cndmask_b32_e64 v17, v69, v17, s[38:39]
	v_cndmask_b32_e64 v99, 0, v17, s[58:59]
	v_cndmask_b32_e64 v98, 0, v19, s[58:59]
	v_pk_fma_f32 v[94:95], v[16:17], v[98:99], v[94:95] op_sel_hi:[0,1,1]
	v_pk_add_f32 v[94:95], v[68:69], v[94:95] op_sel_hi:[0,1]
	s_waitcnt lgkmcnt(0)
	v_and_b32_e32 v17, 0xffff0000, v118
	v_and_b32_e32 v19, 0xffff0000, v110
	v_lshlrev_b32_e32 v67, 16, v118
	v_lshlrev_b32_e32 v69, 16, v110
	v_cndmask_b32_e64 v69, v69, v19, s[38:39]
	v_cndmask_b32_e64 v67, v67, v17, s[38:39]
	v_pk_fma_f32 v[22:23], v[22:23], v[70:71], v[92:93] op_sel_hi:[1,0,1]
	v_cndmask_b32_e64 v93, 0, v67, s[60:61]
	v_cndmask_b32_e64 v92, 0, v69, s[60:61]
	v_lshlrev_b32_e32 v67, 16, v111
	v_lshlrev_b32_e32 v69, 16, v119
	v_pk_mul_f32 v[22:23], v[22:23], v[94:95]
	v_cndmask_b32_e64 v95, v17, v69, s[38:39]
	v_cndmask_b32_e64 v94, v19, v67, s[38:39]
	v_pk_mul_f32 v[94:95], v[66:67], v[94:95] op_sel_hi:[0,1]
	v_pk_fma_f32 v[92:93], v[18:19], v[92:93], v[94:95] op_sel_hi:[0,1,1]
	v_and_b32_e32 v17, 0xffff0000, v119
	v_and_b32_e32 v19, 0xffff0000, v111
	v_cndmask_b32_e64 v19, v67, v19, s[38:39]
	v_cndmask_b32_e64 v17, v69, v17, s[38:39]
	v_cndmask_b32_e64 v95, 0, v17, s[62:63]
	v_cndmask_b32_e64 v94, 0, v19, s[62:63]
	v_pk_fma_f32 v[92:93], v[16:17], v[94:95], v[92:93] op_sel_hi:[0,1,1]
	ds_read2_b32 v[94:95], v143 offset1:1
	v_pk_add_f32 v[92:93], v[68:69], v[92:93] op_sel_hi:[0,1]
	v_and_b32_e32 v19, 0xffff0000, v102
	v_lshlrev_b32_e32 v69, 16, v102
	v_cndmask_b32_e64 v69, v69, v19, s[38:39]
	s_waitcnt lgkmcnt(0)
	v_and_b32_e32 v17, 0xffff0000, v94
	v_lshlrev_b32_e32 v67, 16, v94
	v_cndmask_b32_e64 v67, v67, v17, s[38:39]
	v_cndmask_b32_e64 v101, 0, v67, s[64:65]
	v_cndmask_b32_e64 v100, 0, v69, s[64:65]
	v_lshlrev_b32_e32 v67, 16, v103
	v_lshlrev_b32_e32 v69, 16, v95
	v_cndmask_b32_e64 v107, v17, v69, s[38:39]
	v_cndmask_b32_e64 v106, v19, v67, s[38:39]
	v_pk_mul_f32 v[106:107], v[66:67], v[106:107] op_sel_hi:[0,1]
	v_pk_fma_f32 v[32:33], v[32:33], v[70:71], v[90:91] op_sel_hi:[1,0,1]
	v_pk_fma_f32 v[100:101], v[18:19], v[100:101], v[106:107] op_sel_hi:[0,1,1]
	v_and_b32_e32 v17, 0xffff0000, v95
	v_and_b32_e32 v19, 0xffff0000, v103
	v_pk_mul_f32 v[32:33], v[32:33], v[92:93]
	ds_read2_b32 v[98:99], v144 offset1:1
	ds_read2_b32 v[90:91], v145 offset1:1
	ds_read2_b32 v[92:93], v146 offset1:1
	v_cndmask_b32_e64 v19, v67, v19, s[38:39]
	v_cndmask_b32_e64 v17, v69, v17, s[38:39]
	v_cndmask_b32_e64 v95, 0, v17, s[66:67]
	v_cndmask_b32_e64 v94, 0, v19, s[66:67]
	v_pk_fma_f32 v[94:95], v[16:17], v[94:95], v[100:101] op_sel_hi:[0,1,1]
	v_pk_add_f32 v[94:95], v[68:69], v[94:95] op_sel_hi:[0,1]
	s_waitcnt lgkmcnt(2)
	v_and_b32_e32 v17, 0xffff0000, v98
	v_and_b32_e32 v19, 0xffff0000, v104
	v_lshlrev_b32_e32 v67, 16, v98
	v_lshlrev_b32_e32 v69, 16, v104
	v_cndmask_b32_e64 v69, v69, v19, s[38:39]
	v_cndmask_b32_e64 v67, v67, v17, s[38:39]
	v_pk_fma_f32 v[34:35], v[34:35], v[70:71], v[86:87] op_sel_hi:[1,0,1]
	v_cndmask_b32_e64 v87, 0, v67, s[68:69]
	v_cndmask_b32_e64 v86, 0, v69, s[68:69]
	v_lshlrev_b32_e32 v67, 16, v105
	v_lshlrev_b32_e32 v69, 16, v99
	v_pk_mul_f32 v[34:35], v[34:35], v[94:95]
	v_cndmask_b32_e64 v95, v17, v69, s[38:39]
	v_cndmask_b32_e64 v94, v19, v67, s[38:39]
	v_pk_mul_f32 v[94:95], v[66:67], v[94:95] op_sel_hi:[0,1]
	v_pk_fma_f32 v[86:87], v[18:19], v[86:87], v[94:95] op_sel_hi:[0,1,1]
	v_and_b32_e32 v17, 0xffff0000, v99
	v_and_b32_e32 v19, 0xffff0000, v105
	v_cndmask_b32_e64 v19, v67, v19, s[38:39]
	v_cndmask_b32_e64 v17, v69, v17, s[38:39]
	v_cndmask_b32_e64 v95, 0, v17, s[70:71]
	v_cndmask_b32_e64 v94, 0, v19, s[70:71]
	v_pk_fma_f32 v[86:87], v[16:17], v[94:95], v[86:87] op_sel_hi:[0,1,1]
	ds_read2st64_b32 v[94:95], v130 offset0:64 offset1:96
	v_pk_fma_f32 v[36:37], v[36:37], v[70:71], v[82:83] op_sel_hi:[1,0,1]
	ds_read2st64_b32 v[82:83], v129 offset0:64 offset1:96
	v_pk_add_f32 v[86:87], v[68:69], v[86:87] op_sel_hi:[0,1]
	v_pk_mul_f32 v[36:37], v[36:37], v[86:87]
	s_waitcnt lgkmcnt(1)
; #define LAS __attribute__((address_space(3)))
; #define U2F(x) __uint_as_float(x)
; template <int MODE> DEV void hyena_conv_rows(const LAS unsigned char* lds, int slot0, float w0, float w1, float w2, float bs, cf (&z)[2][8], const cf (&y)[2][8], float hb, int tid) {
;     ...
;     for (int b = 0; b < 4; ++b) {
;         const LAS bf16_t* row = (const LAS bf16_t*)(lds + (slot0 + b) * 8192);
; #pragma unroll
;         for (int i = 0; i < 8; ++i) {
;             const int t = tid + 512 * i, par = tid & 1, d0 = (tid >> 1) + par;
;             const LAS unsigned* rw = (const LAS unsigned*)row + d0;
;             const unsigned dw0 = (i == 0) ? rw[d0 > 0 ? -1 : 0] : rw[256 * i - 1], dw1 = rw[256 * i];
;             float um = par ? U2F(dw0 << 16) : U2F(dw0 & 0xffff0000u);
;             const float u0 = par ? U2F(dw0 & 0xffff0000u) : U2F(dw1 << 16);
;             float up = par ? U2F(dw1 << 16) : U2F(dw1 & 0xffff0000u);
;             um = (t > 0) ? um : 0.f; up = (t < 4095) ? up : 0.f;
;             const float r = um * w0 + u0 * w1 + up * w2 + bs;
;             if (MODE == 0) { if (b & 1) z[b >> 1][i].y = r; else z[b >> 1][i].x = r; }
;             else { if (b & 1) z[b >> 1][i].y = r * (y[b >> 1][i].y + hb * z[b >> 1][i].y); else z[b >> 1][i].x = r * (y[b >> 1][i].x + hb * z[b >> 1][i].x); }
	v_and_b32_e32 v17, 0xffff0000, v95
	v_and_b32_e32 v19, 0xffff0000, v94
	v_lshlrev_b32_e32 v67, 16, v95
	v_lshlrev_b32_e32 v69, 16, v94
	v_cndmask_b32_e64 v69, v69, v19, s[38:39]
	v_cndmask_b32_e64 v67, v67, v17, s[38:39]
	v_cndmask_b32_e64 v87, 0, v67, s[40:41]
	v_cndmask_b32_e64 v86, 0, v69, s[40:41]
	s_waitcnt lgkmcnt(0)
	v_lshlrev_b32_e32 v67, 16, v82
	v_lshlrev_b32_e32 v69, 16, v83
	v_cndmask_b32_e64 v95, v17, v69, s[38:39]
	v_cndmask_b32_e64 v94, v19, v67, s[38:39]
	v_pk_mul_f32 v[94:95], v[66:67], v[94:95] op_sel_hi:[0,1]
	v_pk_fma_f32 v[86:87], v[18:19], v[86:87], v[94:95] op_sel_hi:[0,1,1]
	v_and_b32_e32 v17, 0xffff0000, v83
	v_and_b32_e32 v19, 0xffff0000, v82
	v_cndmask_b32_e64 v19, v67, v19, s[38:39]
	v_cndmask_b32_e64 v17, v69, v17, s[38:39]
	v_cndmask_b32_e64 v83, 0, v17, s[42:43]
	v_cndmask_b32_e64 v82, 0, v19, s[42:43]
	v_pk_fma_f32 v[82:83], v[16:17], v[82:83], v[86:87] op_sel_hi:[0,1,1]
	ds_read2_b32 v[86:87], v152 offset1:1
	v_pk_add_f32 v[82:83], v[68:69], v[82:83] op_sel_hi:[0,1]
	v_and_b32_e32 v19, 0xffff0000, v90
	v_lshlrev_b32_e32 v69, 16, v90
	v_cndmask_b32_e64 v69, v69, v19, s[38:39]
	s_waitcnt lgkmcnt(0)
	v_and_b32_e32 v17, 0xffff0000, v86
	v_lshlrev_b32_e32 v67, 16, v86
	v_cndmask_b32_e64 v67, v67, v17, s[38:39]
	v_cndmask_b32_e64 v99, 0, v67, s[44:45]
	v_cndmask_b32_e64 v98, 0, v69, s[44:45]
	v_lshlrev_b32_e32 v67, 16, v91
	v_lshlrev_b32_e32 v69, 16, v87
	v_cndmask_b32_e64 v101, v17, v69, s[38:39]
	v_cndmask_b32_e64 v100, v19, v67, s[38:39]
	v_pk_mul_f32 v[100:101], v[66:67], v[100:101] op_sel_hi:[0,1]
	v_pk_fma_f32 v[38:39], v[38:39], v[70:71], v[96:97] op_sel_hi:[1,0,1]
	v_pk_fma_f32 v[98:99], v[18:19], v[98:99], v[100:101] op_sel_hi:[0,1,1]
	v_and_b32_e32 v17, 0xffff0000, v87
	v_and_b32_e32 v19, 0xffff0000, v91
	v_pk_mul_f32 v[38:39], v[38:39], v[82:83]
	ds_read2_b32 v[82:83], v153 offset1:1
	ds_read2_b32 v[94:95], v154 offset1:1
	ds_read2_b32 v[96:97], v151 offset1:1
	v_cndmask_b32_e64 v19, v67, v19, s[38:39]
	v_cndmask_b32_e64 v17, v69, v17, s[38:39]
	v_cndmask_b32_e64 v87, 0, v17, s[46:47]
	v_cndmask_b32_e64 v86, 0, v19, s[46:47]
	v_pk_fma_f32 v[86:87], v[16:17], v[86:87], v[98:99] op_sel_hi:[0,1,1]
	v_pk_add_f32 v[86:87], v[68:69], v[86:87] op_sel_hi:[0,1]
	s_waitcnt lgkmcnt(2)
	v_and_b32_e32 v17, 0xffff0000, v82
	v_and_b32_e32 v19, 0xffff0000, v92
	v_lshlrev_b32_e32 v67, 16, v82
	v_lshlrev_b32_e32 v69, 16, v92
	v_pk_fma_f32 v[42:43], v[42:43], v[70:71], v[88:89] op_sel_hi:[1,0,1]
	v_cndmask_b32_e64 v69, v69, v19, s[38:39]
	v_cndmask_b32_e64 v67, v67, v17, s[38:39]
	v_pk_mul_f32 v[42:43], v[42:43], v[86:87]
	v_cndmask_b32_e64 v87, 0, v67, s[48:49]
	v_cndmask_b32_e64 v86, 0, v69, s[48:49]
	v_lshlrev_b32_e32 v67, 16, v93
	v_lshlrev_b32_e32 v69, 16, v83
	v_cndmask_b32_e64 v89, v17, v69, s[38:39]
	v_cndmask_b32_e64 v88, v19, v67, s[38:39]
	v_pk_mul_f32 v[88:89], v[66:67], v[88:89] op_sel_hi:[0,1]
	v_pk_fma_f32 v[86:87], v[18:19], v[86:87], v[88:89] op_sel_hi:[0,1,1]
	v_and_b32_e32 v17, 0xffff0000, v83
	v_and_b32_e32 v19, 0xffff0000, v93
	v_cndmask_b32_e64 v19, v67, v19, s[38:39]
	v_cndmask_b32_e64 v17, v69, v17, s[38:39]
	v_cndmask_b32_e64 v83, 0, v17, s[50:51]
	v_cndmask_b32_e64 v82, 0, v19, s[50:51]
	v_pk_fma_f32 v[82:83], v[16:17], v[82:83], v[86:87] op_sel_hi:[0,1,1]
	v_pk_add_f32 v[82:83], v[68:69], v[82:83] op_sel_hi:[0,1]
	v_pk_fma_f32 v[44:45], v[44:45], v[70:71], v[84:85] op_sel_hi:[1,0,1]
	s_waitcnt lgkmcnt(1)
	v_and_b32_e32 v17, 0xffff0000, v94
	v_pk_mul_f32 v[44:45], v[44:45], v[82:83]
	ds_read2_b32 v[82:83], v147 offset1:1
	v_lshlrev_b32_e32 v67, 16, v94
	v_cndmask_b32_e64 v67, v67, v17, s[38:39]
	v_cndmask_b32_e64 v91, 0, v67, s[52:53]
	ds_read2_b32 v[84:85], v148 offset1:1
	ds_read2_b32 v[86:87], v149 offset1:1
	ds_read2_b32 v[88:89], v150 offset1:1
	s_waitcnt lgkmcnt(3)
	v_and_b32_e32 v19, 0xffff0000, v82
	v_lshlrev_b32_e32 v69, 16, v82
	v_cndmask_b32_e64 v69, v69, v19, s[38:39]
	v_cndmask_b32_e64 v90, 0, v69, s[52:53]
	v_lshlrev_b32_e32 v67, 16, v83
	v_lshlrev_b32_e32 v69, 16, v95
	v_cndmask_b32_e64 v93, v17, v69, s[38:39]
	v_cndmask_b32_e64 v92, v19, v67, s[38:39]
	v_pk_mul_f32 v[92:93], v[66:67], v[92:93] op_sel_hi:[0,1]
	v_pk_fma_f32 v[50:51], v[50:51], v[70:71], v[80:81] op_sel_hi:[1,0,1]
	ds_read2_b32 v[80:81], v155 offset1:1
	v_pk_fma_f32 v[90:91], v[18:19], v[90:91], v[92:93] op_sel_hi:[0,1,1]
	v_and_b32_e32 v17, 0xffff0000, v95
	v_and_b32_e32 v19, 0xffff0000, v83
	v_cndmask_b32_e64 v19, v67, v19, s[38:39]
	v_cndmask_b32_e64 v17, v69, v17, s[38:39]
	v_cndmask_b32_e64 v83, 0, v17, s[54:55]
	v_cndmask_b32_e64 v82, 0, v19, s[54:55]
	v_pk_fma_f32 v[82:83], v[16:17], v[82:83], v[90:91] op_sel_hi:[0,1,1]
	v_pk_add_f32 v[82:83], v[68:69], v[82:83] op_sel_hi:[0,1]
	s_waitcnt lgkmcnt(0)
	v_and_b32_e32 v17, 0xffff0000, v80
	v_and_b32_e32 v19, 0xffff0000, v84
	v_lshlrev_b32_e32 v67, 16, v80
	v_lshlrev_b32_e32 v69, 16, v84
	v_cndmask_b32_e64 v69, v69, v19, s[38:39]
	v_cndmask_b32_e64 v67, v67, v17, s[38:39]
	v_cndmask_b32_e64 v95, 0, v67, s[56:57]
	v_cndmask_b32_e64 v94, 0, v69, s[56:57]
	v_lshlrev_b32_e32 v67, 16, v85
	v_lshlrev_b32_e32 v69, 16, v81
	v_cndmask_b32_e64 v99, v17, v69, s[38:39]
	v_cndmask_b32_e64 v98, v19, v67, s[38:39]
	v_pk_mul_f32 v[98:99], v[66:67], v[98:99] op_sel_hi:[0,1]
	v_pk_fma_f32 v[94:95], v[18:19], v[94:95], v[98:99] op_sel_hi:[0,1,1]
	v_and_b32_e32 v17, 0xffff0000, v81
	v_and_b32_e32 v19, 0xffff0000, v85
	v_pk_mul_f32 v[50:51], v[50:51], v[82:83]
	ds_read2_b32 v[82:83], v156 offset1:1
	ds_read2_b32 v[90:91], v157 offset1:1
	ds_read2_b32 v[92:93], v158 offset1:1
	v_cndmask_b32_e64 v19, v67, v19, s[38:39]
	v_cndmask_b32_e64 v17, v69, v17, s[38:39]
	v_cndmask_b32_e64 v81, 0, v17, s[58:59]
	v_cndmask_b32_e64 v80, 0, v19, s[58:59]
	v_pk_fma_f32 v[80:81], v[16:17], v[80:81], v[94:95] op_sel_hi:[0,1,1]
	v_pk_add_f32 v[80:81], v[68:69], v[80:81] op_sel_hi:[0,1]
	s_waitcnt lgkmcnt(2)
; #define LAS __attribute__((address_space(3)))
; #define U2F(x) __uint_as_float(x)
; DEV void fft_f1x2(LAS cf* buf0, LAS cf* buf1, const cf (&z0)[8], const cf (&z1)[8], int tid) {
;     ...
;     for (int q = 0; q < 8; ++q) { v[q] = z0[q]; v[q + 8] = cf{0.f, 0.f}; u[q] = z1[q]; u[q + 8] = cf{0.f, 0.f}; }
;     dft_regs<16, false>(v); dft_regs<16, false>(u);
; template <int MODE> DEV void hyena_conv_rows(const LAS unsigned char* lds, int slot0, float w0, float w1, float w2, float bs, cf (&z)[2][8], const cf (&y)[2][8], float hb, int tid) {
;     ...
;     for (int b = 0; b < 4; ++b) {
;         const LAS bf16_t* row = (const LAS bf16_t*)(lds + (slot0 + b) * 8192);
; #pragma unroll
;         for (int i = 0; i < 8; ++i) {
;             const int t = tid + 512 * i, par = tid & 1, d0 = (tid >> 1) + par;
;             const LAS unsigned* rw = (const LAS unsigned*)row + d0;
;             const unsigned dw0 = (i == 0) ? rw[d0 > 0 ? -1 : 0] : rw[256 * i - 1], dw1 = rw[256 * i];
;             float um = par ? U2F(dw0 << 16) : U2F(dw0 & 0xffff0000u);
;             const float u0 = par ? U2F(dw0 & 0xffff0000u) : U2F(dw1 << 16);
;             float up = par ? U2F(dw1 << 16) : U2F(dw1 & 0xffff0000u);
;             um = (t > 0) ? um : 0.f; up = (t < 4095) ? up : 0.f;
;             const float r = um * w0 + u0 * w1 + up * w2 + bs;
;             if (MODE == 0) { if (b & 1) z[b >> 1][i].y = r; else z[b >> 1][i].x = r; }
;             else { if (b & 1) z[b >> 1][i].y = r * (y[b >> 1][i].y + hb * z[b >> 1][i].y); else z[b >> 1][i].x = r * (y[b >> 1][i].x + hb * z[b >> 1][i].x); }
	v_and_b32_e32 v17, 0xffff0000, v82
	v_and_b32_e32 v19, 0xffff0000, v86
	v_lshlrev_b32_e32 v67, 16, v82
	v_lshlrev_b32_e32 v69, 16, v86
	v_cndmask_b32_e64 v69, v69, v19, s[38:39]
	v_cndmask_b32_e64 v67, v67, v17, s[38:39]
	v_pk_fma_f32 v[46:47], v[46:47], v[70:71], v[78:79] op_sel_hi:[1,0,1]
	v_cndmask_b32_e64 v79, 0, v67, s[60:61]
	v_cndmask_b32_e64 v78, 0, v69, s[60:61]
	v_lshlrev_b32_e32 v67, 16, v87
	v_lshlrev_b32_e32 v69, 16, v83
	v_pk_mul_f32 v[46:47], v[46:47], v[80:81]
	v_cndmask_b32_e64 v81, v17, v69, s[38:39]
	v_cndmask_b32_e64 v80, v19, v67, s[38:39]
	v_pk_mul_f32 v[80:81], v[66:67], v[80:81] op_sel_hi:[0,1]
	v_pk_fma_f32 v[78:79], v[18:19], v[78:79], v[80:81] op_sel_hi:[0,1,1]
	v_and_b32_e32 v17, 0xffff0000, v83
	v_and_b32_e32 v19, 0xffff0000, v87
	v_cndmask_b32_e64 v19, v67, v19, s[38:39]
	v_cndmask_b32_e64 v17, v69, v17, s[38:39]
	v_cndmask_b32_e64 v81, 0, v17, s[62:63]
	v_cndmask_b32_e64 v80, 0, v19, s[62:63]
	v_pk_fma_f32 v[78:79], v[16:17], v[80:81], v[78:79] op_sel_hi:[0,1,1]
	v_pk_add_f32 v[78:79], v[68:69], v[78:79] op_sel_hi:[0,1]
	s_waitcnt lgkmcnt(1)
	v_and_b32_e32 v17, 0xffff0000, v90
	v_and_b32_e32 v19, 0xffff0000, v88
	v_lshlrev_b32_e32 v67, 16, v90
	v_lshlrev_b32_e32 v69, 16, v88
	v_cndmask_b32_e64 v69, v69, v19, s[38:39]
	v_cndmask_b32_e64 v67, v67, v17, s[38:39]
	v_pk_fma_f32 v[48:49], v[48:49], v[70:71], v[76:77] op_sel_hi:[1,0,1]
	v_cndmask_b32_e64 v77, 0, v67, s[64:65]
	v_cndmask_b32_e64 v76, 0, v69, s[64:65]
	v_lshlrev_b32_e32 v67, 16, v89
	v_lshlrev_b32_e32 v69, 16, v91
	v_pk_mul_f32 v[48:49], v[48:49], v[78:79]
	v_cndmask_b32_e64 v79, v17, v69, s[38:39]
	v_cndmask_b32_e64 v78, v19, v67, s[38:39]
	v_pk_mul_f32 v[78:79], v[66:67], v[78:79] op_sel_hi:[0,1]
	v_pk_fma_f32 v[76:77], v[18:19], v[76:77], v[78:79] op_sel_hi:[0,1,1]
	v_and_b32_e32 v17, 0xffff0000, v91
	v_and_b32_e32 v19, 0xffff0000, v89
	v_cndmask_b32_e64 v19, v67, v19, s[38:39]
	v_cndmask_b32_e64 v17, v69, v17, s[38:39]
	v_cndmask_b32_e64 v79, 0, v17, s[66:67]
	v_cndmask_b32_e64 v78, 0, v19, s[66:67]
	v_pk_fma_f32 v[76:77], v[16:17], v[78:79], v[76:77] op_sel_hi:[0,1,1]
	v_pk_add_f32 v[76:77], v[68:69], v[76:77] op_sel_hi:[0,1]
	v_and_b32_e32 v19, 0xffff0000, v96
	v_lshlrev_b32_e32 v69, 16, v96
	v_cndmask_b32_e64 v69, v69, v19, s[38:39]
	v_pk_fma_f32 v[52:53], v[52:53], v[70:71], v[74:75] op_sel_hi:[1,0,1]
	s_waitcnt lgkmcnt(0)
	v_and_b32_e32 v17, 0xffff0000, v92
	v_lshlrev_b32_e32 v67, 16, v92
	v_cndmask_b32_e64 v74, 0, v69, s[68:69]
	v_lshlrev_b32_e32 v69, 16, v97
	v_lshlrev_b32_e32 v71, 16, v93
	v_pk_mul_f32 v[52:53], v[52:53], v[76:77]
	v_cndmask_b32_e64 v67, v67, v17, s[38:39]
	v_cndmask_b32_e64 v77, v17, v71, s[38:39]
	v_cndmask_b32_e64 v76, v19, v69, s[38:39]
	v_cndmask_b32_e64 v75, 0, v67, s[68:69]
	v_pk_mul_f32 v[66:67], v[66:67], v[76:77] op_sel_hi:[0,1]
	v_pk_fma_f32 v[18:19], v[18:19], v[74:75], v[66:67] op_sel_hi:[0,1,1]
	v_and_b32_e32 v17, 0xffff0000, v93
	v_and_b32_e32 v66, 0xffff0000, v97
	v_cndmask_b32_e64 v66, v69, v66, s[38:39]
	v_cndmask_b32_e64 v17, v71, v17, s[38:39]
	v_cndmask_b32_e64 v67, 0, v17, s[70:71]
	v_cndmask_b32_e64 v66, 0, v66, s[70:71]
	v_pk_add_f32 v[72:73], v[126:127], v[166:167]
	v_pk_fma_f32 v[16:17], v[16:17], v[66:67], v[18:19] op_sel_hi:[0,1,1]
	v_pk_add_f32 v[16:17], v[68:69], v[16:17] op_sel_hi:[0,1]
	v_pk_fma_f32 v[18:19], v[40:41], v[70:71], v[72:73] op_sel_hi:[1,0,1]
	s_mov_b64 s[22:23], 0
	v_pk_mul_f32 v[40:41], v[18:19], v[16:17]
	s_and_b64 vcc, exec, s[2:3]
	s_barrier
	s_cbranch_vccnz .LBB0_522
.LBB0_519:
	v_pk_mul_f32 v[16:17], v[26:27], s[16:17] op_sel_hi:[1,0]
	v_pk_add_f32 v[0:1], v[24:25], 0 op_sel_hi:[1,0]
	v_pk_fma_f32 v[18:19], v[26:27], s[84:85], v[16:17] op_sel:[0,0,1] op_sel_hi:[1,0,0]
	v_pk_fma_f32 v[16:17], v[26:27], s[84:85], v[16:17] op_sel:[0,0,1] op_sel_hi:[1,0,0] neg_lo:[0,0,1] neg_hi:[0,0,1]
	v_mov_b32_e32 v19, v17
	v_pk_add_f32 v[16:17], v[22:23], 0 op_sel_hi:[1,0]
	v_mov_b32_e32 v4, v24
	v_mov_b32_e32 v5, v25
	v_pk_add_f32 v[80:81], v[0:1], v[16:17]
	v_pk_add_f32 v[0:1], v[0:1], v[16:17] neg_lo:[0,1] neg_hi:[0,1]
	v_mov_b32_e32 v2, v24
	v_mov_b32_e32 v3, v25
	v_pk_fma_f32 v[66:67], v[22:23], 0, v[22:23] op_sel:[0,0,1] op_sel_hi:[1,0,0]
	v_pk_fma_f32 v[68:69], v[22:23], 0, v[22:23] op_sel:[0,0,1] op_sel_hi:[1,0,0] neg_lo:[0,0,1] neg_hi:[0,0,1]
	v_mov_b32_e32 v5, v3
	v_pk_add_f32 v[2:3], v[30:31], 0 op_sel_hi:[1,0]
	v_pk_mul_f32 v[6:7], v[30:31], s[84:85] op_sel_hi:[1,0]
	v_mov_b32_e32 v67, v69
	v_pk_add_f32 v[68:69], v[32:33], 0 op_sel_hi:[1,0]
	v_mov_b32_e32 v82, v0
	v_mov_b32_e32 v83, v1
	v_pk_fma_f32 v[8:9], v[30:31], s[16:17], v[6:7] op_sel:[0,0,1] op_sel_hi:[1,0,0]
	v_pk_fma_f32 v[6:7], v[30:31], s[16:17], v[6:7] op_sel:[0,0,1] op_sel_hi:[1,0,0] neg_lo:[0,0,1] neg_hi:[0,0,1]
	v_pk_add_f32 v[0:1], v[2:3], v[68:69]
	v_pk_add_f32 v[2:3], v[2:3], v[68:69] neg_lo:[0,1] neg_hi:[0,1]
	v_mov_b32_e32 v9, v7
	v_pk_add_f32 v[6:7], v[28:29], 0 op_sel_hi:[1,0]
	v_pk_add_f32 v[72:73], v[34:35], 0 op_sel_hi:[1,0]
	v_pk_mul_f32 v[16:17], v[2:3], s[18:19] op_sel_hi:[1,0]
	v_pk_mul_f32 v[10:11], v[28:29], s[18:19] op_sel_hi:[1,0]
	v_pk_fma_f32 v[68:69], v[2:3], s[18:19], v[16:17] op_sel:[0,0,1] op_sel_hi:[1,0,0]
	v_pk_fma_f32 v[2:3], v[2:3], s[18:19], v[16:17] op_sel_hi:[1,0,0] neg_lo:[0,0,1] neg_hi:[0,0,1]
	v_pk_add_f32 v[16:17], v[6:7], v[72:73]
	v_pk_add_f32 v[6:7], v[6:7], v[72:73] neg_lo:[0,1] neg_hi:[0,1]
	v_pk_add_f32 v[14:15], v[26:27], 0 op_sel_hi:[1,0]
	v_pk_add_f32 v[76:77], v[36:37], 0 op_sel_hi:[1,0]
	v_pk_add_f32 v[72:73], v[6:7], 0 op_sel:[1,0] op_sel_hi:[0,0] neg_hi:[1,0]
	v_pk_fma_f32 v[12:13], v[28:29], s[18:19], v[10:11] op_sel:[0,0,1] op_sel_hi:[1,0,0]
; template <int R, bool INV> DEV void dft_regs(cf (&v)[R]) {
;     ...
;     for (int s = R; s >= 2; s >>= 1) {
;         const int h = s >> 1;
; #pragma unroll
;         for (int b = 0; b < R; b += s) {
; #pragma unroll
;             for (int k = 0; k < h; ++k) {
;                 const cf a = v[b + k], c = v[b + k + h];
;                 v[b + k] = a + c;
;                 const cf d = a - c;
;                 const int m = k * (32 / s);
;                 const float wr = tw_cos(m), wi = INV ? tw_sin(m) : -tw_sin(m);
;                 v[b + k + h] = cf{d.x * wr - d.y * wi, d.x * wi + d.y * wr};
;             }
	v_pk_fma_f32 v[10:11], v[28:29], s[18:19], v[10:11] op_sel_hi:[1,0,0] neg_lo:[0,0,1] neg_hi:[0,0,1]
	v_pk_add_f32 v[6:7], v[14:15], v[76:77]
	v_pk_add_f32 v[14:15], v[14:15], v[76:77] neg_lo:[0,1] neg_hi:[0,1]
	v_pk_add_f32 v[76:77], v[4:5], v[66:67]
	v_pk_add_f32 v[4:5], v[4:5], v[66:67] neg_lo:[0,1] neg_hi:[0,1]
	v_mov_b32_e32 v10, v33
	s_mov_b32 s30, s85
	s_mov_b32 s31, s0
	v_pk_mul_f32 v[70:71], v[32:33], s[84:85] op_sel_hi:[0,1]
	v_pk_fma_f32 v[70:71], v[10:11], s[30:31], v[70:71] op_sel_hi:[0,1,1] neg_lo:[0,0,1] neg_hi:[0,0,1]
	v_mov_b32_e32 v84, v4
	v_mov_b32_e32 v85, v5
	v_mul_f32_e32 v10, 0x3f3504f3, v34
	v_mov_b32_e32 v74, v35
	s_mov_b32 s28, s97
	s_mov_b32 s29, s96
	s_mov_b32 s24, s85
	s_mov_b32 s25, s84
	v_pk_add_f32 v[4:5], v[8:9], v[70:71]
	v_pk_add_f32 v[8:9], v[8:9], v[70:71] neg_lo:[0,1] neg_hi:[0,1]
	v_pk_fma_f32 v[74:75], v[74:75], s[28:29], v[10:11] op_sel_hi:[0,1,0] neg_lo:[0,0,1] neg_hi:[0,0,1]
	v_mov_b32_e32 v10, v37
	s_mov_b32 s34, s84
	s_mov_b32 s35, s88
	v_pk_mul_f32 v[78:79], v[36:37], s[24:25] op_sel_hi:[0,1]
	v_pk_mul_f32 v[66:67], v[8:9], s[18:19] op_sel_hi:[1,0]
	v_mov_b32_e32 v13, v11
	v_pk_fma_f32 v[78:79], v[10:11], s[34:35], v[78:79] op_sel_hi:[0,1,1] neg_lo:[0,0,1] neg_hi:[0,0,1]
	v_pk_fma_f32 v[70:71], v[8:9], s[18:19], v[66:67] op_sel:[0,0,1] op_sel_hi:[1,0,0]
	v_pk_fma_f32 v[8:9], v[8:9], s[18:19], v[66:67] op_sel_hi:[1,0,0] neg_lo:[0,0,1] neg_hi:[0,0,1]
	v_pk_add_f32 v[10:11], v[12:13], v[74:75] neg_lo:[0,1] neg_hi:[0,1]
	v_pk_add_f32 v[66:67], v[80:81], v[16:17]
	v_pk_add_f32 v[16:17], v[80:81], v[16:17] neg_lo:[0,1] neg_hi:[0,1]
	v_mov_b32_e32 v71, v9
	v_pk_add_f32 v[8:9], v[12:13], v[74:75]
	v_pk_add_f32 v[12:13], v[10:11], 0 op_sel:[1,0] op_sel_hi:[0,0] neg_hi:[1,0]
	v_pk_add_f32 v[10:11], v[18:19], v[78:79]
	v_pk_add_f32 v[18:19], v[18:19], v[78:79] neg_lo:[0,1] neg_hi:[0,1]
	v_mov_b32_e32 v78, v16
	v_mov_b32_e32 v79, v17
	v_mul_f32_e32 v2, 0x3f3504f3, v14
	v_pk_add_f32 v[16:17], v[0:1], v[6:7]
	v_pk_add_f32 v[0:1], v[0:1], v[6:7] neg_lo:[0,1] neg_hi:[0,1]
	v_pk_add_f32 v[74:75], v[82:83], v[72:73]
	v_pk_add_f32 v[6:7], v[0:1], 0 op_sel:[1,0] op_sel_hi:[0,0] neg_hi:[1,0]
	v_pk_fma_f32 v[14:15], v[14:15], s[28:29], v[2:3] op_sel:[1,0,0] op_sel_hi:[1,1,0] neg_lo:[0,0,1] neg_hi:[0,0,1]
	v_pk_add_f32 v[0:1], v[82:83], v[72:73] neg_lo:[0,1] neg_hi:[0,1]
	v_mov_b32_e32 v69, v3
	v_mul_f32_e32 v2, 0x3f3504f3, v18
	v_mov_b32_e32 v80, v0
	v_mov_b32_e32 v81, v1
	v_pk_fma_f32 v[18:19], v[18:19], s[28:29], v[2:3] op_sel:[1,0,0] op_sel_hi:[1,1,0] neg_lo:[0,0,1] neg_hi:[0,0,1]
	v_pk_add_f32 v[0:1], v[68:69], v[14:15] neg_lo:[0,1] neg_hi:[0,1]
	v_pk_add_f32 v[2:3], v[68:69], v[14:15]
	v_pk_add_f32 v[14:15], v[0:1], 0 op_sel:[1,0] op_sel_hi:[0,0] neg_hi:[1,0]
	v_pk_add_f32 v[72:73], v[76:77], v[8:9]
	v_pk_add_f32 v[0:1], v[76:77], v[8:9] neg_lo:[0,1] neg_hi:[0,1]
	v_pk_add_f32 v[86:87], v[84:85], v[12:13]
	v_pk_add_f32 v[68:69], v[66:67], v[16:17]
	v_mov_b32_e32 v82, v0
	v_mov_b32_e32 v83, v1
	v_pk_add_f32 v[8:9], v[4:5], v[10:11]
	v_pk_add_f32 v[0:1], v[4:5], v[10:11] neg_lo:[0,1] neg_hi:[0,1]
	v_pk_add_f32 v[88:89], v[70:71], v[18:19]
	v_pk_add_f32 v[10:11], v[0:1], 0 op_sel:[1,0] op_sel_hi:[0,0] neg_hi:[1,0]
	v_pk_add_f32 v[76:77], v[72:73], v[8:9]
	v_pk_add_f32 v[0:1], v[84:85], v[12:13] neg_lo:[0,1] neg_hi:[0,1]
	v_pk_add_f32 v[8:9], v[72:73], v[8:9] neg_lo:[0,1] neg_hi:[0,1]
	v_pk_add_f32 v[72:73], v[82:83], v[10:11]
	v_mov_b32_e32 v84, v0
	v_mov_b32_e32 v85, v1
	v_pk_add_f32 v[10:11], v[82:83], v[10:11] neg_lo:[0,1] neg_hi:[0,1]
	v_pk_add_f32 v[0:1], v[70:71], v[18:19] neg_lo:[0,1] neg_hi:[0,1]
	v_pk_add_f32 v[70:71], v[74:75], v[2:3]
	v_pk_add_f32 v[90:91], v[0:1], 0 op_sel:[1,0] op_sel_hi:[0,0] neg_hi:[1,0]
	v_pk_add_f32 v[2:3], v[74:75], v[2:3] neg_lo:[0,1] neg_hi:[0,1]
	v_pk_add_f32 v[0:1], v[66:67], v[16:17] neg_lo:[0,1] neg_hi:[0,1]
	v_pk_add_f32 v[16:17], v[78:79], v[6:7]
	v_pk_add_f32 v[6:7], v[78:79], v[6:7] neg_lo:[0,1] neg_hi:[0,1]
	v_mov_b32_e32 v4, v0
	v_mov_b32_e32 v5, v1
	v_mov_b32_e32 v0, v6
	v_mov_b32_e32 v1, v7
	v_mov_b32_e32 v6, v2
	v_mov_b32_e32 v7, v3
	v_pk_add_f32 v[12:13], v[80:81], v[14:15] neg_lo:[0,1] neg_hi:[0,1]
	v_pk_add_f32 v[18:19], v[80:81], v[14:15]
	v_mov_b32_e32 v2, v12
	v_mov_b32_e32 v3, v13
	v_mov_b32_e32 v12, v8
	v_mov_b32_e32 v13, v9
	v_mov_b32_e32 v8, v10
	v_mov_b32_e32 v9, v11
	v_pk_mul_f32 v[92:93], v[50:51], s[16:17] op_sel_hi:[1,0]
	v_pk_add_f32 v[10:11], v[86:87], v[88:89] neg_lo:[0,1] neg_hi:[0,1]
	v_pk_fma_f32 v[94:95], v[50:51], s[84:85], v[92:93] op_sel:[0,0,1] op_sel_hi:[1,0,0]
	v_pk_fma_f32 v[92:93], v[50:51], s[84:85], v[92:93] op_sel:[0,0,1] op_sel_hi:[1,0,0] neg_lo:[0,0,1] neg_hi:[0,0,1]
	v_mov_b32_e32 v14, v10
	v_mov_b32_e32 v15, v11
	v_pk_add_f32 v[66:67], v[84:85], v[90:91] neg_lo:[0,1] neg_hi:[0,1]
	v_mov_b32_e32 v95, v93
	v_mov_b32_e32 v10, v66
	v_mov_b32_e32 v11, v67
	v_pk_add_f32 v[92:93], v[46:47], 0 op_sel_hi:[1,0]
	v_pk_add_f32 v[66:67], v[38:39], 0 op_sel_hi:[1,0]
	v_mov_b32_e32 v108, v41
	v_pk_mul_f32 v[110:111], v[40:41], s[24:25] op_sel_hi:[0,1]
	v_pk_fma_f32 v[108:109], v[108:109], s[34:35], v[110:111] op_sel_hi:[0,1,1] neg_lo:[0,0,1] neg_hi:[0,0,1]
	v_pk_add_f32 v[110:111], v[66:67], v[92:93]
	v_pk_add_f32 v[66:67], v[66:67], v[92:93] neg_lo:[0,1] neg_hi:[0,1]
	v_mov_b32_e32 v82, v38
	v_mov_b32_e32 v83, v39
	v_mov_b32_e32 v80, v38
	v_mov_b32_e32 v81, v39
	v_pk_fma_f32 v[96:97], v[46:47], 0, v[46:47] op_sel:[0,0,1] op_sel_hi:[1,0,0]
	v_pk_fma_f32 v[98:99], v[46:47], 0, v[46:47] op_sel:[0,0,1] op_sel_hi:[1,0,0] neg_lo:[0,0,1] neg_hi:[0,0,1]
	v_mov_b32_e32 v83, v81
	v_pk_add_f32 v[80:81], v[42:43], 0 op_sel_hi:[1,0]
	v_mov_b32_e32 v97, v99
; template <int R, bool INV> DEV void dft_regs(cf (&v)[R]) {
;     ...
;     for (int s = R; s >= 2; s >>= 1) {
;         const int h = s >> 1;
; #pragma unroll
;         for (int b = 0; b < R; b += s) {
; #pragma unroll
;             for (int k = 0; k < h; ++k) {
;                 const cf a = v[b + k], c = v[b + k + h];
;                 v[b + k] = a + c;
;                 const cf d = a - c;
;                 const int m = k * (32 / s);
;                 const float wr = tw_cos(m), wi = INV ? tw_sin(m) : -tw_sin(m);
;                 v[b + k + h] = cf{d.x * wr - d.y * wi, d.x * wi + d.y * wr};
;             }
; DEV void fft_midx2(LAS cf* buf0, LAS cf* buf1, const unsigned* Kp, int blk) {
;     ...
;     u32x4 kw[4];
; #pragma unroll
;     for (int j = 0; j < 4; ++j) kw[j] = *(const u32x4*)(Kp + base + 4 * j);
	v_pk_add_f32 v[98:99], v[48:49], 0 op_sel_hi:[1,0]
	v_mov_b32_e32 v112, v66
	v_mov_b32_e32 v113, v67
	v_pk_add_f32 v[74:75], v[84:85], v[90:91]
	v_pk_mul_f32 v[84:85], v[42:43], s[84:85] op_sel_hi:[1,0]
	v_pk_add_f32 v[66:67], v[80:81], v[98:99]
	v_pk_add_f32 v[80:81], v[80:81], v[98:99] neg_lo:[0,1] neg_hi:[0,1]
	v_pk_add_f32 v[78:79], v[86:87], v[88:89]
	v_pk_fma_f32 v[86:87], v[42:43], s[16:17], v[84:85] op_sel:[0,0,1] op_sel_hi:[1,0,0]
	v_pk_fma_f32 v[84:85], v[42:43], s[16:17], v[84:85] op_sel:[0,0,1] op_sel_hi:[1,0,0] neg_lo:[0,0,1] neg_hi:[0,0,1]
	v_mov_b32_e32 v100, v49
	v_pk_mul_f32 v[102:103], v[48:49], s[84:85] op_sel_hi:[0,1]
	v_pk_mul_f32 v[92:93], v[80:81], s[18:19] op_sel_hi:[1,0]
	v_mov_b32_e32 v87, v85
	v_pk_add_f32 v[84:85], v[44:45], 0 op_sel_hi:[1,0]
	v_pk_mul_f32 v[88:89], v[44:45], s[18:19] op_sel_hi:[1,0]
	v_pk_fma_f32 v[100:101], v[100:101], s[30:31], v[102:103] op_sel_hi:[0,1,1] neg_lo:[0,0,1] neg_hi:[0,0,1]
	v_pk_add_f32 v[102:103], v[52:53], 0 op_sel_hi:[1,0]
	v_pk_fma_f32 v[98:99], v[80:81], s[18:19], v[92:93] op_sel:[0,0,1] op_sel_hi:[1,0,0]
	v_pk_fma_f32 v[80:81], v[80:81], s[18:19], v[92:93] op_sel_hi:[1,0,0] neg_lo:[0,0,1] neg_hi:[0,0,1]
	v_pk_fma_f32 v[90:91], v[44:45], s[18:19], v[88:89] op_sel:[0,0,1] op_sel_hi:[1,0,0]
	v_pk_fma_f32 v[88:89], v[44:45], s[18:19], v[88:89] op_sel_hi:[1,0,0] neg_lo:[0,0,1] neg_hi:[0,0,1]
	v_mul_f32_e32 v104, 0x3f3504f3, v52
	v_mov_b32_e32 v106, v53
	v_mov_b32_e32 v99, v81
	v_pk_add_f32 v[80:81], v[84:85], v[102:103]
	v_pk_add_f32 v[84:85], v[84:85], v[102:103] neg_lo:[0,1] neg_hi:[0,1]
	v_mov_b32_e32 v91, v89
	v_pk_add_f32 v[88:89], v[50:51], 0 op_sel_hi:[1,0]
	v_pk_fma_f32 v[104:105], v[106:107], s[28:29], v[104:105] op_sel_hi:[0,1,0] neg_lo:[0,0,1] neg_hi:[0,0,1]
	v_pk_add_f32 v[106:107], v[40:41], 0 op_sel_hi:[1,0]
	v_pk_add_f32 v[92:93], v[84:85], 0 op_sel:[1,0] op_sel_hi:[0,0] neg_hi:[1,0]
	v_mov_b32_e32 v114, v21
	v_pk_add_f32 v[84:85], v[88:89], v[106:107]
	v_pk_add_f32 v[88:89], v[88:89], v[106:107] neg_lo:[0,1] neg_hi:[0,1]
	s_mov_b32 s2, s86
	v_mul_f32_e32 v102, 0x3f3504f3, v88
	v_pk_fma_f32 v[88:89], v[88:89], s[28:29], v[102:103] op_sel:[1,0,0] op_sel_hi:[1,1,0] neg_lo:[0,0,1] neg_hi:[0,0,1]
	v_pk_add_f32 v[102:103], v[82:83], v[96:97]
	v_pk_add_f32 v[82:83], v[82:83], v[96:97] neg_lo:[0,1] neg_hi:[0,1]
	s_mov_b32 s3, s4
	s_mov_b32 s10, s4
	v_mov_b32_e32 v106, v82
	v_mov_b32_e32 v107, v83
	s_mov_b32 s6, s94
	v_pk_add_f32 v[82:83], v[86:87], v[100:101]
	v_pk_add_f32 v[86:87], v[86:87], v[100:101] neg_lo:[0,1] neg_hi:[0,1]
	s_mov_b32 s7, s82
	v_pk_mul_f32 v[96:97], v[86:87], s[18:19] op_sel_hi:[1,0]
	s_mov_b32 s8, s82
	v_pk_fma_f32 v[100:101], v[86:87], s[18:19], v[96:97] op_sel:[0,0,1] op_sel_hi:[1,0,0]
	v_pk_fma_f32 v[86:87], v[86:87], s[18:19], v[96:97] op_sel_hi:[1,0,0] neg_lo:[0,0,1] neg_hi:[0,0,1]
	s_lshl_b32 s92, s19, 13
	v_lshl_add_u64 v[232:233], s[92:93], 2, v[54:55]
	global_load_dwordx4 v[170:173], v[232:233], off offset:48
	global_load_dwordx4 v[174:177], v[232:233], off offset:32
	global_load_dwordx4 v[178:181], v[232:233], off offset:16
	global_load_dwordx4 v[182:185], v[232:233], off
	v_mov_b32_e32 v101, v87
	v_pk_add_f32 v[86:87], v[90:91], v[104:105]
	v_pk_add_f32 v[90:91], v[90:91], v[104:105] neg_lo:[0,1] neg_hi:[0,1]
	s_mov_b32 s1, s85
	v_pk_add_f32 v[96:97], v[90:91], 0 op_sel:[1,0] op_sel_hi:[0,0] neg_hi:[1,0]
	s_mov_b32 s89, s84
	v_pk_add_f32 v[90:91], v[94:95], v[108:109]
	v_pk_add_f32 v[94:95], v[94:95], v[108:109] neg_lo:[0,1] neg_hi:[0,1]
	v_mul_f32_e32 v104, 0x3f3504f3, v94
	v_pk_fma_f32 v[94:95], v[94:95], s[28:29], v[104:105] op_sel:[1,0,0] op_sel_hi:[1,1,0] neg_lo:[0,0,1] neg_hi:[0,0,1]
	v_pk_add_f32 v[104:105], v[110:111], v[80:81]
	v_pk_add_f32 v[80:81], v[110:111], v[80:81] neg_lo:[0,1] neg_hi:[0,1]
	v_mov_b32_e32 v110, v80
	v_mov_b32_e32 v111, v81
	v_pk_add_f32 v[80:81], v[66:67], v[84:85]
	v_pk_add_f32 v[66:67], v[66:67], v[84:85] neg_lo:[0,1] neg_hi:[0,1]
	v_pk_add_f32 v[84:85], v[66:67], 0 op_sel:[1,0] op_sel_hi:[0,0] neg_hi:[1,0]
	v_pk_add_f32 v[66:67], v[112:113], v[92:93]
	v_pk_add_f32 v[92:93], v[112:113], v[92:93] neg_lo:[0,1] neg_hi:[0,1]
	v_mov_b32_e32 v112, v92
	v_mov_b32_e32 v113, v93
	v_pk_add_f32 v[92:93], v[98:99], v[88:89]
	v_pk_add_f32 v[88:89], v[98:99], v[88:89] neg_lo:[0,1] neg_hi:[0,1]
	v_pk_add_f32 v[98:99], v[88:89], 0 op_sel:[1,0] op_sel_hi:[0,0] neg_hi:[1,0]
	v_pk_add_f32 v[88:89], v[102:103], v[86:87]
	v_pk_add_f32 v[86:87], v[102:103], v[86:87] neg_lo:[0,1] neg_hi:[0,1]
	v_mov_b32_e32 v108, v86
	v_mov_b32_e32 v109, v87
	v_pk_add_f32 v[86:87], v[82:83], v[90:91]
	v_pk_add_f32 v[82:83], v[82:83], v[90:91] neg_lo:[0,1] neg_hi:[0,1]
	v_pk_add_f32 v[90:91], v[82:83], 0 op_sel:[1,0] op_sel_hi:[0,0] neg_hi:[1,0]
	v_pk_add_f32 v[82:83], v[106:107], v[96:97]
	v_pk_add_f32 v[96:97], v[106:107], v[96:97] neg_lo:[0,1] neg_hi:[0,1]
	v_mov_b32_e32 v106, v96
	v_mov_b32_e32 v107, v97
	v_pk_add_f32 v[96:97], v[100:101], v[94:95]
	v_pk_add_f32 v[94:95], v[100:101], v[94:95] neg_lo:[0,1] neg_hi:[0,1]
	v_pk_add_f32 v[100:101], v[94:95], 0 op_sel:[1,0] op_sel_hi:[0,0] neg_hi:[1,0]
	v_pk_add_f32 v[94:95], v[104:105], v[80:81]
	v_pk_add_f32 v[80:81], v[104:105], v[80:81] neg_lo:[0,1] neg_hi:[0,1]
	v_mov_b32_e32 v104, v80
	v_mov_b32_e32 v105, v81
	v_pk_add_f32 v[80:81], v[110:111], v[84:85]
	v_pk_add_f32 v[84:85], v[110:111], v[84:85] neg_lo:[0,1] neg_hi:[0,1]
	v_mov_b32_e32 v110, v84
	v_mov_b32_e32 v111, v85
	v_pk_add_f32 v[84:85], v[66:67], v[92:93]
	v_pk_add_f32 v[66:67], v[66:67], v[92:93] neg_lo:[0,1] neg_hi:[0,1]
	v_mov_b32_e32 v102, v66
	v_mov_b32_e32 v103, v67
	v_pk_add_f32 v[92:93], v[112:113], v[98:99]
; #define LAS __attribute__((address_space(3)))
; #define SINCOSPI(x, s, c) do { const float hx_ = 0.5f * (x); *(s) = __builtin_amdgcn_sinf(hx_); *(c) = __builtin_amdgcn_cosf(hx_); } while (0)
; template <int R, bool INV> DEV void dft_regs(cf (&v)[R]) {
;     ...
;     for (int s = R; s >= 2; s >>= 1) {
;         const int h = s >> 1;
; #pragma unroll
;         for (int b = 0; b < R; b += s) {
; #pragma unroll
;             for (int k = 0; k < h; ++k) {
;                 const cf a = v[b + k], c = v[b + k + h];
;                 v[b + k] = a + c;
;                 const cf d = a - c;
;                 const int m = k * (32 / s);
;                 const float wr = tw_cos(m), wi = INV ? tw_sin(m) : -tw_sin(m);
;                 v[b + k + h] = cf{d.x * wr - d.y * wi, d.x * wi + d.y * wr};
;             }
; DEV void fft_f1x2(LAS cf* buf0, LAS cf* buf1, const cf (&z0)[8], const cf (&z1)[8], int tid) {
;     ...
;     float sn, cs; SINCOSPI(-(float)tid * (2.0f / 8192.0f), &sn, &cs);
;     const cf w = cf{cs, sn}; cf wp = cf{1.f, 0.f};
;     LAS cf* p0 = buf0 + PADI(tid); LAS cf* p1 = buf1 + PADI(tid);
; #pragma unroll
;     for (int p = 0; p < 16; ++p) { p0[544 * p] = cmul(v[BR16[p]], wp); p1[544 * p] = cmul(u[BR16[p]], wp); wp = cmul(wp, w); }
	v_pk_add_f32 v[66:67], v[112:113], v[98:99] neg_lo:[0,1] neg_hi:[0,1]
	v_mov_b32_e32 v112, v66
	v_mov_b32_e32 v113, v67
	v_pk_add_f32 v[98:99], v[88:89], v[86:87]
	v_pk_add_f32 v[66:67], v[88:89], v[86:87] neg_lo:[0,1] neg_hi:[0,1]
	v_mov_b32_e32 v88, v66
	v_mov_b32_e32 v89, v67
	v_pk_add_f32 v[86:87], v[108:109], v[90:91]
	v_pk_add_f32 v[66:67], v[108:109], v[90:91] neg_lo:[0,1] neg_hi:[0,1]
	v_mov_b32_e32 v108, v66
	v_mov_b32_e32 v109, v67
	v_pk_add_f32 v[90:91], v[82:83], v[96:97]
	v_pk_add_f32 v[66:67], v[82:83], v[96:97] neg_lo:[0,1] neg_hi:[0,1]
	v_mov_b32_e32 v96, v66
	v_mov_b32_e32 v97, v67
	v_pk_add_f32 v[82:83], v[106:107], v[100:101]
	v_pk_add_f32 v[66:67], v[106:107], v[100:101] neg_lo:[0,1] neg_hi:[0,1]
	v_mov_b32_e32 v106, v66
	v_mov_b32_e32 v107, v67
	s_nop 0
	v_cvt_f32_i32_e32 v66, v114
	v_mul_f32_e32 v66, 0xb9800000, v66
	v_mul_f32_e32 v66, 0.5, v66
	v_sin_f32_e32 v101, v66
	v_cos_f32_e32 v100, v66
	v_ashrrev_i32_e32 v66, 4, v114
	v_add_lshl_u32 v66, v66, v114, 3
	v_add_u32_e32 v116, 0, v66
	v_add_u32_e32 v117, s33, v66
	v_mov_b64_e32 v[66:67], s[90:91]
	v_pk_mul_f32 v[114:115], v[68:69], v[66:67] op_sel:[1,1] op_sel_hi:[1,0] neg_lo:[1,0]
	v_pk_fma_f32 v[68:69], v[68:69], v[66:67], v[114:115] op_sel_hi:[0,1,1]
	ds_write_b64 v116, v[68:69]
	v_pk_mul_f32 v[114:115], v[94:95], v[66:67] op_sel:[1,1] op_sel_hi:[1,0] neg_lo:[1,0]
	v_pk_fma_f32 v[68:69], v[94:95], v[66:67], v[114:115] op_sel_hi:[0,1,1]
	ds_write_b64 v117, v[68:69]
	v_pk_mul_f32 v[68:69], v[66:67], v[100:101] op_sel:[1,1] op_sel_hi:[1,0] neg_lo:[1,0]
	v_pk_fma_f32 v[94:95], v[66:67], v[100:101], v[68:69] op_sel_hi:[0,1,1]
	v_pk_mul_f32 v[114:115], v[76:77], v[94:95] op_sel:[1,1] op_sel_hi:[1,0] neg_lo:[1,0]
	v_pk_fma_f32 v[68:69], v[76:77], v[94:95], v[114:115] op_sel_hi:[0,1,1]
	ds_write_b64 v116, v[68:69] offset:4352
	v_pk_mul_f32 v[76:77], v[98:99], v[94:95] op_sel:[1,1] op_sel_hi:[1,0] neg_lo:[1,0]
	v_pk_fma_f32 v[68:69], v[98:99], v[94:95], v[76:77] op_sel_hi:[0,1,1]
	ds_write_b64 v117, v[68:69] offset:4352
	v_pk_mul_f32 v[68:69], v[94:95], v[100:101] op_sel:[1,1] op_sel_hi:[1,0] neg_lo:[1,0]
	v_pk_fma_f32 v[76:77], v[94:95], v[100:101], v[68:69] op_sel_hi:[0,1,1]
	v_pk_mul_f32 v[94:95], v[70:71], v[76:77] op_sel:[1,1] op_sel_hi:[1,0] neg_lo:[1,0]
	v_pk_fma_f32 v[68:69], v[70:71], v[76:77], v[94:95] op_sel_hi:[0,1,1]
	ds_write_b64 v116, v[68:69] offset:8704
	v_pk_mul_f32 v[70:71], v[84:85], v[76:77] op_sel:[1,1] op_sel_hi:[1,0] neg_lo:[1,0]
	v_pk_fma_f32 v[68:69], v[84:85], v[76:77], v[70:71] op_sel_hi:[0,1,1]
	ds_write_b64 v117, v[68:69] offset:8704
	v_pk_mul_f32 v[68:69], v[76:77], v[100:101] op_sel:[1,1] op_sel_hi:[1,0] neg_lo:[1,0]
	v_pk_fma_f32 v[70:71], v[76:77], v[100:101], v[68:69] op_sel_hi:[0,1,1]
	v_pk_mul_f32 v[76:77], v[78:79], v[70:71] op_sel:[1,1] op_sel_hi:[1,0] neg_lo:[1,0]
	v_pk_fma_f32 v[68:69], v[78:79], v[70:71], v[76:77] op_sel_hi:[0,1,1]
	ds_write_b64 v116, v[68:69] offset:13056
	v_pk_mul_f32 v[76:77], v[90:91], v[70:71] op_sel:[1,1] op_sel_hi:[1,0] neg_lo:[1,0]
	v_pk_fma_f32 v[68:69], v[90:91], v[70:71], v[76:77] op_sel_hi:[0,1,1]
	ds_write_b64 v117, v[68:69] offset:13056
	v_pk_mul_f32 v[68:69], v[70:71], v[100:101] op_sel:[1,1] op_sel_hi:[1,0] neg_lo:[1,0]
	v_pk_fma_f32 v[70:71], v[70:71], v[100:101], v[68:69] op_sel_hi:[0,1,1]
	v_pk_mul_f32 v[68:69], v[16:17], v[70:71] op_sel:[1,1] op_sel_hi:[1,0] neg_lo:[1,0]
	v_pk_fma_f32 v[16:17], v[16:17], v[70:71], v[68:69] op_sel_hi:[0,1,1]
	ds_write_b64 v116, v[16:17] offset:17408
	v_pk_mul_f32 v[68:69], v[80:81], v[70:71] op_sel:[1,1] op_sel_hi:[1,0] neg_lo:[1,0]
	v_pk_fma_f32 v[16:17], v[80:81], v[70:71], v[68:69] op_sel_hi:[0,1,1]
	ds_write_b64 v117, v[16:17] offset:17408
	v_pk_mul_f32 v[16:17], v[70:71], v[100:101] op_sel:[1,1] op_sel_hi:[1,0] neg_lo:[1,0]
	v_pk_fma_f32 v[68:69], v[70:71], v[100:101], v[16:17] op_sel_hi:[0,1,1]
	v_pk_mul_f32 v[70:71], v[72:73], v[68:69] op_sel:[1,1] op_sel_hi:[1,0] neg_lo:[1,0]
	v_pk_fma_f32 v[16:17], v[72:73], v[68:69], v[70:71] op_sel_hi:[0,1,1]
	ds_write_b64 v116, v[16:17] offset:21760
	v_pk_mul_f32 v[70:71], v[86:87], v[68:69] op_sel:[1,1] op_sel_hi:[1,0] neg_lo:[1,0]
	v_pk_fma_f32 v[16:17], v[86:87], v[68:69], v[70:71] op_sel_hi:[0,1,1]
	ds_write_b64 v117, v[16:17] offset:21760
	v_pk_mul_f32 v[16:17], v[68:69], v[100:101] op_sel:[1,1] op_sel_hi:[1,0] neg_lo:[1,0]
	v_pk_fma_f32 v[68:69], v[68:69], v[100:101], v[16:17] op_sel_hi:[0,1,1]
	v_pk_mul_f32 v[70:71], v[18:19], v[68:69] op_sel:[1,1] op_sel_hi:[1,0] neg_lo:[1,0]
	v_pk_fma_f32 v[16:17], v[18:19], v[68:69], v[70:71] op_sel_hi:[0,1,1]
	ds_write_b64 v116, v[16:17] offset:26112
	v_pk_mul_f32 v[18:19], v[92:93], v[68:69] op_sel:[1,1] op_sel_hi:[1,0] neg_lo:[1,0]
	v_pk_fma_f32 v[16:17], v[92:93], v[68:69], v[18:19] op_sel_hi:[0,1,1]
	ds_write_b64 v117, v[16:17] offset:26112
	v_pk_mul_f32 v[16:17], v[68:69], v[100:101] op_sel:[1,1] op_sel_hi:[1,0] neg_lo:[1,0]
	v_pk_fma_f32 v[18:19], v[68:69], v[100:101], v[16:17] op_sel_hi:[0,1,1]
	v_pk_mul_f32 v[68:69], v[74:75], v[18:19] op_sel:[1,1] op_sel_hi:[1,0] neg_lo:[1,0]
	v_pk_fma_f32 v[16:17], v[74:75], v[18:19], v[68:69] op_sel_hi:[0,1,1]
	ds_write_b64 v116, v[16:17] offset:30464
	v_pk_mul_f32 v[68:69], v[82:83], v[18:19] op_sel:[1,1] op_sel_hi:[1,0] neg_lo:[1,0]
	v_pk_fma_f32 v[16:17], v[82:83], v[18:19], v[68:69] op_sel_hi:[0,1,1]
	ds_write_b64 v117, v[16:17] offset:30464
	v_pk_mul_f32 v[16:17], v[18:19], v[100:101] op_sel:[1,1] op_sel_hi:[1,0] neg_lo:[1,0]
	v_pk_fma_f32 v[18:19], v[18:19], v[100:101], v[16:17] op_sel_hi:[0,1,1]
	v_pk_mul_f32 v[16:17], v[4:5], v[18:19] op_sel:[1,1] op_sel_hi:[1,0] neg_lo:[1,0]
	v_pk_fma_f32 v[4:5], v[4:5], v[18:19], v[16:17] op_sel_hi:[0,1,1]
; #define LAS __attribute__((address_space(3)))
; #define SINCOSPI(x, s, c) do { const float hx_ = 0.5f * (x); *(s) = __builtin_amdgcn_sinf(hx_); *(c) = __builtin_amdgcn_cosf(hx_); } while (0)
; #define OPAQUE_I(x) asm volatile("" : "+v"(x))
; DEV void fft_f1x2(LAS cf* buf0, LAS cf* buf1, const cf (&z0)[8], const cf (&z1)[8], int tid) {
;     ...
;     float sn, cs; SINCOSPI(-(float)tid * (2.0f / 8192.0f), &sn, &cs);
;     const cf w = cf{cs, sn}; cf wp = cf{1.f, 0.f};
;     LAS cf* p0 = buf0 + PADI(tid); LAS cf* p1 = buf1 + PADI(tid);
; #pragma unroll
;     for (int p = 0; p < 16; ++p) { p0[544 * p] = cmul(v[BR16[p]], wp); p1[544 * p] = cmul(u[BR16[p]], wp); wp = cmul(wp, w); }
; DEV void fft_f2(LAS cf* buf, int t8) {
;     OPAQUE_I(t8);
;     LAS cf* pb = buf + (t8 >> 4) * 544 + (t8 & 15);
;     cf v[32];
; #pragma unroll
;     for (int q = 0; q < 32; ++q) v[q] = pb[17 * q];
;     dft_regs<32, false>(v);
	ds_write_b64 v116, v[4:5] offset:34816
	v_pk_mul_f32 v[16:17], v[104:105], v[18:19] op_sel:[1,1] op_sel_hi:[1,0] neg_lo:[1,0]
	v_pk_fma_f32 v[4:5], v[104:105], v[18:19], v[16:17] op_sel_hi:[0,1,1]
	ds_write_b64 v117, v[4:5] offset:34816
	v_pk_mul_f32 v[4:5], v[18:19], v[100:101] op_sel:[1,1] op_sel_hi:[1,0] neg_lo:[1,0]
	v_pk_fma_f32 v[16:17], v[18:19], v[100:101], v[4:5] op_sel_hi:[0,1,1]
	v_pk_mul_f32 v[18:19], v[12:13], v[16:17] op_sel:[1,1] op_sel_hi:[1,0] neg_lo:[1,0]
	v_pk_fma_f32 v[4:5], v[12:13], v[16:17], v[18:19] op_sel_hi:[0,1,1]
	ds_write_b64 v116, v[4:5] offset:39168
	v_pk_mul_f32 v[12:13], v[88:89], v[16:17] op_sel:[1,1] op_sel_hi:[1,0] neg_lo:[1,0]
	v_pk_fma_f32 v[4:5], v[88:89], v[16:17], v[12:13] op_sel_hi:[0,1,1]
	ds_write_b64 v117, v[4:5] offset:39168
	v_pk_mul_f32 v[4:5], v[16:17], v[100:101] op_sel:[1,1] op_sel_hi:[1,0] neg_lo:[1,0]
	v_pk_fma_f32 v[12:13], v[16:17], v[100:101], v[4:5] op_sel_hi:[0,1,1]
	v_pk_mul_f32 v[16:17], v[6:7], v[12:13] op_sel:[1,1] op_sel_hi:[1,0] neg_lo:[1,0]
	v_pk_fma_f32 v[4:5], v[6:7], v[12:13], v[16:17] op_sel_hi:[0,1,1]
	ds_write_b64 v116, v[4:5] offset:43520
	v_pk_mul_f32 v[6:7], v[102:103], v[12:13] op_sel:[1,1] op_sel_hi:[1,0] neg_lo:[1,0]
	v_pk_fma_f32 v[4:5], v[102:103], v[12:13], v[6:7] op_sel_hi:[0,1,1]
	ds_write_b64 v117, v[4:5] offset:43520
	v_pk_mul_f32 v[4:5], v[12:13], v[100:101] op_sel:[1,1] op_sel_hi:[1,0] neg_lo:[1,0]
	v_pk_fma_f32 v[6:7], v[12:13], v[100:101], v[4:5] op_sel_hi:[0,1,1]
	v_pk_mul_f32 v[12:13], v[14:15], v[6:7] op_sel:[1,1] op_sel_hi:[1,0] neg_lo:[1,0]
	v_pk_fma_f32 v[4:5], v[14:15], v[6:7], v[12:13] op_sel_hi:[0,1,1]
	ds_write_b64 v116, v[4:5] offset:47872
	v_pk_mul_f32 v[12:13], v[96:97], v[6:7] op_sel:[1,1] op_sel_hi:[1,0] neg_lo:[1,0]
	v_pk_fma_f32 v[4:5], v[96:97], v[6:7], v[12:13] op_sel_hi:[0,1,1]
	ds_write_b64 v117, v[4:5] offset:47872
	v_pk_mul_f32 v[4:5], v[6:7], v[100:101] op_sel:[1,1] op_sel_hi:[1,0] neg_lo:[1,0]
	v_pk_fma_f32 v[6:7], v[6:7], v[100:101], v[4:5] op_sel_hi:[0,1,1]
	v_pk_mul_f32 v[4:5], v[0:1], v[6:7] op_sel:[1,1] op_sel_hi:[1,0] neg_lo:[1,0]
	v_pk_fma_f32 v[0:1], v[0:1], v[6:7], v[4:5] op_sel_hi:[0,1,1]
	ds_write_b64 v116, v[0:1] offset:52224
	v_pk_mul_f32 v[4:5], v[110:111], v[6:7] op_sel:[1,1] op_sel_hi:[1,0] neg_lo:[1,0]
	v_pk_fma_f32 v[0:1], v[110:111], v[6:7], v[4:5] op_sel_hi:[0,1,1]
	ds_write_b64 v117, v[0:1] offset:52224
	v_pk_mul_f32 v[0:1], v[6:7], v[100:101] op_sel:[1,1] op_sel_hi:[1,0] neg_lo:[1,0]
	v_pk_fma_f32 v[4:5], v[6:7], v[100:101], v[0:1] op_sel_hi:[0,1,1]
	v_pk_mul_f32 v[6:7], v[8:9], v[4:5] op_sel:[1,1] op_sel_hi:[1,0] neg_lo:[1,0]
	v_pk_fma_f32 v[0:1], v[8:9], v[4:5], v[6:7] op_sel_hi:[0,1,1]
	ds_write_b64 v116, v[0:1] offset:56576
	v_pk_mul_f32 v[6:7], v[108:109], v[4:5] op_sel:[1,1] op_sel_hi:[1,0] neg_lo:[1,0]
	v_pk_fma_f32 v[0:1], v[108:109], v[4:5], v[6:7] op_sel_hi:[0,1,1]
	ds_write_b64 v117, v[0:1] offset:56576
	v_pk_mul_f32 v[0:1], v[4:5], v[100:101] op_sel:[1,1] op_sel_hi:[1,0] neg_lo:[1,0]
	v_pk_fma_f32 v[4:5], v[4:5], v[100:101], v[0:1] op_sel_hi:[0,1,1]
	v_pk_mul_f32 v[6:7], v[2:3], v[4:5] op_sel:[1,1] op_sel_hi:[1,0] neg_lo:[1,0]
	v_pk_fma_f32 v[0:1], v[2:3], v[4:5], v[6:7] op_sel_hi:[0,1,1]
	ds_write_b64 v116, v[0:1] offset:60928
	v_pk_mul_f32 v[2:3], v[112:113], v[4:5] op_sel:[1,1] op_sel_hi:[1,0] neg_lo:[1,0]
	v_pk_fma_f32 v[0:1], v[112:113], v[4:5], v[2:3] op_sel_hi:[0,1,1]
	ds_write_b64 v117, v[0:1] offset:60928
	v_pk_mul_f32 v[0:1], v[4:5], v[100:101] op_sel:[1,1] op_sel_hi:[1,0] neg_lo:[1,0]
	v_pk_fma_f32 v[2:3], v[4:5], v[100:101], v[0:1] op_sel_hi:[0,1,1]
	v_pk_mul_f32 v[4:5], v[10:11], v[2:3] op_sel:[1,1] op_sel_hi:[1,0] neg_lo:[1,0]
	v_pk_fma_f32 v[0:1], v[10:11], v[2:3], v[4:5] op_sel_hi:[0,1,1]
	ds_write_b64 v116, v[0:1] offset:65280
	v_pk_mul_f32 v[4:5], v[106:107], v[2:3] op_sel:[1,1] op_sel_hi:[1,0] neg_lo:[1,0]
	v_pk_fma_f32 v[0:1], v[106:107], v[2:3], v[4:5] op_sel_hi:[0,1,1]
	ds_write_b64 v117, v[0:1] offset:65280
	v_mov_b32_e32 v0, v160
	s_waitcnt lgkmcnt(0)
	s_barrier
	s_nop 0
	v_lshrrev_b32_e32 v1, 4, v0
	v_and_b32_e32 v3, 15, v0
	v_mul_lo_u32 v1, v1, s15
	v_lshlrev_b32_e32 v0, 3, v3
	v_add3_u32 v2, v159, v1, v0
	ds_read2_b64 v[4:7], v2 offset1:17
	ds_read2_b64 v[8:11], v2 offset0:34 offset1:51
	ds_read2_b64 v[12:15], v2 offset0:68 offset1:85
	ds_read2_b64 v[16:19], v2 offset0:102 offset1:119
	ds_read2_b64 v[68:71], v2 offset0:136 offset1:153
	ds_read2_b64 v[72:75], v2 offset0:170 offset1:187
	ds_read2_b64 v[76:79], v2 offset0:204 offset1:221
	ds_read2_b64 v[80:83], v2 offset0:238 offset1:255
	v_add_u32_e32 v0, 0x800, v2
	ds_read2_b64 v[84:87], v0 offset0:16 offset1:33
	ds_read2_b64 v[88:91], v0 offset0:50 offset1:67
	ds_read2_b64 v[92:95], v0 offset0:84 offset1:101
	ds_read2_b64 v[96:99], v0 offset0:118 offset1:135
	ds_read2_b64 v[100:103], v0 offset0:152 offset1:169
	ds_read2_b64 v[104:107], v0 offset0:186 offset1:203
	ds_read2_b64 v[108:111], v0 offset0:220 offset1:237
	s_waitcnt lgkmcnt(6)
	v_pk_add_f32 v[116:117], v[4:5], v[84:85]
	v_pk_add_f32 v[4:5], v[4:5], v[84:85] neg_lo:[0,1] neg_hi:[0,1]
	v_add_u32_e32 v1, 0xc00, v2
	ds_read2_b64 v[112:115], v1 offset0:126 offset1:143
	v_mov_b32_e32 v118, v4
	v_mov_b32_e32 v119, v5
	v_cvt_f32_ubyte0_e32 v3, v3
	v_pk_add_f32 v[4:5], v[6:7], v[86:87]
	v_pk_add_f32 v[6:7], v[6:7], v[86:87] neg_lo:[0,1] neg_hi:[0,1]
	v_mul_f32_e32 v3, 0xbb800000, v3
	v_pk_mul_f32 v[84:85], v[6:7], s[82:83] op_sel_hi:[1,0]
	v_mul_f32_e32 v3, 0.5, v3
	v_pk_fma_f32 v[86:87], v[6:7], s[94:95], v[84:85] op_sel:[0,0,1] op_sel_hi:[1,0,0]
	v_pk_fma_f32 v[6:7], v[6:7], s[94:95], v[84:85] op_sel:[0,0,1] op_sel_hi:[1,0,0] neg_lo:[0,0,1] neg_hi:[0,0,1]
	v_mov_b32_e32 v87, v7
	s_waitcnt lgkmcnt(6)
; template <int R, bool INV> DEV void dft_regs(cf (&v)[R]) {
;     ...
;     for (int s = R; s >= 2; s >>= 1) {
;         const int h = s >> 1;
; #pragma unroll
;         for (int b = 0; b < R; b += s) {
; #pragma unroll
;             for (int k = 0; k < h; ++k) {
;                 const cf a = v[b + k], c = v[b + k + h];
;                 v[b + k] = a + c;
;                 const cf d = a - c;
;                 const int m = k * (32 / s);
;                 const float wr = tw_cos(m), wi = INV ? tw_sin(m) : -tw_sin(m);
;                 v[b + k + h] = cf{d.x * wr - d.y * wi, d.x * wi + d.y * wr};
;             }
	v_pk_add_f32 v[6:7], v[8:9], v[88:89]
	v_pk_add_f32 v[8:9], v[8:9], v[88:89] neg_lo:[0,1] neg_hi:[0,1]
	v_pk_mul_f32 v[84:85], v[8:9], s[84:85] op_sel_hi:[1,0]
	v_pk_fma_f32 v[88:89], v[8:9], s[16:17], v[84:85] op_sel:[0,0,1] op_sel_hi:[1,0,0]
	v_pk_fma_f32 v[8:9], v[8:9], s[16:17], v[84:85] op_sel:[0,0,1] op_sel_hi:[1,0,0] neg_lo:[0,0,1] neg_hi:[0,0,1]
	v_mov_b32_e32 v89, v9
	v_pk_add_f32 v[8:9], v[10:11], v[90:91]
	v_pk_add_f32 v[10:11], v[10:11], v[90:91] neg_lo:[0,1] neg_hi:[0,1]
	v_pk_mul_f32 v[84:85], v[10:11], s[4:5] op_sel_hi:[1,0]
	v_pk_fma_f32 v[90:91], v[10:11], s[86:87], v[84:85] op_sel:[0,0,1] op_sel_hi:[1,0,0]
	v_pk_fma_f32 v[10:11], v[10:11], s[86:87], v[84:85] op_sel:[0,0,1] op_sel_hi:[1,0,0] neg_lo:[0,0,1] neg_hi:[0,0,1]
	v_mov_b32_e32 v91, v11
	s_waitcnt lgkmcnt(5)
	v_pk_add_f32 v[10:11], v[12:13], v[92:93]
	v_pk_add_f32 v[12:13], v[12:13], v[92:93] neg_lo:[0,1] neg_hi:[0,1]
	v_pk_mul_f32 v[84:85], v[12:13], s[18:19] op_sel_hi:[1,0]
	v_pk_fma_f32 v[92:93], v[12:13], s[18:19], v[84:85] op_sel:[0,0,1] op_sel_hi:[1,0,0]
	v_pk_fma_f32 v[12:13], v[12:13], s[18:19], v[84:85] op_sel_hi:[1,0,0] neg_lo:[0,0,1] neg_hi:[0,0,1]
	v_mov_b32_e32 v93, v13
	v_pk_add_f32 v[12:13], v[14:15], v[94:95]
	v_pk_add_f32 v[14:15], v[14:15], v[94:95] neg_lo:[0,1] neg_hi:[0,1]
	v_pk_mul_f32 v[84:85], v[14:15], s[86:87] op_sel_hi:[1,0]
	v_pk_fma_f32 v[94:95], v[14:15], s[4:5], v[84:85] op_sel:[0,0,1] op_sel_hi:[1,0,0]
	v_pk_fma_f32 v[14:15], v[14:15], s[4:5], v[84:85] op_sel:[0,0,1] op_sel_hi:[1,0,0] neg_lo:[0,0,1] neg_hi:[0,0,1]
	s_mov_b32 s5, s86
	v_mov_b32_e32 v95, v15
	s_waitcnt lgkmcnt(4)
	v_pk_add_f32 v[14:15], v[16:17], v[96:97]
	v_pk_add_f32 v[16:17], v[16:17], v[96:97] neg_lo:[0,1] neg_hi:[0,1]
	v_pk_mul_f32 v[84:85], v[16:17], s[16:17] op_sel_hi:[1,0]
	v_pk_fma_f32 v[96:97], v[16:17], s[84:85], v[84:85] op_sel:[0,0,1] op_sel_hi:[1,0,0]
	v_pk_fma_f32 v[16:17], v[16:17], s[84:85], v[84:85] op_sel:[0,0,1] op_sel_hi:[1,0,0] neg_lo:[0,0,1] neg_hi:[0,0,1]
	v_mov_b32_e32 v97, v17
	v_pk_add_f32 v[16:17], v[18:19], v[98:99]
	v_pk_add_f32 v[18:19], v[18:19], v[98:99] neg_lo:[0,1] neg_hi:[0,1]
	v_pk_mul_f32 v[84:85], v[18:19], s[94:95] op_sel_hi:[1,0]
	v_pk_fma_f32 v[98:99], v[18:19], s[82:83], v[84:85] op_sel:[0,0,1] op_sel_hi:[1,0,0]
	v_pk_fma_f32 v[18:19], v[18:19], s[82:83], v[84:85] op_sel:[0,0,1] op_sel_hi:[1,0,0] neg_lo:[0,0,1] neg_hi:[0,0,1]
	s_mov_b32 s83, s94
	v_mov_b32_e32 v99, v19
	s_waitcnt lgkmcnt(3)
	v_pk_add_f32 v[18:19], v[68:69], v[100:101]
	v_pk_add_f32 v[68:69], v[68:69], v[100:101] neg_lo:[0,1] neg_hi:[0,1]
	v_pk_add_f32 v[84:85], v[68:69], 0 op_sel:[1,0] op_sel_hi:[0,0] neg_hi:[1,0]
	v_pk_add_f32 v[68:69], v[70:71], v[102:103]
	v_pk_add_f32 v[70:71], v[70:71], v[102:103] neg_lo:[0,1] neg_hi:[0,1]
	v_pk_mul_f32 v[100:101], v[70:71], s[82:83] op_sel_hi:[0,1]
	v_pk_fma_f32 v[70:71], v[70:71], s[94:95], v[100:101] op_sel:[1,0,0] neg_lo:[0,0,1] neg_hi:[0,0,1]
	s_waitcnt lgkmcnt(2)
	v_pk_add_f32 v[100:101], v[72:73], v[104:105]
	v_pk_add_f32 v[72:73], v[72:73], v[104:105] neg_lo:[0,1] neg_hi:[0,1]
	v_pk_mul_f32 v[102:103], v[72:73], s[84:85] op_sel_hi:[0,1]
	v_pk_fma_f32 v[72:73], v[72:73], s[30:31], v[102:103] op_sel:[1,0,0] neg_lo:[0,0,1] neg_hi:[0,0,1]
	v_pk_add_f32 v[102:103], v[74:75], v[106:107]
	v_pk_add_f32 v[74:75], v[74:75], v[106:107] neg_lo:[0,1] neg_hi:[0,1]
	v_pk_mul_f32 v[104:105], v[74:75], s[4:5] op_sel_hi:[0,1]
	v_pk_fma_f32 v[74:75], v[74:75], s[86:87], v[104:105] op_sel:[1,0,0] neg_lo:[0,0,1] neg_hi:[0,0,1]
	s_waitcnt lgkmcnt(1)
	v_pk_add_f32 v[104:105], v[76:77], v[108:109]
	v_pk_add_f32 v[76:77], v[76:77], v[108:109] neg_lo:[0,1] neg_hi:[0,1]
	v_mul_f32_e32 v106, 0x3f3504f3, v76
	v_pk_fma_f32 v[76:77], v[76:77], s[28:29], v[106:107] op_sel:[1,0,0] op_sel_hi:[1,1,0] neg_lo:[0,0,1] neg_hi:[0,0,1]
	v_pk_add_f32 v[106:107], v[78:79], v[110:111]
	v_pk_add_f32 v[78:79], v[78:79], v[110:111] neg_lo:[0,1] neg_hi:[0,1]
	v_pk_mul_f32 v[108:109], v[78:79], s[2:3] op_sel_hi:[0,1]
	v_pk_fma_f32 v[78:79], v[78:79], s[10:11], v[108:109] op_sel:[1,0,0] neg_lo:[0,0,1] neg_hi:[0,0,1]
	s_waitcnt lgkmcnt(0)
	v_pk_add_f32 v[108:109], v[80:81], v[112:113]
	v_pk_add_f32 v[80:81], v[80:81], v[112:113] neg_lo:[0,1] neg_hi:[0,1]
	v_pk_mul_f32 v[110:111], v[80:81], s[24:25] op_sel_hi:[0,1]
	v_pk_fma_f32 v[80:81], v[80:81], s[34:35], v[110:111] op_sel:[1,0,0] neg_lo:[0,0,1] neg_hi:[0,0,1]
	v_pk_add_f32 v[110:111], v[82:83], v[114:115]
	v_pk_add_f32 v[82:83], v[82:83], v[114:115] neg_lo:[0,1] neg_hi:[0,1]
	v_pk_mul_f32 v[112:113], v[82:83], s[6:7] op_sel_hi:[0,1]
	v_pk_fma_f32 v[82:83], v[82:83], s[8:9], v[112:113] op_sel:[1,0,0] neg_lo:[0,0,1] neg_hi:[0,0,1]
	v_pk_add_f32 v[112:113], v[116:117], v[18:19]
	v_pk_add_f32 v[18:19], v[116:117], v[18:19] neg_lo:[0,1] neg_hi:[0,1]
	v_mov_b32_e32 v116, v18
	v_mov_b32_e32 v117, v19
	v_pk_add_f32 v[18:19], v[4:5], v[68:69]
	v_pk_add_f32 v[4:5], v[4:5], v[68:69] neg_lo:[0,1] neg_hi:[0,1]
	v_pk_mul_f32 v[68:69], v[4:5], s[84:85] op_sel_hi:[1,0]
	v_pk_fma_f32 v[114:115], v[4:5], s[16:17], v[68:69] op_sel:[0,0,1] op_sel_hi:[1,0,0]
	v_pk_fma_f32 v[4:5], v[4:5], s[16:17], v[68:69] op_sel:[0,0,1] op_sel_hi:[1,0,0] neg_lo:[0,0,1] neg_hi:[0,0,1]
	v_mov_b32_e32 v115, v5
	v_pk_add_f32 v[4:5], v[6:7], v[100:101]
	v_pk_add_f32 v[6:7], v[6:7], v[100:101] neg_lo:[0,1] neg_hi:[0,1]
	v_pk_mul_f32 v[68:69], v[6:7], s[18:19] op_sel_hi:[1,0]
	v_pk_fma_f32 v[100:101], v[6:7], s[18:19], v[68:69] op_sel:[0,0,1] op_sel_hi:[1,0,0]
	v_pk_fma_f32 v[6:7], v[6:7], s[18:19], v[68:69] op_sel_hi:[1,0,0] neg_lo:[0,0,1] neg_hi:[0,0,1]
	v_mov_b32_e32 v101, v7
	v_pk_add_f32 v[6:7], v[8:9], v[102:103]
; template <int R, bool INV> DEV void dft_regs(cf (&v)[R]) {
;     ...
;     for (int s = R; s >= 2; s >>= 1) {
;         const int h = s >> 1;
; #pragma unroll
;         for (int b = 0; b < R; b += s) {
; #pragma unroll
;             for (int k = 0; k < h; ++k) {
;                 const cf a = v[b + k], c = v[b + k + h];
;                 v[b + k] = a + c;
;                 const cf d = a - c;
;                 const int m = k * (32 / s);
;                 const float wr = tw_cos(m), wi = INV ? tw_sin(m) : -tw_sin(m);
;                 v[b + k + h] = cf{d.x * wr - d.y * wi, d.x * wi + d.y * wr};
;             }
	v_pk_add_f32 v[8:9], v[8:9], v[102:103] neg_lo:[0,1] neg_hi:[0,1]
	v_pk_mul_f32 v[68:69], v[8:9], s[16:17] op_sel_hi:[1,0]
	v_pk_fma_f32 v[102:103], v[8:9], s[84:85], v[68:69] op_sel:[0,0,1] op_sel_hi:[1,0,0]
	v_pk_fma_f32 v[8:9], v[8:9], s[84:85], v[68:69] op_sel:[0,0,1] op_sel_hi:[1,0,0] neg_lo:[0,0,1] neg_hi:[0,0,1]
	v_mov_b32_e32 v103, v9
	v_pk_add_f32 v[8:9], v[10:11], v[104:105]
	v_pk_add_f32 v[10:11], v[10:11], v[104:105] neg_lo:[0,1] neg_hi:[0,1]
	v_pk_add_f32 v[68:69], v[10:11], 0 op_sel:[1,0] op_sel_hi:[0,0] neg_hi:[1,0]
	v_pk_add_f32 v[10:11], v[12:13], v[106:107]
	v_pk_add_f32 v[12:13], v[12:13], v[106:107] neg_lo:[0,1] neg_hi:[0,1]
	v_pk_mul_f32 v[104:105], v[12:13], s[84:85] op_sel_hi:[0,1]
	v_pk_fma_f32 v[12:13], v[12:13], s[30:31], v[104:105] op_sel:[1,0,0] neg_lo:[0,0,1] neg_hi:[0,0,1]
	v_pk_add_f32 v[104:105], v[14:15], v[108:109]
	v_pk_add_f32 v[14:15], v[14:15], v[108:109] neg_lo:[0,1] neg_hi:[0,1]
	v_mul_f32_e32 v106, 0x3f3504f3, v14
	v_pk_fma_f32 v[14:15], v[14:15], s[28:29], v[106:107] op_sel:[1,0,0] op_sel_hi:[1,1,0] neg_lo:[0,0,1] neg_hi:[0,0,1]
	v_pk_add_f32 v[106:107], v[16:17], v[110:111]
	v_pk_add_f32 v[16:17], v[16:17], v[110:111] neg_lo:[0,1] neg_hi:[0,1]
	v_pk_mul_f32 v[108:109], v[16:17], s[24:25] op_sel_hi:[0,1]
	v_pk_fma_f32 v[16:17], v[16:17], s[34:35], v[108:109] op_sel:[1,0,0] neg_lo:[0,0,1] neg_hi:[0,0,1]
	v_pk_add_f32 v[108:109], v[118:119], v[84:85]
	v_pk_add_f32 v[84:85], v[118:119], v[84:85] neg_lo:[0,1] neg_hi:[0,1]
	v_mov_b32_e32 v118, v84
	v_mov_b32_e32 v119, v85
	v_pk_add_f32 v[84:85], v[86:87], v[70:71]
	v_pk_add_f32 v[70:71], v[86:87], v[70:71] neg_lo:[0,1] neg_hi:[0,1]
	v_pk_mul_f32 v[86:87], v[70:71], s[84:85] op_sel_hi:[1,0]
	v_pk_fma_f32 v[110:111], v[70:71], s[16:17], v[86:87] op_sel:[0,0,1] op_sel_hi:[1,0,0]
	v_pk_fma_f32 v[70:71], v[70:71], s[16:17], v[86:87] op_sel:[0,0,1] op_sel_hi:[1,0,0] neg_lo:[0,0,1] neg_hi:[0,0,1]
	v_mov_b32_e32 v111, v71
	v_pk_add_f32 v[70:71], v[88:89], v[72:73]
	v_pk_add_f32 v[72:73], v[88:89], v[72:73] neg_lo:[0,1] neg_hi:[0,1]
	v_pk_mul_f32 v[86:87], v[72:73], s[18:19] op_sel_hi:[1,0]
	v_pk_fma_f32 v[88:89], v[72:73], s[18:19], v[86:87] op_sel:[0,0,1] op_sel_hi:[1,0,0]
	v_pk_fma_f32 v[72:73], v[72:73], s[18:19], v[86:87] op_sel_hi:[1,0,0] neg_lo:[0,0,1] neg_hi:[0,0,1]
	v_mov_b32_e32 v89, v73
	v_pk_add_f32 v[72:73], v[90:91], v[74:75]
	v_pk_add_f32 v[74:75], v[90:91], v[74:75] neg_lo:[0,1] neg_hi:[0,1]
	v_pk_mul_f32 v[86:87], v[74:75], s[16:17] op_sel_hi:[1,0]
	v_pk_fma_f32 v[90:91], v[74:75], s[84:85], v[86:87] op_sel:[0,0,1] op_sel_hi:[1,0,0]
	v_pk_fma_f32 v[74:75], v[74:75], s[84:85], v[86:87] op_sel:[0,0,1] op_sel_hi:[1,0,0] neg_lo:[0,0,1] neg_hi:[0,0,1]
	v_mov_b32_e32 v91, v75
	v_pk_add_f32 v[74:75], v[92:93], v[76:77]
	v_pk_add_f32 v[76:77], v[92:93], v[76:77] neg_lo:[0,1] neg_hi:[0,1]
	v_pk_add_f32 v[86:87], v[76:77], 0 op_sel:[1,0] op_sel_hi:[0,0] neg_hi:[1,0]
	v_pk_add_f32 v[76:77], v[94:95], v[78:79]
	v_pk_add_f32 v[78:79], v[94:95], v[78:79] neg_lo:[0,1] neg_hi:[0,1]
	v_pk_mul_f32 v[92:93], v[78:79], s[84:85] op_sel_hi:[0,1]
	v_pk_fma_f32 v[78:79], v[78:79], s[30:31], v[92:93] op_sel:[1,0,0] neg_lo:[0,0,1] neg_hi:[0,0,1]
	v_pk_add_f32 v[92:93], v[96:97], v[80:81]
	v_pk_add_f32 v[80:81], v[96:97], v[80:81] neg_lo:[0,1] neg_hi:[0,1]
	v_mul_f32_e32 v94, 0x3f3504f3, v80
	v_pk_fma_f32 v[80:81], v[80:81], s[28:29], v[94:95] op_sel:[1,0,0] op_sel_hi:[1,1,0] neg_lo:[0,0,1] neg_hi:[0,0,1]
	v_pk_add_f32 v[94:95], v[98:99], v[82:83]
	v_pk_add_f32 v[82:83], v[98:99], v[82:83] neg_lo:[0,1] neg_hi:[0,1]
	v_pk_mul_f32 v[96:97], v[82:83], s[24:25] op_sel_hi:[0,1]
	v_pk_fma_f32 v[82:83], v[82:83], s[34:35], v[96:97] op_sel:[1,0,0] neg_lo:[0,0,1] neg_hi:[0,0,1]
	v_pk_add_f32 v[96:97], v[112:113], v[8:9]
	v_pk_add_f32 v[8:9], v[112:113], v[8:9] neg_lo:[0,1] neg_hi:[0,1]
	v_mov_b32_e32 v112, v8
	v_mov_b32_e32 v113, v9
	v_pk_add_f32 v[8:9], v[18:19], v[10:11]
	v_pk_add_f32 v[10:11], v[18:19], v[10:11] neg_lo:[0,1] neg_hi:[0,1]
	v_pk_mul_f32 v[18:19], v[10:11], s[18:19] op_sel_hi:[1,0]
	v_pk_fma_f32 v[98:99], v[10:11], s[18:19], v[18:19] op_sel:[0,0,1] op_sel_hi:[1,0,0]
	v_pk_fma_f32 v[10:11], v[10:11], s[18:19], v[18:19] op_sel_hi:[1,0,0] neg_lo:[0,0,1] neg_hi:[0,0,1]
	v_mov_b32_e32 v99, v11
	v_pk_add_f32 v[10:11], v[4:5], v[104:105]
	v_pk_add_f32 v[4:5], v[4:5], v[104:105] neg_lo:[0,1] neg_hi:[0,1]
	v_pk_add_f32 v[18:19], v[4:5], 0 op_sel:[1,0] op_sel_hi:[0,0] neg_hi:[1,0]
	v_pk_add_f32 v[4:5], v[6:7], v[106:107]
	v_pk_add_f32 v[6:7], v[6:7], v[106:107] neg_lo:[0,1] neg_hi:[0,1]
	v_mul_f32_e32 v104, 0x3f3504f3, v6
	v_pk_fma_f32 v[6:7], v[6:7], s[28:29], v[104:105] op_sel:[1,0,0] op_sel_hi:[1,1,0] neg_lo:[0,0,1] neg_hi:[0,0,1]
	v_pk_add_f32 v[104:105], v[116:117], v[68:69]
	v_pk_add_f32 v[68:69], v[116:117], v[68:69] neg_lo:[0,1] neg_hi:[0,1]
	v_mov_b32_e32 v116, v68
	v_mov_b32_e32 v117, v69
	v_pk_add_f32 v[68:69], v[114:115], v[12:13]
	v_pk_add_f32 v[12:13], v[114:115], v[12:13] neg_lo:[0,1] neg_hi:[0,1]
	v_pk_mul_f32 v[106:107], v[12:13], s[18:19] op_sel_hi:[1,0]
	v_pk_fma_f32 v[114:115], v[12:13], s[18:19], v[106:107] op_sel:[0,0,1] op_sel_hi:[1,0,0]
	v_pk_fma_f32 v[12:13], v[12:13], s[18:19], v[106:107] op_sel_hi:[1,0,0] neg_lo:[0,0,1] neg_hi:[0,0,1]
	v_mov_b32_e32 v115, v13
	v_pk_add_f32 v[12:13], v[100:101], v[14:15]
	v_pk_add_f32 v[14:15], v[100:101], v[14:15] neg_lo:[0,1] neg_hi:[0,1]
	v_pk_add_f32 v[100:101], v[14:15], 0 op_sel:[1,0] op_sel_hi:[0,0] neg_hi:[1,0]
	v_pk_add_f32 v[14:15], v[102:103], v[16:17]
	v_pk_add_f32 v[16:17], v[102:103], v[16:17] neg_lo:[0,1] neg_hi:[0,1]
	v_mul_f32_e32 v102, 0x3f3504f3, v16
; template <int R, bool INV> DEV void dft_regs(cf (&v)[R]) {
;     ...
;     for (int s = R; s >= 2; s >>= 1) {
;         const int h = s >> 1;
; #pragma unroll
;         for (int b = 0; b < R; b += s) {
; #pragma unroll
;             for (int k = 0; k < h; ++k) {
;                 const cf a = v[b + k], c = v[b + k + h];
;                 v[b + k] = a + c;
;                 const cf d = a - c;
;                 const int m = k * (32 / s);
;                 const float wr = tw_cos(m), wi = INV ? tw_sin(m) : -tw_sin(m);
;                 v[b + k + h] = cf{d.x * wr - d.y * wi, d.x * wi + d.y * wr};
;             }
	v_pk_fma_f32 v[16:17], v[16:17], s[28:29], v[102:103] op_sel:[1,0,0] op_sel_hi:[1,1,0] neg_lo:[0,0,1] neg_hi:[0,0,1]
	v_pk_add_f32 v[102:103], v[108:109], v[74:75]
	v_pk_add_f32 v[74:75], v[108:109], v[74:75] neg_lo:[0,1] neg_hi:[0,1]
	v_mov_b32_e32 v108, v74
	v_mov_b32_e32 v109, v75
	v_pk_add_f32 v[74:75], v[84:85], v[76:77]
	v_pk_add_f32 v[76:77], v[84:85], v[76:77] neg_lo:[0,1] neg_hi:[0,1]
	v_pk_mul_f32 v[84:85], v[76:77], s[18:19] op_sel_hi:[1,0]
	v_pk_fma_f32 v[106:107], v[76:77], s[18:19], v[84:85] op_sel:[0,0,1] op_sel_hi:[1,0,0]
	v_pk_fma_f32 v[76:77], v[76:77], s[18:19], v[84:85] op_sel_hi:[1,0,0] neg_lo:[0,0,1] neg_hi:[0,0,1]
	v_mov_b32_e32 v107, v77
	v_pk_add_f32 v[76:77], v[70:71], v[92:93]
	v_pk_add_f32 v[70:71], v[70:71], v[92:93] neg_lo:[0,1] neg_hi:[0,1]
	v_pk_add_f32 v[84:85], v[70:71], 0 op_sel:[1,0] op_sel_hi:[0,0] neg_hi:[1,0]
	v_pk_add_f32 v[70:71], v[72:73], v[94:95]
	v_pk_add_f32 v[72:73], v[72:73], v[94:95] neg_lo:[0,1] neg_hi:[0,1]
	v_mul_f32_e32 v92, 0x3f3504f3, v72
	v_pk_fma_f32 v[72:73], v[72:73], s[28:29], v[92:93] op_sel:[1,0,0] op_sel_hi:[1,1,0] neg_lo:[0,0,1] neg_hi:[0,0,1]
	v_pk_add_f32 v[92:93], v[118:119], v[86:87]
	v_pk_add_f32 v[86:87], v[118:119], v[86:87] neg_lo:[0,1] neg_hi:[0,1]
	v_mov_b32_e32 v118, v86
	v_mov_b32_e32 v119, v87
	v_pk_add_f32 v[86:87], v[110:111], v[78:79]
	v_pk_add_f32 v[78:79], v[110:111], v[78:79] neg_lo:[0,1] neg_hi:[0,1]
	v_pk_mul_f32 v[94:95], v[78:79], s[18:19] op_sel_hi:[1,0]
	v_pk_fma_f32 v[110:111], v[78:79], s[18:19], v[94:95] op_sel:[0,0,1] op_sel_hi:[1,0,0]
	v_pk_fma_f32 v[78:79], v[78:79], s[18:19], v[94:95] op_sel_hi:[1,0,0] neg_lo:[0,0,1] neg_hi:[0,0,1]
	v_mov_b32_e32 v111, v79
	v_pk_add_f32 v[78:79], v[88:89], v[80:81]
	v_pk_add_f32 v[80:81], v[88:89], v[80:81] neg_lo:[0,1] neg_hi:[0,1]
	v_pk_add_f32 v[88:89], v[80:81], 0 op_sel:[1,0] op_sel_hi:[0,0] neg_hi:[1,0]
	v_pk_add_f32 v[80:81], v[90:91], v[82:83]
	v_pk_add_f32 v[82:83], v[90:91], v[82:83] neg_lo:[0,1] neg_hi:[0,1]
	v_mul_f32_e32 v90, 0x3f3504f3, v82
	v_pk_fma_f32 v[82:83], v[82:83], s[28:29], v[90:91] op_sel:[1,0,0] op_sel_hi:[1,1,0] neg_lo:[0,0,1] neg_hi:[0,0,1]
	v_pk_add_f32 v[90:91], v[96:97], v[10:11]
	v_pk_add_f32 v[10:11], v[96:97], v[10:11] neg_lo:[0,1] neg_hi:[0,1]
	v_mov_b32_e32 v96, v10
	v_mov_b32_e32 v97, v11
	v_pk_add_f32 v[10:11], v[8:9], v[4:5]
	v_pk_add_f32 v[4:5], v[8:9], v[4:5] neg_lo:[0,1] neg_hi:[0,1]
	v_pk_add_f32 v[8:9], v[4:5], 0 op_sel:[1,0] op_sel_hi:[0,0] neg_hi:[1,0]
	v_pk_add_f32 v[4:5], v[112:113], v[18:19]
	v_pk_add_f32 v[18:19], v[112:113], v[18:19] neg_lo:[0,1] neg_hi:[0,1]
	v_mov_b32_e32 v112, v18
	v_mov_b32_e32 v113, v19
	v_pk_add_f32 v[18:19], v[98:99], v[6:7]
	v_pk_add_f32 v[6:7], v[98:99], v[6:7] neg_lo:[0,1] neg_hi:[0,1]
	v_pk_add_f32 v[94:95], v[6:7], 0 op_sel:[1,0] op_sel_hi:[0,0] neg_hi:[1,0]
	v_pk_add_f32 v[6:7], v[104:105], v[12:13]
	v_pk_add_f32 v[12:13], v[104:105], v[12:13] neg_lo:[0,1] neg_hi:[0,1]
	v_mov_b32_e32 v104, v12
	v_mov_b32_e32 v105, v13
	v_pk_add_f32 v[98:99], v[116:117], v[100:101] neg_lo:[0,1] neg_hi:[0,1]
	v_pk_add_f32 v[12:13], v[68:69], v[14:15]
	v_pk_add_f32 v[14:15], v[68:69], v[14:15] neg_lo:[0,1] neg_hi:[0,1]
	v_pk_add_f32 v[68:69], v[14:15], 0 op_sel:[1,0] op_sel_hi:[0,0] neg_hi:[1,0]
	v_pk_add_f32 v[14:15], v[116:117], v[100:101]
	v_mov_b32_e32 v116, v98
	v_mov_b32_e32 v117, v99
	v_pk_add_f32 v[98:99], v[114:115], v[16:17]
	v_pk_add_f32 v[16:17], v[114:115], v[16:17] neg_lo:[0,1] neg_hi:[0,1]
	v_pk_add_f32 v[100:101], v[16:17], 0 op_sel:[1,0] op_sel_hi:[0,0] neg_hi:[1,0]
	v_pk_add_f32 v[16:17], v[102:103], v[76:77]
	v_pk_add_f32 v[76:77], v[102:103], v[76:77] neg_lo:[0,1] neg_hi:[0,1]
	v_mov_b32_e32 v114, v76
	v_mov_b32_e32 v115, v77
	v_pk_add_f32 v[76:77], v[74:75], v[70:71]
	v_pk_add_f32 v[70:71], v[74:75], v[70:71] neg_lo:[0,1] neg_hi:[0,1]
	v_pk_add_f32 v[74:75], v[70:71], 0 op_sel:[1,0] op_sel_hi:[0,0] neg_hi:[1,0]
	v_pk_add_f32 v[70:71], v[108:109], v[84:85]
	v_pk_add_f32 v[84:85], v[108:109], v[84:85] neg_lo:[0,1] neg_hi:[0,1]
	v_mov_b32_e32 v108, v84
	v_mov_b32_e32 v109, v85
	v_pk_add_f32 v[84:85], v[106:107], v[72:73]
	v_pk_add_f32 v[72:73], v[106:107], v[72:73] neg_lo:[0,1] neg_hi:[0,1]
	v_pk_add_f32 v[102:103], v[72:73], 0 op_sel:[1,0] op_sel_hi:[0,0] neg_hi:[1,0]
	v_pk_add_f32 v[72:73], v[92:93], v[78:79]
	v_pk_add_f32 v[78:79], v[92:93], v[78:79] neg_lo:[0,1] neg_hi:[0,1]
	v_mov_b32_e32 v106, v78
	v_mov_b32_e32 v107, v79
	v_pk_add_f32 v[78:79], v[86:87], v[80:81]
	v_pk_add_f32 v[80:81], v[86:87], v[80:81] neg_lo:[0,1] neg_hi:[0,1]
	v_pk_add_f32 v[86:87], v[80:81], 0 op_sel:[1,0] op_sel_hi:[0,0] neg_hi:[1,0]
	v_pk_add_f32 v[80:81], v[118:119], v[88:89]
	v_pk_add_f32 v[88:89], v[118:119], v[88:89] neg_lo:[0,1] neg_hi:[0,1]
	v_mov_b32_e32 v118, v88
	v_mov_b32_e32 v119, v89
	v_pk_add_f32 v[88:89], v[110:111], v[82:83]
	v_pk_add_f32 v[82:83], v[110:111], v[82:83] neg_lo:[0,1] neg_hi:[0,1]
	v_pk_add_f32 v[92:93], v[82:83], 0 op_sel:[1,0] op_sel_hi:[0,0] neg_hi:[1,0]
	v_pk_add_f32 v[82:83], v[90:91], v[10:11]
	v_pk_add_f32 v[10:11], v[90:91], v[10:11] neg_lo:[0,1] neg_hi:[0,1]
	v_mov_b32_e32 v110, v10
	v_mov_b32_e32 v111, v11
	v_pk_add_f32 v[10:11], v[96:97], v[8:9]
	v_pk_add_f32 v[8:9], v[96:97], v[8:9] neg_lo:[0,1] neg_hi:[0,1]
	v_mov_b32_e32 v96, v8
	v_mov_b32_e32 v97, v9
	v_pk_add_f32 v[8:9], v[4:5], v[18:19]
	v_pk_add_f32 v[4:5], v[4:5], v[18:19] neg_lo:[0,1] neg_hi:[0,1]
	v_mov_b32_e32 v90, v4
	v_mov_b32_e32 v91, v5
	v_pk_add_f32 v[18:19], v[112:113], v[94:95] neg_lo:[0,1] neg_hi:[0,1]
	v_pk_add_f32 v[4:5], v[112:113], v[94:95]
	v_mov_b32_e32 v112, v18
	v_mov_b32_e32 v113, v19
	v_pk_add_f32 v[18:19], v[6:7], v[12:13]
; #define SINCOSPI(x, s, c) do { const float hx_ = 0.5f * (x); *(s) = __builtin_amdgcn_sinf(hx_); *(c) = __builtin_amdgcn_cosf(hx_); } while (0)
; template <int R, bool INV> DEV void dft_regs(cf (&v)[R]) {
;     ...
;     for (int s = R; s >= 2; s >>= 1) {
;         const int h = s >> 1;
; #pragma unroll
;         for (int b = 0; b < R; b += s) {
; #pragma unroll
;             for (int k = 0; k < h; ++k) {
;                 const cf a = v[b + k], c = v[b + k + h];
;                 v[b + k] = a + c;
;                 const cf d = a - c;
;                 const int m = k * (32 / s);
;                 const float wr = tw_cos(m), wi = INV ? tw_sin(m) : -tw_sin(m);
;                 v[b + k + h] = cf{d.x * wr - d.y * wi, d.x * wi + d.y * wr};
;             }
; DEV void fft_f2(LAS cf* buf, int t8) {
;     ...
;     float sn, cs; SINCOSPI(-(float)(t8 & 15) * (2.0f / 512.0f), &sn, &cs);
;     const cf w = cf{cs, sn}; cf wp = cf{1.f, 0.f};
; #pragma unroll
;     for (int p = 0; p < 32; ++p) { pb[17 * p] = cmul(v[BR32[p]], wp); wp = cmul(wp, w); }
	v_pk_add_f32 v[6:7], v[6:7], v[12:13] neg_lo:[0,1] neg_hi:[0,1]
	v_mov_b32_e32 v94, v6
	v_mov_b32_e32 v95, v7
	v_pk_add_f32 v[12:13], v[104:105], v[68:69] neg_lo:[0,1] neg_hi:[0,1]
	v_pk_add_f32 v[6:7], v[104:105], v[68:69]
	v_mov_b32_e32 v104, v12
	v_mov_b32_e32 v105, v13
	v_pk_add_f32 v[12:13], v[14:15], v[98:99]
	v_pk_add_f32 v[14:15], v[14:15], v[98:99] neg_lo:[0,1] neg_hi:[0,1]
	v_mov_b32_e32 v98, v14
	v_mov_b32_e32 v99, v15
	v_pk_add_f32 v[68:69], v[116:117], v[100:101] neg_lo:[0,1] neg_hi:[0,1]
	v_pk_add_f32 v[14:15], v[116:117], v[100:101]
	v_mov_b32_e32 v116, v68
	v_mov_b32_e32 v117, v69
	v_pk_add_f32 v[68:69], v[16:17], v[76:77]
	v_pk_add_f32 v[16:17], v[16:17], v[76:77] neg_lo:[0,1] neg_hi:[0,1]
	v_mov_b32_e32 v100, v16
	v_mov_b32_e32 v101, v17
	v_pk_add_f32 v[16:17], v[114:115], v[74:75]
	v_pk_add_f32 v[74:75], v[114:115], v[74:75] neg_lo:[0,1] neg_hi:[0,1]
	v_mov_b32_e32 v114, v74
	v_mov_b32_e32 v115, v75
	v_pk_add_f32 v[74:75], v[70:71], v[84:85]
	v_pk_add_f32 v[70:71], v[70:71], v[84:85] neg_lo:[0,1] neg_hi:[0,1]
	v_mov_b32_e32 v84, v70
	v_mov_b32_e32 v85, v71
	v_pk_add_f32 v[76:77], v[108:109], v[102:103] neg_lo:[0,1] neg_hi:[0,1]
	v_pk_add_f32 v[70:71], v[108:109], v[102:103]
	v_mov_b32_e32 v108, v76
	v_mov_b32_e32 v109, v77
	v_pk_add_f32 v[76:77], v[72:73], v[78:79]
	v_pk_add_f32 v[72:73], v[72:73], v[78:79] neg_lo:[0,1] neg_hi:[0,1]
	v_mov_b32_e32 v102, v72
	v_mov_b32_e32 v103, v73
	v_pk_add_f32 v[78:79], v[106:107], v[86:87] neg_lo:[0,1] neg_hi:[0,1]
	v_pk_add_f32 v[72:73], v[106:107], v[86:87]
	v_mov_b32_e32 v106, v78
	v_mov_b32_e32 v107, v79
	v_pk_add_f32 v[78:79], v[80:81], v[88:89]
	v_pk_add_f32 v[80:81], v[80:81], v[88:89] neg_lo:[0,1] neg_hi:[0,1]
	v_mov_b32_e32 v88, v80
	v_mov_b32_e32 v89, v81
	v_pk_add_f32 v[86:87], v[118:119], v[92:93] neg_lo:[0,1] neg_hi:[0,1]
	v_pk_add_f32 v[80:81], v[118:119], v[92:93]
	v_mov_b32_e32 v118, v86
	v_mov_b32_e32 v119, v87
	v_pk_mul_f32 v[92:93], v[82:83], v[66:67] op_sel:[1,1] op_sel_hi:[1,0] neg_lo:[1,0]
	v_pk_fma_f32 v[82:83], v[82:83], v[66:67], v[92:93] op_sel_hi:[0,1,1]
	s_nop 0
	v_sin_f32_e32 v87, v3
	v_cos_f32_e32 v86, v3
	v_pk_mul_f32 v[92:93], v[66:67], v[86:87] op_sel:[1,1] op_sel_hi:[1,0] neg_lo:[1,0]
	v_pk_fma_f32 v[120:121], v[66:67], v[86:87], v[92:93] op_sel_hi:[0,1,1]
	v_pk_mul_f32 v[92:93], v[68:69], v[120:121] op_sel:[1,1] op_sel_hi:[1,0] neg_lo:[1,0]
	v_pk_fma_f32 v[68:69], v[68:69], v[120:121], v[92:93] op_sel_hi:[0,1,1]
	ds_write2_b64 v2, v[82:83], v[68:69] offset1:17
	v_pk_mul_f32 v[68:69], v[120:121], v[86:87] op_sel:[1,1] op_sel_hi:[1,0] neg_lo:[1,0]
	v_pk_fma_f32 v[82:83], v[120:121], v[86:87], v[68:69] op_sel_hi:[0,1,1]
	v_pk_mul_f32 v[68:69], v[18:19], v[82:83] op_sel:[1,1] op_sel_hi:[1,0] neg_lo:[1,0]
	v_pk_fma_f32 v[18:19], v[18:19], v[82:83], v[68:69] op_sel_hi:[0,1,1]
	s_nop 0
	v_pk_mul_f32 v[68:69], v[82:83], v[86:87] op_sel:[1,1] op_sel_hi:[1,0] neg_lo:[1,0]
	v_pk_fma_f32 v[82:83], v[82:83], v[86:87], v[68:69] op_sel_hi:[0,1,1]
	v_pk_mul_f32 v[92:93], v[76:77], v[82:83] op_sel:[1,1] op_sel_hi:[1,0] neg_lo:[1,0]
	v_pk_fma_f32 v[68:69], v[76:77], v[82:83], v[92:93] op_sel_hi:[0,1,1]
	ds_write2_b64 v2, v[18:19], v[68:69] offset0:34 offset1:51
	v_pk_mul_f32 v[18:19], v[82:83], v[86:87] op_sel:[1,1] op_sel_hi:[1,0] neg_lo:[1,0]
	v_pk_fma_f32 v[68:69], v[82:83], v[86:87], v[18:19] op_sel_hi:[0,1,1]
	v_pk_mul_f32 v[18:19], v[8:9], v[68:69] op_sel:[1,1] op_sel_hi:[1,0] neg_lo:[1,0]
	v_pk_fma_f32 v[8:9], v[8:9], v[68:69], v[18:19] op_sel_hi:[0,1,1]
	s_nop 0
	v_pk_mul_f32 v[18:19], v[68:69], v[86:87] op_sel:[1,1] op_sel_hi:[1,0] neg_lo:[1,0]
	v_pk_fma_f32 v[68:69], v[68:69], v[86:87], v[18:19] op_sel_hi:[0,1,1]
	v_pk_mul_f32 v[76:77], v[74:75], v[68:69] op_sel:[1,1] op_sel_hi:[1,0] neg_lo:[1,0]
	v_pk_fma_f32 v[18:19], v[74:75], v[68:69], v[76:77] op_sel_hi:[0,1,1]
	ds_write2_b64 v2, v[8:9], v[18:19] offset0:68 offset1:85
	v_pk_mul_f32 v[8:9], v[68:69], v[86:87] op_sel:[1,1] op_sel_hi:[1,0] neg_lo:[1,0]
	v_pk_fma_f32 v[18:19], v[68:69], v[86:87], v[8:9] op_sel_hi:[0,1,1]
	v_pk_mul_f32 v[68:69], v[12:13], v[18:19] op_sel:[1,1] op_sel_hi:[1,0] neg_lo:[1,0]
	v_pk_fma_f32 v[8:9], v[12:13], v[18:19], v[68:69] op_sel_hi:[0,1,1]
	v_pk_mul_f32 v[12:13], v[18:19], v[86:87] op_sel:[1,1] op_sel_hi:[1,0] neg_lo:[1,0]
	v_pk_fma_f32 v[18:19], v[18:19], v[86:87], v[12:13] op_sel_hi:[0,1,1]
	v_pk_mul_f32 v[68:69], v[78:79], v[18:19] op_sel:[1,1] op_sel_hi:[1,0] neg_lo:[1,0]
	v_pk_fma_f32 v[12:13], v[78:79], v[18:19], v[68:69] op_sel_hi:[0,1,1]
	ds_write2_b64 v2, v[8:9], v[12:13] offset0:102 offset1:119
	v_pk_mul_f32 v[8:9], v[18:19], v[86:87] op_sel:[1,1] op_sel_hi:[1,0] neg_lo:[1,0]
	v_pk_fma_f32 v[12:13], v[18:19], v[86:87], v[8:9] op_sel_hi:[0,1,1]
	v_pk_mul_f32 v[18:19], v[10:11], v[12:13] op_sel:[1,1] op_sel_hi:[1,0] neg_lo:[1,0]
	v_pk_fma_f32 v[8:9], v[10:11], v[12:13], v[18:19] op_sel_hi:[0,1,1]
	v_pk_mul_f32 v[10:11], v[12:13], v[86:87] op_sel:[1,1] op_sel_hi:[1,0] neg_lo:[1,0]
	v_pk_fma_f32 v[12:13], v[12:13], v[86:87], v[10:11] op_sel_hi:[0,1,1]
	v_pk_mul_f32 v[18:19], v[16:17], v[12:13] op_sel:[1,1] op_sel_hi:[1,0] neg_lo:[1,0]
	v_pk_fma_f32 v[10:11], v[16:17], v[12:13], v[18:19] op_sel_hi:[0,1,1]
	ds_write2_b64 v2, v[8:9], v[10:11] offset0:136 offset1:153
	v_pk_mul_f32 v[8:9], v[12:13], v[86:87] op_sel:[1,1] op_sel_hi:[1,0] neg_lo:[1,0]
	v_pk_fma_f32 v[10:11], v[12:13], v[86:87], v[8:9] op_sel_hi:[0,1,1]
	v_pk_mul_f32 v[8:9], v[6:7], v[10:11] op_sel:[1,1] op_sel_hi:[1,0] neg_lo:[1,0]
	v_pk_fma_f32 v[6:7], v[6:7], v[10:11], v[8:9] op_sel_hi:[0,1,1]
	s_nop 0
	v_pk_mul_f32 v[8:9], v[10:11], v[86:87] op_sel:[1,1] op_sel_hi:[1,0] neg_lo:[1,0]
; #define SINCOSPI(x, s, c) do { const float hx_ = 0.5f * (x); *(s) = __builtin_amdgcn_sinf(hx_); *(c) = __builtin_amdgcn_cosf(hx_); } while (0)
; DEV void fft_f2(LAS cf* buf, int t8) {
;     ...
;     float sn, cs; SINCOSPI(-(float)(t8 & 15) * (2.0f / 512.0f), &sn, &cs);
;     const cf w = cf{cs, sn}; cf wp = cf{1.f, 0.f};
; #pragma unroll
;     for (int p = 0; p < 32; ++p) { pb[17 * p] = cmul(v[BR32[p]], wp); wp = cmul(wp, w); }
	v_pk_fma_f32 v[10:11], v[10:11], v[86:87], v[8:9] op_sel_hi:[0,1,1]
	v_pk_mul_f32 v[12:13], v[72:73], v[10:11] op_sel:[1,1] op_sel_hi:[1,0] neg_lo:[1,0]
	v_pk_fma_f32 v[8:9], v[72:73], v[10:11], v[12:13] op_sel_hi:[0,1,1]
	ds_write2_b64 v2, v[6:7], v[8:9] offset0:170 offset1:187
	v_pk_mul_f32 v[6:7], v[10:11], v[86:87] op_sel:[1,1] op_sel_hi:[1,0] neg_lo:[1,0]
	v_pk_fma_f32 v[8:9], v[10:11], v[86:87], v[6:7] op_sel_hi:[0,1,1]
	v_pk_mul_f32 v[6:7], v[4:5], v[8:9] op_sel:[1,1] op_sel_hi:[1,0] neg_lo:[1,0]
	v_pk_fma_f32 v[4:5], v[4:5], v[8:9], v[6:7] op_sel_hi:[0,1,1]
	s_nop 0
	v_pk_mul_f32 v[6:7], v[8:9], v[86:87] op_sel:[1,1] op_sel_hi:[1,0] neg_lo:[1,0]
	v_pk_fma_f32 v[8:9], v[8:9], v[86:87], v[6:7] op_sel_hi:[0,1,1]
	v_pk_mul_f32 v[10:11], v[70:71], v[8:9] op_sel:[1,1] op_sel_hi:[1,0] neg_lo:[1,0]
	v_pk_fma_f32 v[6:7], v[70:71], v[8:9], v[10:11] op_sel_hi:[0,1,1]
	ds_write2_b64 v2, v[4:5], v[6:7] offset0:204 offset1:221
	v_pk_mul_f32 v[4:5], v[8:9], v[86:87] op_sel:[1,1] op_sel_hi:[1,0] neg_lo:[1,0]
	v_pk_fma_f32 v[6:7], v[8:9], v[86:87], v[4:5] op_sel_hi:[0,1,1]
	v_pk_mul_f32 v[8:9], v[14:15], v[6:7] op_sel:[1,1] op_sel_hi:[1,0] neg_lo:[1,0]
	v_pk_fma_f32 v[4:5], v[14:15], v[6:7], v[8:9] op_sel_hi:[0,1,1]
	s_nop 0
	v_pk_mul_f32 v[8:9], v[6:7], v[86:87] op_sel:[1,1] op_sel_hi:[1,0] neg_lo:[1,0]
	v_pk_fma_f32 v[6:7], v[6:7], v[86:87], v[8:9] op_sel_hi:[0,1,1]
	v_pk_mul_f32 v[10:11], v[80:81], v[6:7] op_sel:[1,1] op_sel_hi:[1,0] neg_lo:[1,0]
	v_pk_fma_f32 v[8:9], v[80:81], v[6:7], v[10:11] op_sel_hi:[0,1,1]
	ds_write2_b64 v2, v[4:5], v[8:9] offset0:238 offset1:255
	v_pk_mul_f32 v[2:3], v[6:7], v[86:87] op_sel:[1,1] op_sel_hi:[1,0] neg_lo:[1,0]
	v_pk_fma_f32 v[4:5], v[6:7], v[86:87], v[2:3] op_sel_hi:[0,1,1]
	v_pk_mul_f32 v[6:7], v[110:111], v[4:5] op_sel:[1,1] op_sel_hi:[1,0] neg_lo:[1,0]
	v_pk_fma_f32 v[2:3], v[110:111], v[4:5], v[6:7] op_sel_hi:[0,1,1]
	s_nop 0
	v_pk_mul_f32 v[6:7], v[4:5], v[86:87] op_sel:[1,1] op_sel_hi:[1,0] neg_lo:[1,0]
	v_pk_fma_f32 v[4:5], v[4:5], v[86:87], v[6:7] op_sel_hi:[0,1,1]
	v_pk_mul_f32 v[8:9], v[100:101], v[4:5] op_sel:[1,1] op_sel_hi:[1,0] neg_lo:[1,0]
	v_pk_fma_f32 v[6:7], v[100:101], v[4:5], v[8:9] op_sel_hi:[0,1,1]
	ds_write2_b64 v0, v[2:3], v[6:7] offset0:16 offset1:33
	v_pk_mul_f32 v[2:3], v[4:5], v[86:87] op_sel:[1,1] op_sel_hi:[1,0] neg_lo:[1,0]
	v_pk_fma_f32 v[4:5], v[4:5], v[86:87], v[2:3] op_sel_hi:[0,1,1]
	v_pk_mul_f32 v[6:7], v[94:95], v[4:5] op_sel:[1,1] op_sel_hi:[1,0] neg_lo:[1,0]
	v_pk_fma_f32 v[2:3], v[94:95], v[4:5], v[6:7] op_sel_hi:[0,1,1]
	s_nop 0
	v_pk_mul_f32 v[6:7], v[4:5], v[86:87] op_sel:[1,1] op_sel_hi:[1,0] neg_lo:[1,0]
	v_pk_fma_f32 v[4:5], v[4:5], v[86:87], v[6:7] op_sel_hi:[0,1,1]
	v_pk_mul_f32 v[8:9], v[102:103], v[4:5] op_sel:[1,1] op_sel_hi:[1,0] neg_lo:[1,0]
	v_pk_fma_f32 v[6:7], v[102:103], v[4:5], v[8:9] op_sel_hi:[0,1,1]
	ds_write2_b64 v0, v[2:3], v[6:7] offset0:50 offset1:67
	v_pk_mul_f32 v[2:3], v[4:5], v[86:87] op_sel:[1,1] op_sel_hi:[1,0] neg_lo:[1,0]
	v_pk_fma_f32 v[4:5], v[4:5], v[86:87], v[2:3] op_sel_hi:[0,1,1]
	v_pk_mul_f32 v[6:7], v[90:91], v[4:5] op_sel:[1,1] op_sel_hi:[1,0] neg_lo:[1,0]
	v_pk_fma_f32 v[2:3], v[90:91], v[4:5], v[6:7] op_sel_hi:[0,1,1]
	s_nop 0
	v_pk_mul_f32 v[6:7], v[4:5], v[86:87] op_sel:[1,1] op_sel_hi:[1,0] neg_lo:[1,0]
	v_pk_fma_f32 v[4:5], v[4:5], v[86:87], v[6:7] op_sel_hi:[0,1,1]
	v_pk_mul_f32 v[8:9], v[84:85], v[4:5] op_sel:[1,1] op_sel_hi:[1,0] neg_lo:[1,0]
	v_pk_fma_f32 v[6:7], v[84:85], v[4:5], v[8:9] op_sel_hi:[0,1,1]
	ds_write2_b64 v0, v[2:3], v[6:7] offset0:84 offset1:101
	v_pk_mul_f32 v[2:3], v[4:5], v[86:87] op_sel:[1,1] op_sel_hi:[1,0] neg_lo:[1,0]
	v_pk_fma_f32 v[4:5], v[4:5], v[86:87], v[2:3] op_sel_hi:[0,1,1]
	v_pk_mul_f32 v[6:7], v[98:99], v[4:5] op_sel:[1,1] op_sel_hi:[1,0] neg_lo:[1,0]
	v_pk_fma_f32 v[2:3], v[98:99], v[4:5], v[6:7] op_sel_hi:[0,1,1]
	s_nop 0
	v_pk_mul_f32 v[6:7], v[4:5], v[86:87] op_sel:[1,1] op_sel_hi:[1,0] neg_lo:[1,0]
	v_pk_fma_f32 v[4:5], v[4:5], v[86:87], v[6:7] op_sel_hi:[0,1,1]
	v_pk_mul_f32 v[8:9], v[88:89], v[4:5] op_sel:[1,1] op_sel_hi:[1,0] neg_lo:[1,0]
	v_pk_fma_f32 v[6:7], v[88:89], v[4:5], v[8:9] op_sel_hi:[0,1,1]
	ds_write2_b64 v0, v[2:3], v[6:7] offset0:118 offset1:135
	v_pk_mul_f32 v[2:3], v[4:5], v[86:87] op_sel:[1,1] op_sel_hi:[1,0] neg_lo:[1,0]
	v_pk_fma_f32 v[4:5], v[4:5], v[86:87], v[2:3] op_sel_hi:[0,1,1]
	v_pk_mul_f32 v[6:7], v[96:97], v[4:5] op_sel:[1,1] op_sel_hi:[1,0] neg_lo:[1,0]
	v_pk_fma_f32 v[2:3], v[96:97], v[4:5], v[6:7] op_sel_hi:[0,1,1]
	s_nop 0
	v_pk_mul_f32 v[6:7], v[4:5], v[86:87] op_sel:[1,1] op_sel_hi:[1,0] neg_lo:[1,0]
	v_pk_fma_f32 v[4:5], v[4:5], v[86:87], v[6:7] op_sel_hi:[0,1,1]
	v_pk_mul_f32 v[8:9], v[114:115], v[4:5] op_sel:[1,1] op_sel_hi:[1,0] neg_lo:[1,0]
	v_pk_fma_f32 v[6:7], v[114:115], v[4:5], v[8:9] op_sel_hi:[0,1,1]
	ds_write2_b64 v0, v[2:3], v[6:7] offset0:152 offset1:169
	v_pk_mul_f32 v[2:3], v[4:5], v[86:87] op_sel:[1,1] op_sel_hi:[1,0] neg_lo:[1,0]
	v_pk_fma_f32 v[4:5], v[4:5], v[86:87], v[2:3] op_sel_hi:[0,1,1]
	v_pk_mul_f32 v[6:7], v[104:105], v[4:5] op_sel:[1,1] op_sel_hi:[1,0] neg_lo:[1,0]
	v_pk_fma_f32 v[2:3], v[104:105], v[4:5], v[6:7] op_sel_hi:[0,1,1]
	s_nop 0
	v_pk_mul_f32 v[6:7], v[4:5], v[86:87] op_sel:[1,1] op_sel_hi:[1,0] neg_lo:[1,0]
	v_pk_fma_f32 v[4:5], v[4:5], v[86:87], v[6:7] op_sel_hi:[0,1,1]
	v_pk_mul_f32 v[8:9], v[106:107], v[4:5] op_sel:[1,1] op_sel_hi:[1,0] neg_lo:[1,0]
	v_pk_fma_f32 v[6:7], v[106:107], v[4:5], v[8:9] op_sel_hi:[0,1,1]
	ds_write2_b64 v0, v[2:3], v[6:7] offset0:186 offset1:203
	v_pk_mul_f32 v[2:3], v[4:5], v[86:87] op_sel:[1,1] op_sel_hi:[1,0] neg_lo:[1,0]
	v_pk_fma_f32 v[4:5], v[4:5], v[86:87], v[2:3] op_sel_hi:[0,1,1]
	v_pk_mul_f32 v[6:7], v[112:113], v[4:5] op_sel:[1,1] op_sel_hi:[1,0] neg_lo:[1,0]
	v_pk_fma_f32 v[2:3], v[112:113], v[4:5], v[6:7] op_sel_hi:[0,1,1]
	s_nop 0
	v_pk_mul_f32 v[6:7], v[4:5], v[86:87] op_sel:[1,1] op_sel_hi:[1,0] neg_lo:[1,0]
	v_pk_fma_f32 v[4:5], v[4:5], v[86:87], v[6:7] op_sel_hi:[0,1,1]
	v_pk_mul_f32 v[8:9], v[108:109], v[4:5] op_sel:[1,1] op_sel_hi:[1,0] neg_lo:[1,0]
	v_pk_fma_f32 v[6:7], v[108:109], v[4:5], v[8:9] op_sel_hi:[0,1,1]
	ds_write2_b64 v0, v[2:3], v[6:7] offset0:220 offset1:237
	v_pk_mul_f32 v[2:3], v[4:5], v[86:87] op_sel:[1,1] op_sel_hi:[1,0] neg_lo:[1,0]
	v_pk_fma_f32 v[4:5], v[4:5], v[86:87], v[2:3] op_sel_hi:[0,1,1]
	v_pk_mul_f32 v[6:7], v[116:117], v[4:5] op_sel:[1,1] op_sel_hi:[1,0] neg_lo:[1,0]
	v_pk_fma_f32 v[2:3], v[116:117], v[4:5], v[6:7] op_sel_hi:[0,1,1]
	s_nop 0
	v_pk_mul_f32 v[6:7], v[4:5], v[86:87] op_sel:[1,1] op_sel_hi:[1,0] neg_lo:[1,0]
	v_pk_fma_f32 v[4:5], v[4:5], v[86:87], v[6:7] op_sel_hi:[0,1,1]
	v_pk_mul_f32 v[6:7], v[118:119], v[4:5] op_sel:[1,1] op_sel_hi:[1,0] neg_lo:[1,0]
	v_pk_fma_f32 v[4:5], v[118:119], v[4:5], v[6:7] op_sel_hi:[0,1,1]
	ds_write2_b64 v1, v[2:3], v[4:5] offset0:126 offset1:143
	s_waitcnt lgkmcnt(0)
	s_barrier
; template <int R, bool INV> DEV void dft_regs(cf (&v)[R]) {
; #pragma unroll
;     for (int s = R; s >= 2; s >>= 1) {
;         const int h = s >> 1;
; #pragma unroll
;         for (int b = 0; b < R; b += s) {
; #pragma unroll
;             for (int k = 0; k < h; ++k) {
;                 const cf a = v[b + k], c = v[b + k + h];
;                 v[b + k] = a + c;
;                 const cf d = a - c;
;                 const int m = k * (32 / s);
;                 const float wr = tw_cos(m), wi = INV ? tw_sin(m) : -tw_sin(m);
;                 v[b + k + h] = cf{d.x * wr - d.y * wi, d.x * wi + d.y * wr};
;             }
;         }
;     }
; }
; DEV void fft_midx2(LAS cf* buf0, LAS cf* buf1, const unsigned* Kp, int blk) {
;     ...
;     for (int q = 0; q < 16; ++q) { v[q] = p0[q]; u[q] = p1[q]; }
;     dft_regs<16, false>(v); dft_regs<16, false>(u);
	ds_read2_b64 v[68:71], v161 offset1:1
	ds_read2_b64 v[8:11], v162 offset1:1
	ds_read2_b64 v[72:75], v161 offset0:2 offset1:3
	ds_read2_b64 v[12:15], v162 offset0:2 offset1:3
	ds_read2_b64 v[76:79], v161 offset0:4 offset1:5
	ds_read2_b64 v[0:3], v162 offset0:4 offset1:5
	ds_read2_b64 v[80:83], v161 offset0:6 offset1:7
	ds_read2_b64 v[4:7], v162 offset0:6 offset1:7
	ds_read2_b64 v[84:87], v161 offset0:8 offset1:9
	ds_read2_b64 v[100:103], v162 offset0:8 offset1:9
	ds_read2_b64 v[88:91], v161 offset0:10 offset1:11
	ds_read2_b64 v[104:107], v162 offset0:10 offset1:11
	ds_read2_b64 v[92:95], v161 offset0:12 offset1:13
	ds_read2_b64 v[16:19], v162 offset0:12 offset1:13
	ds_read2_b64 v[96:99], v161 offset0:14 offset1:15
	ds_read2_b64 v[108:111], v162 offset0:14 offset1:15
	s_waitcnt lgkmcnt(7)
	v_pk_add_f32 v[112:113], v[68:69], v[84:85]
	v_pk_add_f32 v[68:69], v[68:69], v[84:85] neg_lo:[0,1] neg_hi:[0,1]
	v_mov_b32_e32 v114, v68
	v_mov_b32_e32 v115, v69
	v_pk_add_f32 v[68:69], v[70:71], v[86:87]
	v_pk_add_f32 v[70:71], v[70:71], v[86:87] neg_lo:[0,1] neg_hi:[0,1]
	v_pk_mul_f32 v[84:85], v[70:71], s[84:85] op_sel_hi:[1,0]
	v_pk_fma_f32 v[86:87], v[70:71], s[16:17], v[84:85] op_sel:[0,0,1] op_sel_hi:[1,0,0]
	v_pk_fma_f32 v[70:71], v[70:71], s[16:17], v[84:85] op_sel:[0,0,1] op_sel_hi:[1,0,0] neg_lo:[0,0,1] neg_hi:[0,0,1]
	v_mov_b32_e32 v87, v71
	s_waitcnt lgkmcnt(5)
	v_pk_add_f32 v[70:71], v[72:73], v[88:89]
	v_pk_add_f32 v[72:73], v[72:73], v[88:89] neg_lo:[0,1] neg_hi:[0,1]
	v_pk_mul_f32 v[84:85], v[72:73], s[18:19] op_sel_hi:[1,0]
	v_pk_fma_f32 v[88:89], v[72:73], s[18:19], v[84:85] op_sel:[0,0,1] op_sel_hi:[1,0,0]
	v_pk_fma_f32 v[72:73], v[72:73], s[18:19], v[84:85] op_sel_hi:[1,0,0] neg_lo:[0,0,1] neg_hi:[0,0,1]
	v_pk_add_f32 v[84:85], v[74:75], v[90:91]
	v_pk_add_f32 v[74:75], v[74:75], v[90:91] neg_lo:[0,1] neg_hi:[0,1]
	v_mov_b32_e32 v89, v73
	v_pk_mul_f32 v[90:91], v[74:75], s[16:17] op_sel_hi:[1,0]
	v_pk_fma_f32 v[116:117], v[74:75], s[84:85], v[90:91] op_sel:[0,0,1] op_sel_hi:[1,0,0]
	v_pk_fma_f32 v[74:75], v[74:75], s[84:85], v[90:91] op_sel:[0,0,1] op_sel_hi:[1,0,0] neg_lo:[0,0,1] neg_hi:[0,0,1]
	v_mov_b32_e32 v117, v75
	s_waitcnt lgkmcnt(3)
	v_pk_add_f32 v[74:75], v[76:77], v[92:93]
	v_pk_add_f32 v[76:77], v[76:77], v[92:93] neg_lo:[0,1] neg_hi:[0,1]
	v_pk_add_f32 v[90:91], v[76:77], 0 op_sel:[1,0] op_sel_hi:[0,0] neg_hi:[1,0]
	v_pk_add_f32 v[76:77], v[78:79], v[94:95]
	v_pk_add_f32 v[78:79], v[78:79], v[94:95] neg_lo:[0,1] neg_hi:[0,1]
	s_waitcnt lgkmcnt(1)
	v_pk_add_f32 v[94:95], v[82:83], v[98:99]
	v_pk_mul_f32 v[92:93], v[78:79], s[84:85] op_sel_hi:[0,1]
	v_pk_add_f32 v[82:83], v[82:83], v[98:99] neg_lo:[0,1] neg_hi:[0,1]
	v_pk_fma_f32 v[78:79], v[78:79], s[30:31], v[92:93] op_sel:[1,0,0] neg_lo:[0,0,1] neg_hi:[0,0,1]
	v_pk_add_f32 v[92:93], v[80:81], v[96:97]
	v_pk_add_f32 v[80:81], v[80:81], v[96:97] neg_lo:[0,1] neg_hi:[0,1]
	v_pk_mul_f32 v[96:97], v[82:83], s[24:25] op_sel_hi:[0,1]
	v_pk_fma_f32 v[82:83], v[82:83], s[34:35], v[96:97] op_sel:[1,0,0] neg_lo:[0,0,1] neg_hi:[0,0,1]
	v_pk_add_f32 v[96:97], v[112:113], v[74:75]
	v_pk_add_f32 v[74:75], v[112:113], v[74:75] neg_lo:[0,1] neg_hi:[0,1]
	v_mul_f32_e32 v72, 0x3f3504f3, v80
	v_pk_fma_f32 v[80:81], v[80:81], s[28:29], v[72:73] op_sel:[1,0,0] op_sel_hi:[1,1,0] neg_lo:[0,0,1] neg_hi:[0,0,1]
	v_mov_b32_e32 v112, v74
	v_mov_b32_e32 v113, v75
	v_pk_add_f32 v[72:73], v[88:89], v[80:81]
	v_pk_add_f32 v[74:75], v[68:69], v[76:77]
	v_pk_add_f32 v[68:69], v[68:69], v[76:77] neg_lo:[0,1] neg_hi:[0,1]
	v_pk_mul_f32 v[76:77], v[68:69], s[18:19] op_sel_hi:[1,0]
	v_pk_fma_f32 v[98:99], v[68:69], s[18:19], v[76:77] op_sel:[0,0,1] op_sel_hi:[1,0,0]
	v_pk_fma_f32 v[68:69], v[68:69], s[18:19], v[76:77] op_sel_hi:[1,0,0] neg_lo:[0,0,1] neg_hi:[0,0,1]
	v_pk_add_f32 v[76:77], v[70:71], v[92:93]
	v_pk_add_f32 v[70:71], v[70:71], v[92:93] neg_lo:[0,1] neg_hi:[0,1]
	v_mov_b32_e32 v99, v69
	v_pk_add_f32 v[92:93], v[70:71], 0 op_sel:[1,0] op_sel_hi:[0,0] neg_hi:[1,0]
	v_pk_add_f32 v[70:71], v[84:85], v[94:95]
	v_pk_add_f32 v[84:85], v[84:85], v[94:95] neg_lo:[0,1] neg_hi:[0,1]
	v_pk_add_f32 v[94:95], v[114:115], v[90:91]
	v_pk_add_f32 v[90:91], v[114:115], v[90:91] neg_lo:[0,1] neg_hi:[0,1]
	v_mul_f32_e32 v68, 0x3f3504f3, v84
	v_pk_fma_f32 v[84:85], v[84:85], s[28:29], v[68:69] op_sel:[1,0,0] op_sel_hi:[1,1,0] neg_lo:[0,0,1] neg_hi:[0,0,1]
	v_mov_b32_e32 v118, v90
	v_mov_b32_e32 v119, v91
	v_pk_add_f32 v[90:91], v[86:87], v[78:79]
	v_pk_add_f32 v[78:79], v[86:87], v[78:79] neg_lo:[0,1] neg_hi:[0,1]
	v_pk_mul_f32 v[86:87], v[78:79], s[18:19] op_sel_hi:[1,0]
	v_pk_fma_f32 v[114:115], v[78:79], s[18:19], v[86:87] op_sel:[0,0,1] op_sel_hi:[1,0,0]
	v_pk_fma_f32 v[78:79], v[78:79], s[18:19], v[86:87] op_sel_hi:[1,0,0] neg_lo:[0,0,1] neg_hi:[0,0,1]
	v_mov_b32_e32 v115, v79
	v_pk_add_f32 v[78:79], v[88:89], v[80:81] neg_lo:[0,1] neg_hi:[0,1]
	v_pk_add_f32 v[88:89], v[96:97], v[76:77]
	v_pk_add_f32 v[76:77], v[96:97], v[76:77] neg_lo:[0,1] neg_hi:[0,1]
	v_pk_add_f32 v[80:81], v[78:79], 0 op_sel:[1,0] op_sel_hi:[0,0] neg_hi:[1,0]
	v_mov_b32_e32 v96, v76
	v_mov_b32_e32 v97, v77
	v_pk_add_f32 v[76:77], v[74:75], v[70:71]
	v_pk_add_f32 v[70:71], v[74:75], v[70:71] neg_lo:[0,1] neg_hi:[0,1]
	v_pk_add_f32 v[78:79], v[116:117], v[82:83]
	v_pk_add_f32 v[74:75], v[70:71], 0 op_sel:[1,0] op_sel_hi:[0,0] neg_hi:[1,0]
	v_pk_add_f32 v[82:83], v[116:117], v[82:83] neg_lo:[0,1] neg_hi:[0,1]
	v_pk_add_f32 v[70:71], v[112:113], v[92:93] neg_lo:[0,1] neg_hi:[0,1]
	v_pk_add_f32 v[116:117], v[112:113], v[92:93]
	v_mul_f32_e32 v68, 0x3f3504f3, v82
	v_mov_b32_e32 v92, v70
	v_mov_b32_e32 v93, v71
; template <int R, bool INV> DEV void dft_regs(cf (&v)[R]) {
; #pragma unroll
;     for (int s = R; s >= 2; s >>= 1) {
;         const int h = s >> 1;
; #pragma unroll
;         for (int b = 0; b < R; b += s) {
; #pragma unroll
;             for (int k = 0; k < h; ++k) {
;                 const cf a = v[b + k], c = v[b + k + h];
;                 v[b + k] = a + c;
;                 const cf d = a - c;
;                 const int m = k * (32 / s);
;                 const float wr = tw_cos(m), wi = INV ? tw_sin(m) : -tw_sin(m);
;                 v[b + k + h] = cf{d.x * wr - d.y * wi, d.x * wi + d.y * wr};
;             }
;         }
;     }
; }
; DEV void fft_midx2(LAS cf* buf0, LAS cf* buf1, const unsigned* Kp, int blk) {
;     ...
;     dft_regs<16, false>(v); dft_regs<16, false>(u);
	v_pk_fma_f32 v[82:83], v[82:83], s[28:29], v[68:69] op_sel:[1,0,0] op_sel_hi:[1,1,0] neg_lo:[0,0,1] neg_hi:[0,0,1]
	v_pk_add_f32 v[70:71], v[98:99], v[84:85] neg_lo:[0,1] neg_hi:[0,1]
	v_pk_add_f32 v[68:69], v[98:99], v[84:85]
	v_pk_add_f32 v[98:99], v[70:71], 0 op_sel:[1,0] op_sel_hi:[0,0] neg_hi:[1,0]
	v_pk_add_f32 v[112:113], v[94:95], v[72:73]
	v_pk_add_f32 v[70:71], v[94:95], v[72:73] neg_lo:[0,1] neg_hi:[0,1]
	v_pk_add_f32 v[122:123], v[118:119], v[80:81]
	v_pk_add_f32 v[124:125], v[114:115], v[82:83]
	v_mov_b32_e32 v120, v70
	v_mov_b32_e32 v121, v71
	v_pk_add_f32 v[72:73], v[90:91], v[78:79]
	v_pk_add_f32 v[70:71], v[90:91], v[78:79] neg_lo:[0,1] neg_hi:[0,1]
	v_pk_add_f32 v[86:87], v[88:89], v[76:77]
	v_pk_add_f32 v[78:79], v[70:71], 0 op_sel:[1,0] op_sel_hi:[0,0] neg_hi:[1,0]
	v_pk_add_f32 v[94:95], v[112:113], v[72:73]
	v_pk_add_f32 v[70:71], v[118:119], v[80:81] neg_lo:[0,1] neg_hi:[0,1]
	v_pk_add_f32 v[72:73], v[112:113], v[72:73] neg_lo:[0,1] neg_hi:[0,1]
	v_pk_add_f32 v[84:85], v[92:93], v[98:99]
	v_mov_b32_e32 v118, v70
	v_mov_b32_e32 v119, v71
	v_pk_add_f32 v[112:113], v[8:9], v[100:101]
	v_pk_add_f32 v[70:71], v[114:115], v[82:83] neg_lo:[0,1] neg_hi:[0,1]
	v_pk_add_f32 v[82:83], v[96:97], v[74:75]
	v_pk_add_f32 v[114:115], v[70:71], 0 op_sel:[1,0] op_sel_hi:[0,0] neg_hi:[1,0]
	v_pk_add_f32 v[74:75], v[96:97], v[74:75] neg_lo:[0,1] neg_hi:[0,1]
	v_pk_add_f32 v[70:71], v[88:89], v[76:77] neg_lo:[0,1] neg_hi:[0,1]
	v_pk_add_f32 v[88:89], v[116:117], v[68:69]
	v_pk_add_f32 v[68:69], v[116:117], v[68:69] neg_lo:[0,1] neg_hi:[0,1]
	v_mov_b32_e32 v76, v70
	v_mov_b32_e32 v77, v71
	v_mov_b32_e32 v70, v74
	v_mov_b32_e32 v71, v75
	v_mov_b32_e32 v74, v68
	v_mov_b32_e32 v75, v69
	v_pk_add_f32 v[80:81], v[92:93], v[98:99] neg_lo:[0,1] neg_hi:[0,1]
	v_pk_add_f32 v[8:9], v[8:9], v[100:101] neg_lo:[0,1] neg_hi:[0,1]
	v_mov_b32_e32 v68, v80
	v_mov_b32_e32 v69, v81
	v_mov_b32_e32 v80, v72
	v_mov_b32_e32 v81, v73
	v_pk_add_f32 v[90:91], v[120:121], v[78:79]
	v_pk_add_f32 v[78:79], v[120:121], v[78:79] neg_lo:[0,1] neg_hi:[0,1]
	v_mov_b32_e32 v72, v78
	v_mov_b32_e32 v73, v79
	v_pk_add_f32 v[92:93], v[122:123], v[124:125] neg_lo:[0,1] neg_hi:[0,1]
	v_pk_add_f32 v[96:97], v[122:123], v[124:125]
	v_mov_b32_e32 v78, v92
	v_mov_b32_e32 v79, v93
	v_pk_add_f32 v[98:99], v[118:119], v[114:115] neg_lo:[0,1] neg_hi:[0,1]
	v_pk_add_f32 v[92:93], v[118:119], v[114:115]
	v_mov_b32_e32 v114, v8
	v_mov_b32_e32 v115, v9
	v_pk_add_f32 v[8:9], v[10:11], v[102:103]
	v_pk_add_f32 v[10:11], v[10:11], v[102:103] neg_lo:[0,1] neg_hi:[0,1]
	v_pk_mul_f32 v[100:101], v[10:11], s[84:85] op_sel_hi:[1,0]
	v_pk_fma_f32 v[102:103], v[10:11], s[16:17], v[100:101] op_sel:[0,0,1] op_sel_hi:[1,0,0]
	v_pk_fma_f32 v[10:11], v[10:11], s[16:17], v[100:101] op_sel:[0,0,1] op_sel_hi:[1,0,0] neg_lo:[0,0,1] neg_hi:[0,0,1]
	v_mov_b32_e32 v103, v11
	v_pk_add_f32 v[10:11], v[12:13], v[104:105]
	v_pk_add_f32 v[12:13], v[12:13], v[104:105] neg_lo:[0,1] neg_hi:[0,1]
	v_pk_mul_f32 v[100:101], v[12:13], s[18:19] op_sel_hi:[1,0]
	v_pk_fma_f32 v[104:105], v[12:13], s[18:19], v[100:101] op_sel:[0,0,1] op_sel_hi:[1,0,0]
	v_pk_fma_f32 v[12:13], v[12:13], s[18:19], v[100:101] op_sel_hi:[1,0,0] neg_lo:[0,0,1] neg_hi:[0,0,1]
	v_mov_b32_e32 v105, v13
	v_pk_add_f32 v[12:13], v[14:15], v[106:107]
	v_pk_add_f32 v[14:15], v[14:15], v[106:107] neg_lo:[0,1] neg_hi:[0,1]
	v_pk_mul_f32 v[100:101], v[14:15], s[16:17] op_sel_hi:[1,0]
	v_pk_fma_f32 v[106:107], v[14:15], s[84:85], v[100:101] op_sel:[0,0,1] op_sel_hi:[1,0,0]
	v_pk_fma_f32 v[14:15], v[14:15], s[84:85], v[100:101] op_sel:[0,0,1] op_sel_hi:[1,0,0] neg_lo:[0,0,1] neg_hi:[0,0,1]
	v_mov_b32_e32 v107, v15
	v_pk_add_f32 v[14:15], v[0:1], v[16:17]
	v_pk_add_f32 v[0:1], v[0:1], v[16:17] neg_lo:[0,1] neg_hi:[0,1]
	v_pk_add_f32 v[16:17], v[0:1], 0 op_sel:[1,0] op_sel_hi:[0,0] neg_hi:[1,0]
	v_pk_add_f32 v[0:1], v[2:3], v[18:19]
	v_pk_add_f32 v[2:3], v[2:3], v[18:19] neg_lo:[0,1] neg_hi:[0,1]
	v_pk_mul_f32 v[18:19], v[2:3], s[84:85] op_sel_hi:[0,1]
	v_pk_fma_f32 v[2:3], v[2:3], s[30:31], v[18:19] op_sel:[1,0,0] neg_lo:[0,0,1] neg_hi:[0,0,1]
	s_waitcnt lgkmcnt(0)
	v_pk_add_f32 v[18:19], v[4:5], v[108:109]
	v_pk_add_f32 v[4:5], v[4:5], v[108:109] neg_lo:[0,1] neg_hi:[0,1]
	v_mul_f32_e32 v100, 0x3f3504f3, v4
	v_pk_fma_f32 v[4:5], v[4:5], s[28:29], v[100:101] op_sel:[1,0,0] op_sel_hi:[1,1,0] neg_lo:[0,0,1] neg_hi:[0,0,1]
	v_pk_add_f32 v[100:101], v[6:7], v[110:111]
	v_pk_add_f32 v[6:7], v[6:7], v[110:111] neg_lo:[0,1] neg_hi:[0,1]
	v_pk_mul_f32 v[108:109], v[6:7], s[24:25] op_sel_hi:[0,1]
	v_pk_fma_f32 v[6:7], v[6:7], s[34:35], v[108:109] op_sel:[1,0,0] neg_lo:[0,0,1] neg_hi:[0,0,1]
	v_pk_add_f32 v[108:109], v[112:113], v[14:15]
	v_pk_add_f32 v[14:15], v[112:113], v[14:15] neg_lo:[0,1] neg_hi:[0,1]
	v_mov_b32_e32 v112, v14
	v_mov_b32_e32 v113, v15
	v_pk_add_f32 v[14:15], v[8:9], v[0:1]
	v_pk_add_f32 v[0:1], v[8:9], v[0:1] neg_lo:[0,1] neg_hi:[0,1]
	v_pk_mul_f32 v[8:9], v[0:1], s[18:19] op_sel_hi:[1,0]
	v_pk_fma_f32 v[110:111], v[0:1], s[18:19], v[8:9] op_sel:[0,0,1] op_sel_hi:[1,0,0]
	v_pk_fma_f32 v[0:1], v[0:1], s[18:19], v[8:9] op_sel_hi:[1,0,0] neg_lo:[0,0,1] neg_hi:[0,0,1]
	v_pk_add_f32 v[8:9], v[10:11], v[18:19] neg_lo:[0,1] neg_hi:[0,1]
	v_mov_b32_e32 v111, v1
	v_pk_add_f32 v[0:1], v[10:11], v[18:19]
	v_pk_add_f32 v[10:11], v[8:9], 0 op_sel:[1,0] op_sel_hi:[0,0] neg_hi:[1,0]
	v_pk_add_f32 v[8:9], v[12:13], v[100:101]
	v_pk_add_f32 v[12:13], v[12:13], v[100:101] neg_lo:[0,1] neg_hi:[0,1]
	v_mul_f32_e32 v18, 0x3f3504f3, v12
	v_pk_fma_f32 v[12:13], v[12:13], s[28:29], v[18:19] op_sel:[1,0,0] op_sel_hi:[1,1,0] neg_lo:[0,0,1] neg_hi:[0,0,1]
; DEV cf kunpack(unsigned w) { return cf{U2F(w << 16), U2F(w & 0xffff0000u)}; }
; DEV void fft_midx2(LAS cf* buf0, LAS cf* buf1, const unsigned* Kp, int blk) {
;     ...
;     dft_regs<16, false>(v); dft_regs<16, false>(u);
;     cf w[16], x[16];
;     u32x4 kw[4];
; #pragma unroll
;     for (int j = 0; j < 4; ++j) kw[j] = *(const u32x4*)(Kp + base + 4 * j);
; #pragma unroll
;     for (int p = 0; p < 16; ++p) { const cf k = kunpack(kw[p >> 2][p & 3]); w[p] = cmul(v[BR16[p]], k); x[p] = cmul(u[BR16[p]], k); }
	v_pk_add_f32 v[18:19], v[114:115], v[16:17]
	v_pk_add_f32 v[16:17], v[114:115], v[16:17] neg_lo:[0,1] neg_hi:[0,1]
	v_mov_b32_e32 v114, v16
	v_mov_b32_e32 v115, v17
	v_pk_add_f32 v[16:17], v[102:103], v[2:3]
	v_pk_add_f32 v[2:3], v[102:103], v[2:3] neg_lo:[0,1] neg_hi:[0,1]
	v_pk_mul_f32 v[100:101], v[2:3], s[18:19] op_sel_hi:[1,0]
	v_pk_fma_f32 v[102:103], v[2:3], s[18:19], v[100:101] op_sel:[0,0,1] op_sel_hi:[1,0,0]
	v_pk_fma_f32 v[2:3], v[2:3], s[18:19], v[100:101] op_sel_hi:[1,0,0] neg_lo:[0,0,1] neg_hi:[0,0,1]
	v_mov_b32_e32 v103, v3
	v_pk_add_f32 v[2:3], v[104:105], v[4:5]
	v_pk_add_f32 v[4:5], v[104:105], v[4:5] neg_lo:[0,1] neg_hi:[0,1]
	v_pk_add_f32 v[100:101], v[4:5], 0 op_sel:[1,0] op_sel_hi:[0,0] neg_hi:[1,0]
	v_pk_add_f32 v[4:5], v[106:107], v[6:7]
	v_pk_add_f32 v[6:7], v[106:107], v[6:7] neg_lo:[0,1] neg_hi:[0,1]
	v_mul_f32_e32 v104, 0x3f3504f3, v6
	v_pk_fma_f32 v[6:7], v[6:7], s[28:29], v[104:105] op_sel:[1,0,0] op_sel_hi:[1,1,0] neg_lo:[0,0,1] neg_hi:[0,0,1]
	v_pk_add_f32 v[104:105], v[108:109], v[0:1]
	v_pk_add_f32 v[0:1], v[108:109], v[0:1] neg_lo:[0,1] neg_hi:[0,1]
	v_pk_add_f32 v[166:167], v[102:103], v[6:7]
	v_pk_add_f32 v[6:7], v[102:103], v[6:7] neg_lo:[0,1] neg_hi:[0,1]
	v_mov_b32_e32 v108, v0
	v_mov_b32_e32 v109, v1
	v_pk_add_f32 v[168:169], v[6:7], 0 op_sel:[1,0] op_sel_hi:[0,0] neg_hi:[1,0]
	v_pk_add_f32 v[0:1], v[14:15], v[8:9]
	v_pk_add_f32 v[8:9], v[14:15], v[8:9] neg_lo:[0,1] neg_hi:[0,1]
	v_pk_add_f32 v[14:15], v[8:9], 0 op_sel:[1,0] op_sel_hi:[0,0] neg_hi:[1,0]
	v_pk_add_f32 v[122:123], v[104:105], v[0:1]
	v_pk_add_f32 v[8:9], v[112:113], v[10:11]
	v_pk_add_f32 v[10:11], v[112:113], v[10:11] neg_lo:[0,1] neg_hi:[0,1]
	v_pk_add_f32 v[0:1], v[104:105], v[0:1] neg_lo:[0,1] neg_hi:[0,1]
	v_mov_b32_e32 v116, v10
	v_mov_b32_e32 v117, v11
	v_pk_add_f32 v[10:11], v[110:111], v[12:13]
	v_pk_add_f32 v[12:13], v[110:111], v[12:13] neg_lo:[0,1] neg_hi:[0,1]
	v_mov_b32_e32 v106, v0
	v_mov_b32_e32 v107, v1
	v_pk_add_f32 v[110:111], v[12:13], 0 op_sel:[1,0] op_sel_hi:[0,0] neg_hi:[1,0]
	v_pk_add_f32 v[12:13], v[18:19], v[2:3]
	v_pk_add_f32 v[2:3], v[18:19], v[2:3] neg_lo:[0,1] neg_hi:[0,1]
	v_pk_add_f32 v[0:1], v[108:109], v[14:15] neg_lo:[0,1] neg_hi:[0,1]
	v_mov_b32_e32 v124, v2
	v_mov_b32_e32 v125, v3
	v_pk_add_f32 v[2:3], v[16:17], v[4:5]
	v_pk_add_f32 v[4:5], v[16:17], v[4:5] neg_lo:[0,1] neg_hi:[0,1]
	v_pk_add_f32 v[16:17], v[114:115], v[100:101] neg_lo:[0,1] neg_hi:[0,1]
	v_pk_add_f32 v[164:165], v[4:5], 0 op_sel:[1,0] op_sel_hi:[0,0] neg_hi:[1,0]
	v_pk_add_f32 v[4:5], v[114:115], v[100:101]
	v_mov_b32_e32 v100, v16
	v_mov_b32_e32 v101, v17
	v_mov_b32_e32 v18, v0
	v_mov_b32_e32 v19, v1
	v_pk_add_f32 v[0:1], v[8:9], v[10:11] neg_lo:[0,1] neg_hi:[0,1]
	v_pk_add_f32 v[126:127], v[12:13], v[2:3]
	v_pk_add_f32 v[112:113], v[116:117], v[110:111]
	v_mov_b32_e32 v104, v0
	v_mov_b32_e32 v105, v1
	v_pk_add_f32 v[114:115], v[108:109], v[14:15]
	v_pk_add_f32 v[0:1], v[116:117], v[110:111] neg_lo:[0,1] neg_hi:[0,1]
	v_pk_add_f32 v[116:117], v[100:101], v[168:169]
	v_pk_add_f32 v[120:121], v[8:9], v[10:11]
	v_mov_b32_e32 v16, v0
	v_mov_b32_e32 v17, v1
	v_pk_add_f32 v[118:119], v[124:125], v[164:165]
	v_pk_add_f32 v[0:1], v[12:13], v[2:3] neg_lo:[0,1] neg_hi:[0,1]
	s_mov_b32 s28, s95
	v_mov_b32_e32 v110, v0
	v_mov_b32_e32 v111, v1
	s_mov_b32 s29, s94
	v_pk_add_f32 v[0:1], v[124:125], v[164:165] neg_lo:[0,1] neg_hi:[0,1]
	v_pk_add_f32 v[124:125], v[4:5], v[166:167]
	v_mov_b32_e32 v102, v0
	v_mov_b32_e32 v103, v1
	v_pk_add_f32 v[0:1], v[4:5], v[166:167] neg_lo:[0,1] neg_hi:[0,1]
	v_mov_b32_e32 v166, v98
	v_mov_b32_e32 v167, v99
	v_mov_b32_e32 v108, v0
	v_mov_b32_e32 v109, v1
	v_pk_add_f32 v[0:1], v[100:101], v[168:169] neg_lo:[0,1] neg_hi:[0,1]
	v_mov_b32_e32 v100, v0
	v_mov_b32_e32 v101, v1
	s_nop 0
	s_waitcnt vmcnt(0)
	v_lshlrev_b32_e32 v98, 16, v182
	v_and_b32_e32 v99, 0xffff0000, v182
	v_lshlrev_b32_e32 v12, 16, v183
	v_and_b32_e32 v13, 0xffff0000, v183
	v_pk_mul_f32 v[168:169], v[86:87], v[98:99] op_sel:[1,1] op_sel_hi:[1,0] neg_lo:[1,0]
	v_pk_fma_f32 v[164:165], v[86:87], v[98:99], v[168:169] op_sel_hi:[0,1,1]
	s_nop 0
	v_pk_mul_f32 v[168:169], v[122:123], v[98:99] op_sel:[1,1] op_sel_hi:[1,0] neg_lo:[1,0]
	v_pk_fma_f32 v[86:87], v[122:123], v[98:99], v[168:169] op_sel_hi:[0,1,1]
	v_pk_mul_f32 v[98:99], v[94:95], v[12:13] op_sel:[1,1] op_sel_hi:[1,0] neg_lo:[1,0]
	v_pk_fma_f32 v[94:95], v[94:95], v[12:13], v[98:99] op_sel_hi:[0,1,1]
	s_nop 0
	v_pk_mul_f32 v[98:99], v[126:127], v[12:13] op_sel:[1,1] op_sel_hi:[1,0] neg_lo:[1,0]
	v_pk_fma_f32 v[12:13], v[126:127], v[12:13], v[98:99] op_sel_hi:[0,1,1]
	s_nop 0
	v_lshlrev_b32_e32 v98, 16, v184
	v_and_b32_e32 v99, 0xffff0000, v184
	v_lshlrev_b32_e32 v14, 16, v185
	v_and_b32_e32 v15, 0xffff0000, v185
	v_pk_mul_f32 v[126:127], v[88:89], v[98:99] op_sel:[1,1] op_sel_hi:[1,0] neg_lo:[1,0]
	v_pk_fma_f32 v[122:123], v[88:89], v[98:99], v[126:127] op_sel_hi:[0,1,1]
	s_nop 0
	v_pk_mul_f32 v[126:127], v[120:121], v[98:99] op_sel:[1,1] op_sel_hi:[1,0] neg_lo:[1,0]
	v_pk_fma_f32 v[88:89], v[120:121], v[98:99], v[126:127] op_sel_hi:[0,1,1]
	v_pk_mul_f32 v[98:99], v[96:97], v[14:15] op_sel:[1,1] op_sel_hi:[1,0] neg_lo:[1,0]
	v_pk_fma_f32 v[96:97], v[96:97], v[14:15], v[98:99] op_sel_hi:[0,1,1]
	s_nop 0
	v_pk_mul_f32 v[98:99], v[124:125], v[14:15] op_sel:[1,1] op_sel_hi:[1,0] neg_lo:[1,0]
	v_pk_fma_f32 v[14:15], v[124:125], v[14:15], v[98:99] op_sel_hi:[0,1,1]
	s_nop 0
	v_lshlrev_b32_e32 v98, 16, v178
	v_and_b32_e32 v99, 0xffff0000, v178
	v_lshlrev_b32_e32 v8, 16, v179
	v_and_b32_e32 v9, 0xffff0000, v179
	v_pk_mul_f32 v[124:125], v[82:83], v[98:99] op_sel:[1,1] op_sel_hi:[1,0] neg_lo:[1,0]
; DEV cf kunpack(unsigned w) { return cf{U2F(w << 16), U2F(w & 0xffff0000u)}; }
; template <int R, bool INV> DEV void dft_regs(cf (&v)[R]) {
; #pragma unroll
;     for (int s = R; s >= 2; s >>= 1) {
;         const int h = s >> 1;
; #pragma unroll
;         for (int b = 0; b < R; b += s) {
; #pragma unroll
;             for (int k = 0; k < h; ++k) {
;                 const cf a = v[b + k], c = v[b + k + h];
;                 v[b + k] = a + c;
;                 const cf d = a - c;
;                 const int m = k * (32 / s);
;                 const float wr = tw_cos(m), wi = INV ? tw_sin(m) : -tw_sin(m);
;                 v[b + k + h] = cf{d.x * wr - d.y * wi, d.x * wi + d.y * wr};
;             }
;         }
;     }
; }
; DEV void fft_midx2(LAS cf* buf0, LAS cf* buf1, const unsigned* Kp, int blk) {
;     ...
;     for (int p = 0; p < 16; ++p) { const cf k = kunpack(kw[p >> 2][p & 3]); w[p] = cmul(v[BR16[p]], k); x[p] = cmul(u[BR16[p]], k); }
;     dft_regs<16, true>(w); dft_regs<16, true>(x);
	v_pk_fma_f32 v[120:121], v[82:83], v[98:99], v[124:125] op_sel_hi:[0,1,1]
	s_nop 0
	v_pk_mul_f32 v[124:125], v[114:115], v[98:99] op_sel:[1,1] op_sel_hi:[1,0] neg_lo:[1,0]
	v_pk_fma_f32 v[82:83], v[114:115], v[98:99], v[124:125] op_sel_hi:[0,1,1]
	v_pk_mul_f32 v[98:99], v[90:91], v[8:9] op_sel:[1,1] op_sel_hi:[1,0] neg_lo:[1,0]
	v_pk_fma_f32 v[90:91], v[90:91], v[8:9], v[98:99] op_sel_hi:[0,1,1]
	s_nop 0
	v_pk_mul_f32 v[98:99], v[118:119], v[8:9] op_sel:[1,1] op_sel_hi:[1,0] neg_lo:[1,0]
	v_pk_fma_f32 v[8:9], v[118:119], v[8:9], v[98:99] op_sel_hi:[0,1,1]
	s_nop 0
	v_lshlrev_b32_e32 v98, 16, v180
	v_and_b32_e32 v99, 0xffff0000, v180
	v_lshlrev_b32_e32 v10, 16, v181
	v_and_b32_e32 v11, 0xffff0000, v181
	v_pk_mul_f32 v[118:119], v[84:85], v[98:99] op_sel:[1,1] op_sel_hi:[1,0] neg_lo:[1,0]
	v_pk_fma_f32 v[114:115], v[84:85], v[98:99], v[118:119] op_sel_hi:[0,1,1]
	s_nop 0
	v_pk_mul_f32 v[118:119], v[112:113], v[98:99] op_sel:[1,1] op_sel_hi:[1,0] neg_lo:[1,0]
	v_pk_fma_f32 v[84:85], v[112:113], v[98:99], v[118:119] op_sel_hi:[0,1,1]
	v_pk_mul_f32 v[98:99], v[92:93], v[10:11] op_sel:[1,1] op_sel_hi:[1,0] neg_lo:[1,0]
	v_pk_fma_f32 v[92:93], v[92:93], v[10:11], v[98:99] op_sel_hi:[0,1,1]
	s_nop 0
	v_pk_mul_f32 v[98:99], v[116:117], v[10:11] op_sel:[1,1] op_sel_hi:[1,0] neg_lo:[1,0]
	v_pk_fma_f32 v[10:11], v[116:117], v[10:11], v[98:99] op_sel_hi:[0,1,1]
	s_nop 0
	v_lshlrev_b32_e32 v98, 16, v174
	v_and_b32_e32 v99, 0xffff0000, v174
	v_pk_mul_f32 v[112:113], v[76:77], v[98:99] op_sel:[1,1] op_sel_hi:[1,0] neg_lo:[1,0]
	v_pk_fma_f32 v[76:77], v[76:77], v[98:99], v[112:113] op_sel_hi:[0,1,1]
	v_lshlrev_b32_e32 v4, 16, v175
	v_pk_mul_f32 v[112:113], v[106:107], v[98:99] op_sel:[1,1] op_sel_hi:[1,0] neg_lo:[1,0]
	v_pk_fma_f32 v[98:99], v[106:107], v[98:99], v[112:113] op_sel_hi:[0,1,1]
	v_and_b32_e32 v5, 0xffff0000, v175
	v_pk_mul_f32 v[106:107], v[80:81], v[4:5] op_sel:[1,1] op_sel_hi:[1,0] neg_lo:[1,0]
	v_pk_fma_f32 v[80:81], v[80:81], v[4:5], v[106:107] op_sel_hi:[0,1,1]
	s_nop 0
	v_pk_mul_f32 v[112:113], v[110:111], v[4:5] op_sel:[1,1] op_sel_hi:[1,0] neg_lo:[1,0]
	v_pk_fma_f32 v[106:107], v[110:111], v[4:5], v[112:113] op_sel_hi:[0,1,1]
	v_lshlrev_b32_e32 v4, 16, v176
	v_and_b32_e32 v5, 0xffff0000, v176
	v_pk_mul_f32 v[110:111], v[74:75], v[4:5] op_sel:[1,1] op_sel_hi:[1,0] neg_lo:[1,0]
	v_pk_fma_f32 v[74:75], v[74:75], v[4:5], v[110:111] op_sel_hi:[0,1,1]
	s_nop 0
	v_pk_mul_f32 v[110:111], v[104:105], v[4:5] op_sel:[1,1] op_sel_hi:[1,0] neg_lo:[1,0]
	v_pk_fma_f32 v[104:105], v[104:105], v[4:5], v[110:111] op_sel_hi:[0,1,1]
	v_lshlrev_b32_e32 v4, 16, v177
	v_and_b32_e32 v5, 0xffff0000, v177
	v_pk_mul_f32 v[110:111], v[78:79], v[4:5] op_sel:[1,1] op_sel_hi:[1,0] neg_lo:[1,0]
	v_pk_fma_f32 v[6:7], v[78:79], v[4:5], v[110:111] op_sel_hi:[0,1,1]
	v_pk_mul_f32 v[78:79], v[108:109], v[4:5] op_sel:[1,1] op_sel_hi:[1,0] neg_lo:[1,0]
	v_pk_fma_f32 v[108:109], v[108:109], v[4:5], v[78:79] op_sel_hi:[0,1,1]
	v_lshlrev_b32_e32 v4, 16, v170
	v_and_b32_e32 v5, 0xffff0000, v170
	v_lshlrev_b32_e32 v0, 16, v171
	v_and_b32_e32 v1, 0xffff0000, v171
	v_pk_mul_f32 v[78:79], v[70:71], v[4:5] op_sel:[1,1] op_sel_hi:[1,0] neg_lo:[1,0]
	v_pk_fma_f32 v[70:71], v[70:71], v[4:5], v[78:79] op_sel_hi:[0,1,1]
	s_nop 0
	v_pk_mul_f32 v[78:79], v[18:19], v[4:5] op_sel:[1,1] op_sel_hi:[1,0] neg_lo:[1,0]
	v_pk_fma_f32 v[110:111], v[18:19], v[4:5], v[78:79] op_sel_hi:[0,1,1]
	v_pk_mul_f32 v[18:19], v[72:73], v[0:1] op_sel:[1,1] op_sel_hi:[1,0] neg_lo:[1,0]
	v_pk_fma_f32 v[4:5], v[72:73], v[0:1], v[18:19] op_sel_hi:[0,1,1]
	s_nop 0
	v_pk_mul_f32 v[18:19], v[102:103], v[0:1] op_sel:[1,1] op_sel_hi:[1,0] neg_lo:[1,0]
	v_pk_fma_f32 v[102:103], v[102:103], v[0:1], v[18:19] op_sel_hi:[0,1,1]
	v_lshlrev_b32_e32 v0, 16, v172
	v_and_b32_e32 v1, 0xffff0000, v172
	v_pk_mul_f32 v[72:73], v[68:69], v[0:1] op_sel:[1,1] op_sel_hi:[1,0] neg_lo:[1,0]
	v_pk_fma_f32 v[18:19], v[68:69], v[0:1], v[72:73] op_sel_hi:[0,1,1]
	v_pk_mul_f32 v[68:69], v[16:17], v[0:1] op_sel:[1,1] op_sel_hi:[1,0] neg_lo:[1,0]
	v_pk_fma_f32 v[112:113], v[16:17], v[0:1], v[68:69] op_sel_hi:[0,1,1]
	v_lshlrev_b32_e32 v0, 16, v173
	v_and_b32_e32 v1, 0xffff0000, v173
	v_pk_mul_f32 v[16:17], v[166:167], v[0:1] op_sel:[1,1] op_sel_hi:[1,0] neg_lo:[1,0]
	v_pk_fma_f32 v[2:3], v[166:167], v[0:1], v[16:17] op_sel_hi:[0,1,1]
	s_nop 0
	v_pk_mul_f32 v[16:17], v[100:101], v[0:1] op_sel:[1,1] op_sel_hi:[1,0] neg_lo:[1,0]
	v_pk_fma_f32 v[100:101], v[100:101], v[0:1], v[16:17] op_sel_hi:[0,1,1]
	v_pk_add_f32 v[0:1], v[164:165], v[76:77]
	v_pk_add_f32 v[16:17], v[164:165], v[76:77] neg_lo:[0,1] neg_hi:[0,1]
	v_mov_b32_e32 v72, v16
	v_mov_b32_e32 v73, v17
	v_pk_add_f32 v[68:69], v[94:95], v[80:81] neg_lo:[0,1] neg_hi:[0,1]
	v_pk_mul_f32 v[76:77], v[68:69], s[84:85] op_sel_hi:[1,0]
	v_pk_add_f32 v[16:17], v[94:95], v[80:81]
	v_pk_fma_f32 v[78:79], v[68:69], s[16:17], v[76:77] op_sel:[0,0,1] op_sel_hi:[1,0,0] neg_lo:[0,0,1] neg_hi:[0,0,1]
	v_pk_fma_f32 v[68:69], v[68:69], s[16:17], v[76:77] op_sel:[0,0,1] op_sel_hi:[1,0,0]
	v_mov_b32_e32 v79, v69
	v_pk_add_f32 v[68:69], v[122:123], v[74:75]
	v_pk_add_f32 v[74:75], v[122:123], v[74:75] neg_lo:[0,1] neg_hi:[0,1]
	v_pk_mul_f32 v[76:77], v[74:75], s[18:19] op_sel_hi:[1,0]
	v_pk_fma_f32 v[80:81], v[74:75], s[18:19], v[76:77] op_sel:[0,0,1] op_sel_hi:[1,0,0] neg_lo:[0,0,1] neg_hi:[0,0,1]
	v_pk_fma_f32 v[74:75], v[74:75], s[18:19], v[76:77] op_sel_hi:[1,0,0]
	v_mov_b32_e32 v81, v75
	v_pk_add_f32 v[74:75], v[96:97], v[6:7]
	v_pk_add_f32 v[6:7], v[96:97], v[6:7] neg_lo:[0,1] neg_hi:[0,1]
	v_pk_mul_f32 v[76:77], v[6:7], s[16:17] op_sel_hi:[1,0]
; template <int R, bool INV> DEV void dft_regs(cf (&v)[R]) {
; #pragma unroll
;     for (int s = R; s >= 2; s >>= 1) {
;         const int h = s >> 1;
; #pragma unroll
;         for (int b = 0; b < R; b += s) {
; #pragma unroll
;             for (int k = 0; k < h; ++k) {
;                 const cf a = v[b + k], c = v[b + k + h];
;                 v[b + k] = a + c;
;                 const cf d = a - c;
;                 const int m = k * (32 / s);
;                 const float wr = tw_cos(m), wi = INV ? tw_sin(m) : -tw_sin(m);
;                 v[b + k + h] = cf{d.x * wr - d.y * wi, d.x * wi + d.y * wr};
;             }
;         }
;     }
; }
; DEV void fft_midx2(LAS cf* buf0, LAS cf* buf1, const unsigned* Kp, int blk) {
;     ...
;     dft_regs<16, true>(w); dft_regs<16, true>(x);
	v_pk_fma_f32 v[94:95], v[6:7], s[84:85], v[76:77] op_sel:[0,0,1] op_sel_hi:[1,0,0] neg_lo:[0,0,1] neg_hi:[0,0,1]
	v_pk_fma_f32 v[6:7], v[6:7], s[84:85], v[76:77] op_sel:[0,0,1] op_sel_hi:[1,0,0]
	v_mov_b32_e32 v95, v7
	v_pk_add_f32 v[6:7], v[120:121], v[70:71]
	v_pk_add_f32 v[70:71], v[120:121], v[70:71] neg_lo:[0,1] neg_hi:[0,1]
	v_pk_add_f32 v[76:77], v[70:71], 0 op_sel:[1,0] op_sel_hi:[0,0] neg_lo:[1,0]
	v_pk_add_f32 v[70:71], v[90:91], v[4:5]
	v_pk_add_f32 v[4:5], v[90:91], v[4:5] neg_lo:[0,1] neg_hi:[0,1]
	v_pk_mul_f32 v[90:91], v[4:5], s[24:25] op_sel:[1,0]
	v_pk_fma_f32 v[4:5], v[4:5], s[0:1], v[90:91] op_sel_hi:[0,1,1] neg_lo:[0,0,1] neg_hi:[0,0,1]
	v_pk_add_f32 v[90:91], v[114:115], v[18:19]
	v_pk_add_f32 v[18:19], v[114:115], v[18:19] neg_lo:[0,1] neg_hi:[0,1]
	v_mul_f32_e32 v96, 0x3f3504f3, v19
	v_pk_fma_f32 v[18:19], v[18:19], s[96:97], v[96:97] op_sel_hi:[0,1,0] neg_lo:[0,0,1] neg_hi:[0,0,1]
	v_pk_add_f32 v[96:97], v[92:93], v[2:3]
	v_pk_add_f32 v[2:3], v[92:93], v[2:3] neg_lo:[0,1] neg_hi:[0,1]
	v_pk_mul_f32 v[92:93], v[2:3], s[84:85] op_sel:[1,0]
	v_pk_fma_f32 v[2:3], v[2:3], s[88:89], v[92:93] op_sel_hi:[0,1,1] neg_lo:[0,0,1] neg_hi:[0,0,1]
	v_pk_add_f32 v[92:93], v[0:1], v[6:7]
	v_pk_add_f32 v[0:1], v[0:1], v[6:7] neg_lo:[0,1] neg_hi:[0,1]
	v_mov_b32_e32 v114, v0
	v_mov_b32_e32 v115, v1
	v_pk_add_f32 v[6:7], v[16:17], v[70:71] neg_lo:[0,1] neg_hi:[0,1]
	v_pk_add_f32 v[0:1], v[16:17], v[70:71]
	v_pk_mul_f32 v[16:17], v[6:7], s[18:19] op_sel_hi:[1,0]
	v_pk_fma_f32 v[70:71], v[6:7], s[18:19], v[16:17] op_sel:[0,0,1] op_sel_hi:[1,0,0] neg_lo:[0,0,1] neg_hi:[0,0,1]
	v_pk_fma_f32 v[6:7], v[6:7], s[18:19], v[16:17] op_sel_hi:[1,0,0]
	v_pk_add_f32 v[16:17], v[68:69], v[90:91] neg_lo:[0,1] neg_hi:[0,1]
	v_mov_b32_e32 v71, v7
	v_pk_add_f32 v[6:7], v[68:69], v[90:91]
	v_pk_add_f32 v[68:69], v[16:17], 0 op_sel:[1,0] op_sel_hi:[0,0] neg_lo:[1,0]
	v_pk_add_f32 v[16:17], v[74:75], v[96:97]
	v_pk_add_f32 v[74:75], v[74:75], v[96:97] neg_lo:[0,1] neg_hi:[0,1]
	v_mul_f32_e32 v90, 0x3f3504f3, v75
	v_pk_fma_f32 v[74:75], v[74:75], s[96:97], v[90:91] op_sel_hi:[0,1,0] neg_lo:[0,0,1] neg_hi:[0,0,1]
	v_pk_add_f32 v[90:91], v[72:73], v[76:77]
	v_pk_add_f32 v[72:73], v[72:73], v[76:77] neg_lo:[0,1] neg_hi:[0,1]
	v_mov_b32_e32 v96, v72
	v_mov_b32_e32 v97, v73
	v_pk_add_f32 v[72:73], v[78:79], v[4:5]
	v_pk_add_f32 v[4:5], v[78:79], v[4:5] neg_lo:[0,1] neg_hi:[0,1]
	v_pk_mul_f32 v[76:77], v[4:5], s[18:19] op_sel_hi:[1,0]
	v_pk_fma_f32 v[78:79], v[4:5], s[18:19], v[76:77] op_sel:[0,0,1] op_sel_hi:[1,0,0] neg_lo:[0,0,1] neg_hi:[0,0,1]
	v_pk_fma_f32 v[4:5], v[4:5], s[18:19], v[76:77] op_sel_hi:[1,0,0]
	v_mov_b32_e32 v79, v5
	v_pk_add_f32 v[4:5], v[80:81], v[18:19]
	v_pk_add_f32 v[18:19], v[80:81], v[18:19] neg_lo:[0,1] neg_hi:[0,1]
	v_pk_add_f32 v[116:117], v[90:91], v[4:5]
	v_pk_add_f32 v[76:77], v[18:19], 0 op_sel:[1,0] op_sel_hi:[0,0] neg_lo:[1,0]
	v_pk_add_f32 v[4:5], v[90:91], v[4:5] neg_lo:[0,1] neg_hi:[0,1]
	v_pk_add_f32 v[18:19], v[94:95], v[2:3]
	v_pk_add_f32 v[2:3], v[94:95], v[2:3] neg_lo:[0,1] neg_hi:[0,1]
	v_pk_add_f32 v[118:119], v[72:73], v[18:19]
	v_mul_f32_e32 v80, 0x3f3504f3, v3
	v_pk_fma_f32 v[2:3], v[2:3], s[96:97], v[80:81] op_sel_hi:[0,1,0] neg_lo:[0,0,1] neg_hi:[0,0,1]
	v_pk_add_f32 v[80:81], v[92:93], v[6:7]
	v_pk_add_f32 v[6:7], v[92:93], v[6:7] neg_lo:[0,1] neg_hi:[0,1]
	v_pk_add_f32 v[122:123], v[78:79], v[2:3]
	v_pk_add_f32 v[2:3], v[78:79], v[2:3] neg_lo:[0,1] neg_hi:[0,1]
	v_mov_b32_e32 v94, v6
	v_mov_b32_e32 v95, v7
	v_pk_add_f32 v[78:79], v[2:3], 0 op_sel:[1,0] op_sel_hi:[0,0] neg_lo:[1,0]
	v_pk_add_f32 v[6:7], v[0:1], v[16:17]
	v_pk_add_f32 v[0:1], v[0:1], v[16:17] neg_lo:[0,1] neg_hi:[0,1]
	v_pk_add_f32 v[16:17], v[0:1], 0 op_sel:[1,0] op_sel_hi:[0,0] neg_lo:[1,0]
	v_pk_add_f32 v[120:121], v[96:97], v[76:77]
	v_pk_add_f32 v[0:1], v[114:115], v[68:69]
	v_pk_add_f32 v[68:69], v[114:115], v[68:69] neg_lo:[0,1] neg_hi:[0,1]
	v_pk_add_f32 v[2:3], v[80:81], v[6:7] neg_lo:[0,1] neg_hi:[0,1]
	v_mov_b32_e32 v114, v68
	v_mov_b32_e32 v115, v69
	v_pk_add_f32 v[92:93], v[70:71], v[74:75]
	v_pk_add_f32 v[68:69], v[70:71], v[74:75] neg_lo:[0,1] neg_hi:[0,1]
	v_pk_add_f32 v[124:125], v[80:81], v[6:7]
	v_pk_add_f32 v[74:75], v[68:69], 0 op_sel:[1,0] op_sel_hi:[0,0] neg_lo:[1,0]
	v_pk_add_f32 v[80:81], v[94:95], v[16:17]
	v_mov_b32_e32 v90, v4
	v_mov_b32_e32 v91, v5
	v_pk_add_f32 v[4:5], v[72:73], v[18:19] neg_lo:[0,1] neg_hi:[0,1]
	v_pk_add_f32 v[72:73], v[4:5], 0 op_sel:[1,0] op_sel_hi:[0,0] neg_lo:[1,0]
	v_pk_add_f32 v[4:5], v[96:97], v[76:77] neg_lo:[0,1] neg_hi:[0,1]
	v_pk_add_f32 v[126:127], v[90:91], v[72:73]
	v_pk_add_f32 v[72:73], v[90:91], v[72:73] neg_lo:[0,1] neg_hi:[0,1]
	v_mov_b32_e32 v96, v4
	v_mov_b32_e32 v97, v5
	v_pk_add_f32 v[90:91], v[120:121], v[122:123]
	v_pk_add_f32 v[164:165], v[96:97], v[78:79]
	v_mov_b32_e32 v18, v2
	v_mov_b32_e32 v19, v3
	v_mov_b32_e32 v68, v2
	v_mov_b32_e32 v69, v3
	v_pk_add_f32 v[4:5], v[94:95], v[16:17] neg_lo:[0,1] neg_hi:[0,1]
	v_pk_add_f32 v[94:95], v[0:1], v[92:93]
	v_pk_add_f32 v[0:1], v[0:1], v[92:93] neg_lo:[0,1] neg_hi:[0,1]
	v_mov_b32_e32 v2, v4
	v_mov_b32_e32 v3, v5
	v_pk_add_f32 v[92:93], v[114:115], v[74:75]
	v_mov_b32_e32 v16, v0
	v_mov_b32_e32 v17, v1
	v_mov_b32_e32 v70, v0
	v_mov_b32_e32 v71, v1
	v_pk_add_f32 v[6:7], v[114:115], v[74:75] neg_lo:[0,1] neg_hi:[0,1]
	v_pk_add_f32 v[114:115], v[116:117], v[118:119]
	v_pk_add_f32 v[78:79], v[96:97], v[78:79] neg_lo:[0,1] neg_hi:[0,1]
	v_mov_b32_e32 v0, v6
	v_mov_b32_e32 v1, v7
	v_pk_add_f32 v[74:75], v[116:117], v[118:119] neg_lo:[0,1] neg_hi:[0,1]
	v_mov_b32_e32 v116, v74
	v_mov_b32_e32 v117, v75
	v_mov_b32_e32 v118, v74
; template <int R, bool INV> DEV void dft_regs(cf (&v)[R]) {
; #pragma unroll
;     for (int s = R; s >= 2; s >>= 1) {
;         const int h = s >> 1;
; #pragma unroll
;         for (int b = 0; b < R; b += s) {
; #pragma unroll
;             for (int k = 0; k < h; ++k) {
;                 const cf a = v[b + k], c = v[b + k + h];
;                 v[b + k] = a + c;
;                 const cf d = a - c;
;                 const int m = k * (32 / s);
;                 const float wr = tw_cos(m), wi = INV ? tw_sin(m) : -tw_sin(m);
;                 v[b + k + h] = cf{d.x * wr - d.y * wi, d.x * wi + d.y * wr};
;             }
;         }
;     }
; }
; DEV void fft_midx2(LAS cf* buf0, LAS cf* buf1, const unsigned* Kp, int blk) {
;     ...
;     dft_regs<16, true>(w); dft_regs<16, true>(x);
	v_mov_b32_e32 v119, v75
	v_mov_b32_e32 v19, v69
	v_mov_b32_e32 v74, v72
	v_mov_b32_e32 v75, v73
	v_mov_b32_e32 v76, v72
	v_mov_b32_e32 v77, v73
	v_pk_add_f32 v[72:73], v[120:121], v[122:123] neg_lo:[0,1] neg_hi:[0,1]
	v_mov_b32_e32 v117, v119
	v_mov_b32_e32 v17, v71
	v_mov_b32_e32 v122, v72
	v_mov_b32_e32 v123, v73
	v_mov_b32_e32 v120, v72
	v_mov_b32_e32 v121, v73
	v_mov_b32_e32 v72, v78
	v_mov_b32_e32 v73, v79
	v_pk_add_f32 v[96:97], v[86:87], v[98:99]
	v_pk_add_f32 v[86:87], v[86:87], v[98:99] neg_lo:[0,1] neg_hi:[0,1]
	v_mov_b32_e32 v123, v121
	v_mov_b32_e32 v166, v86
	v_mov_b32_e32 v167, v87
	v_pk_add_f32 v[86:87], v[12:13], v[106:107]
	v_pk_add_f32 v[12:13], v[12:13], v[106:107] neg_lo:[0,1] neg_hi:[0,1]
	v_mov_b32_e32 v75, v77
	v_pk_mul_f32 v[98:99], v[12:13], s[84:85] op_sel_hi:[1,0]
	v_pk_fma_f32 v[106:107], v[12:13], s[16:17], v[98:99] op_sel:[0,0,1] op_sel_hi:[1,0,0] neg_lo:[0,0,1] neg_hi:[0,0,1]
	v_pk_fma_f32 v[12:13], v[12:13], s[16:17], v[98:99] op_sel:[0,0,1] op_sel_hi:[1,0,0]
	v_mov_b32_e32 v107, v13
	v_pk_add_f32 v[12:13], v[88:89], v[104:105]
	v_pk_add_f32 v[88:89], v[88:89], v[104:105] neg_lo:[0,1] neg_hi:[0,1]
	v_pk_mul_f32 v[98:99], v[88:89], s[18:19] op_sel_hi:[1,0]
	v_pk_fma_f32 v[104:105], v[88:89], s[18:19], v[98:99] op_sel:[0,0,1] op_sel_hi:[1,0,0] neg_lo:[0,0,1] neg_hi:[0,0,1]
	v_pk_fma_f32 v[88:89], v[88:89], s[18:19], v[98:99] op_sel_hi:[1,0,0]
	v_mov_b32_e32 v105, v89
	v_pk_add_f32 v[88:89], v[14:15], v[108:109]
	v_pk_add_f32 v[14:15], v[14:15], v[108:109] neg_lo:[0,1] neg_hi:[0,1]
	v_pk_mul_f32 v[98:99], v[14:15], s[16:17] op_sel_hi:[1,0]
	v_pk_fma_f32 v[108:109], v[14:15], s[84:85], v[98:99] op_sel:[0,0,1] op_sel_hi:[1,0,0] neg_lo:[0,0,1] neg_hi:[0,0,1]
	v_pk_fma_f32 v[14:15], v[14:15], s[84:85], v[98:99] op_sel:[0,0,1] op_sel_hi:[1,0,0]
	v_mov_b32_e32 v109, v15
	v_pk_add_f32 v[14:15], v[82:83], v[110:111]
	v_pk_add_f32 v[82:83], v[82:83], v[110:111] neg_lo:[0,1] neg_hi:[0,1]
	v_pk_add_f32 v[110:111], v[10:11], v[100:101]
	v_pk_add_f32 v[10:11], v[10:11], v[100:101] neg_lo:[0,1] neg_hi:[0,1]
	v_pk_add_f32 v[98:99], v[82:83], 0 op_sel:[1,0] op_sel_hi:[0,0] neg_lo:[1,0]
	v_pk_mul_f32 v[100:101], v[10:11], s[84:85] op_sel:[1,0]
	v_pk_add_f32 v[82:83], v[8:9], v[102:103]
	v_pk_add_f32 v[8:9], v[8:9], v[102:103] neg_lo:[0,1] neg_hi:[0,1]
	v_pk_fma_f32 v[10:11], v[10:11], s[88:89], v[100:101] op_sel_hi:[0,1,1] neg_lo:[0,0,1] neg_hi:[0,0,1]
	v_pk_add_f32 v[100:101], v[96:97], v[14:15]
	v_pk_add_f32 v[14:15], v[96:97], v[14:15] neg_lo:[0,1] neg_hi:[0,1]
	v_pk_mul_f32 v[102:103], v[8:9], s[24:25] op_sel:[1,0]
	v_pk_fma_f32 v[8:9], v[8:9], s[0:1], v[102:103] op_sel_hi:[0,1,1] neg_lo:[0,0,1] neg_hi:[0,0,1]
	v_pk_add_f32 v[102:103], v[84:85], v[112:113]
	v_pk_add_f32 v[84:85], v[84:85], v[112:113] neg_lo:[0,1] neg_hi:[0,1]
	v_mov_b32_e32 v112, v14
	v_mov_b32_e32 v113, v15
	v_mul_f32_e32 v4, 0x3f3504f3, v85
	v_pk_add_f32 v[14:15], v[86:87], v[82:83]
	v_pk_add_f32 v[82:83], v[86:87], v[82:83] neg_lo:[0,1] neg_hi:[0,1]
	v_pk_fma_f32 v[84:85], v[84:85], s[96:97], v[4:5] op_sel_hi:[0,1,0] neg_lo:[0,0,1] neg_hi:[0,0,1]
	v_pk_mul_f32 v[86:87], v[82:83], s[18:19] op_sel_hi:[1,0]
	v_pk_fma_f32 v[96:97], v[82:83], s[18:19], v[86:87] op_sel:[0,0,1] op_sel_hi:[1,0,0] neg_lo:[0,0,1] neg_hi:[0,0,1]
	v_pk_fma_f32 v[82:83], v[82:83], s[18:19], v[86:87] op_sel_hi:[1,0,0]
	v_mov_b32_e32 v97, v83
	v_pk_add_f32 v[82:83], v[12:13], v[102:103]
	v_pk_add_f32 v[12:13], v[12:13], v[102:103] neg_lo:[0,1] neg_hi:[0,1]
	v_pk_add_f32 v[102:103], v[166:167], v[98:99]
	v_pk_add_f32 v[86:87], v[12:13], 0 op_sel:[1,0] op_sel_hi:[0,0] neg_lo:[1,0]
	v_pk_add_f32 v[98:99], v[166:167], v[98:99] neg_lo:[0,1] neg_hi:[0,1]
	v_pk_add_f32 v[12:13], v[88:89], v[110:111]
	v_pk_add_f32 v[88:89], v[88:89], v[110:111] neg_lo:[0,1] neg_hi:[0,1]
	v_mul_f32_e32 v4, 0x3f3504f3, v89
	v_mov_b32_e32 v166, v98
	v_mov_b32_e32 v167, v99
	v_pk_fma_f32 v[88:89], v[88:89], s[96:97], v[4:5] op_sel_hi:[0,1,0] neg_lo:[0,0,1] neg_hi:[0,0,1]
	v_pk_add_f32 v[98:99], v[106:107], v[8:9]
	v_pk_add_f32 v[8:9], v[106:107], v[8:9] neg_lo:[0,1] neg_hi:[0,1]
	v_pk_mul_f32 v[106:107], v[8:9], s[18:19] op_sel_hi:[1,0]
	v_pk_fma_f32 v[110:111], v[8:9], s[18:19], v[106:107] op_sel:[0,0,1] op_sel_hi:[1,0,0] neg_lo:[0,0,1] neg_hi:[0,0,1]
	v_pk_fma_f32 v[8:9], v[8:9], s[18:19], v[106:107] op_sel_hi:[1,0,0]
	v_pk_add_f32 v[106:107], v[100:101], v[82:83]
	v_mov_b32_e32 v111, v9
	v_pk_add_f32 v[8:9], v[104:105], v[84:85]
	v_pk_add_f32 v[84:85], v[104:105], v[84:85] neg_lo:[0,1] neg_hi:[0,1]
	v_pk_add_f32 v[82:83], v[100:101], v[82:83] neg_lo:[0,1] neg_hi:[0,1]
	v_pk_add_f32 v[104:105], v[84:85], 0 op_sel:[1,0] op_sel_hi:[0,0] neg_lo:[1,0]
	v_pk_add_f32 v[84:85], v[108:109], v[10:11]
	v_pk_add_f32 v[10:11], v[108:109], v[10:11] neg_lo:[0,1] neg_hi:[0,1]
	v_mov_b32_e32 v108, v82
	v_mov_b32_e32 v109, v83
	v_mul_f32_e32 v4, 0x3f3504f3, v11
	v_pk_add_f32 v[82:83], v[14:15], v[12:13]
	v_pk_add_f32 v[12:13], v[14:15], v[12:13] neg_lo:[0,1] neg_hi:[0,1]
	v_pk_fma_f32 v[10:11], v[10:11], s[96:97], v[4:5] op_sel_hi:[0,1,0] neg_lo:[0,0,1] neg_hi:[0,0,1]
	v_pk_add_f32 v[14:15], v[12:13], 0 op_sel:[1,0] op_sel_hi:[0,0] neg_lo:[1,0]
	v_pk_add_f32 v[12:13], v[112:113], v[86:87]
	v_pk_add_f32 v[86:87], v[112:113], v[86:87] neg_lo:[0,1] neg_hi:[0,1]
	v_mov_b32_e32 v112, v86
	v_mov_b32_e32 v113, v87
	v_pk_add_f32 v[86:87], v[96:97], v[88:89]
	v_pk_add_f32 v[88:89], v[96:97], v[88:89] neg_lo:[0,1] neg_hi:[0,1]
	v_pk_add_f32 v[96:97], v[88:89], 0 op_sel:[1,0] op_sel_hi:[0,0] neg_lo:[1,0]
	v_pk_add_f32 v[88:89], v[102:103], v[8:9]
	v_pk_add_f32 v[8:9], v[102:103], v[8:9] neg_lo:[0,1] neg_hi:[0,1]
	v_mov_b32_e32 v102, v8
; #define LAS __attribute__((address_space(3)))
; #define SINCOSPI(x, s, c) do { const float hx_ = 0.5f * (x); *(s) = __builtin_amdgcn_sinf(hx_); *(c) = __builtin_amdgcn_cosf(hx_); } while (0)
; #define OPAQUE_I(x) asm volatile("" : "+v"(x))
; DEV void fft_midx2(LAS cf* buf0, LAS cf* buf1, const unsigned* Kp, int blk) {
;     ...
;     dft_regs<16, true>(w); dft_regs<16, true>(x);
; #pragma unroll
;     for (int q = 0; q < 16; ++q) { p0[q] = w[BR16[q]]; p1[q] = x[BR16[q]]; }
; DEV void fft_i2(LAS cf* buf, int t8) {
;     OPAQUE_I(t8);
;     LAS cf* pb = buf + (t8 >> 4) * 544 + (t8 & 15);
;     float sn, cs; SINCOSPI(-(float)(t8 & 15) * (2.0f / 512.0f), &sn, &cs);
;     const cf w = cf{cs, sn}; cf wp = cf{1.f, 0.f};
;     cf v[32];
; #pragma unroll
;     for (int p = 0; p < 32; ++p) { v[p] = cmulc(pb[17 * p], wp); wp = cmul(wp, w); }
; DEV void hyena_issue_rows(const bf16_t* UT, int s, int c, u32x4 (&r)[4], int tid) {
;     ...
;     for (int b = 0; b < 4; ++b) r[b] = *(const u32x4*)(UT + ((size_t)(b * 3072 + s * 1024 + c)) * 4096 + tid * 8);
	v_mov_b32_e32 v103, v9
	v_pk_add_f32 v[100:101], v[166:167], v[104:105] neg_lo:[0,1] neg_hi:[0,1]
	v_pk_add_f32 v[8:9], v[98:99], v[84:85]
	v_pk_add_f32 v[84:85], v[98:99], v[84:85] neg_lo:[0,1] neg_hi:[0,1]
	v_pk_add_f32 v[98:99], v[84:85], 0 op_sel:[1,0] op_sel_hi:[0,0] neg_lo:[1,0]
	v_pk_add_f32 v[84:85], v[166:167], v[104:105]
	v_mov_b32_e32 v166, v100
	v_mov_b32_e32 v167, v101
	v_pk_add_f32 v[100:101], v[110:111], v[10:11]
	v_pk_add_f32 v[10:11], v[110:111], v[10:11] neg_lo:[0,1] neg_hi:[0,1]
	v_pk_add_f32 v[104:105], v[10:11], 0 op_sel:[1,0] op_sel_hi:[0,0] neg_lo:[1,0]
	v_pk_add_f32 v[10:11], v[106:107], v[82:83]
	v_pk_add_f32 v[82:83], v[106:107], v[82:83] neg_lo:[0,1] neg_hi:[0,1]
	v_mov_b32_e32 v110, v82
	v_mov_b32_e32 v111, v83
	v_pk_add_f32 v[106:107], v[108:109], v[14:15]
	v_pk_add_f32 v[14:15], v[108:109], v[14:15] neg_lo:[0,1] neg_hi:[0,1]
	v_mov_b32_e32 v168, v14
	v_mov_b32_e32 v169, v15
	v_pk_add_f32 v[108:109], v[12:13], v[86:87]
	v_pk_add_f32 v[12:13], v[12:13], v[86:87] neg_lo:[0,1] neg_hi:[0,1]
	v_mov_b32_e32 v170, v12
	v_mov_b32_e32 v171, v13
	v_pk_add_f32 v[86:87], v[112:113], v[96:97]
	v_pk_add_f32 v[96:97], v[112:113], v[96:97] neg_lo:[0,1] neg_hi:[0,1]
	v_mov_b32_e32 v172, v96
	v_mov_b32_e32 v173, v97
	v_pk_add_f32 v[112:113], v[88:89], v[8:9]
	v_pk_add_f32 v[8:9], v[88:89], v[8:9] neg_lo:[0,1] neg_hi:[0,1]
	v_mov_b32_e32 v174, v8
	v_mov_b32_e32 v175, v9
	v_pk_add_f32 v[88:89], v[102:103], v[98:99]
	v_pk_add_f32 v[98:99], v[102:103], v[98:99] neg_lo:[0,1] neg_hi:[0,1]
	v_mov_b32_e32 v176, v98
	v_mov_b32_e32 v177, v99
	v_pk_add_f32 v[102:103], v[84:85], v[100:101]
	v_pk_add_f32 v[84:85], v[84:85], v[100:101] neg_lo:[0,1] neg_hi:[0,1]
	v_mov_b32_e32 v178, v84
	v_mov_b32_e32 v179, v85
	v_pk_add_f32 v[100:101], v[166:167], v[104:105]
	v_pk_add_f32 v[104:105], v[166:167], v[104:105] neg_lo:[0,1] neg_hi:[0,1]
	ds_write2_b64 v161, v[124:125], v[114:115] offset1:1
	ds_write2_b64 v162, v[10:11], v[112:113] offset1:1
	ds_write2_b64 v161, v[94:95], v[90:91] offset0:2 offset1:3
	ds_write2_b64 v162, v[108:109], v[102:103] offset0:2 offset1:3
	ds_write2_b64 v161, v[80:81], v[126:127] offset0:4 offset1:5
	ds_write2_b64 v162, v[106:107], v[88:89] offset0:4 offset1:5
	ds_write2_b64 v161, v[92:93], v[164:165] offset0:6 offset1:7
	ds_write2_b64 v162, v[86:87], v[100:101] offset0:6 offset1:7
	v_mov_b32_e32 v180, v104
	v_mov_b32_e32 v181, v105
	ds_write2_b64 v161, v[0:1], v[72:73] offset0:14 offset1:15
	v_mov_b32_e32 v0, v160
	ds_write2_b64 v161, v[18:19], v[116:117] offset0:8 offset1:9
	ds_write2_b64 v162, v[110:111], v[174:175] offset0:8 offset1:9
	ds_write2_b64 v161, v[16:17], v[122:123] offset0:10 offset1:11
	ds_write2_b64 v162, v[170:171], v[178:179] offset0:10 offset1:11
	ds_write2_b64 v161, v[2:3], v[74:75] offset0:12 offset1:13
	ds_write2_b64 v162, v[168:169], v[176:177] offset0:12 offset1:13
	ds_write2_b64 v162, v[172:173], v[180:181] offset0:14 offset1:15
	s_waitcnt lgkmcnt(0)
	s_barrier
	s_lshl_b32 s100, s19, 10
	s_add_i32 s100, s79, s100
	s_ashr_i32 s101, s100, 31
	s_lshl_b64 s[100:101], s[100:101], 13
	v_lshl_add_u64 v[218:219], v[56:57], 0, s[100:101]
	global_load_dwordx4 v[222:225], v[218:219], off
	s_add_u32 s100, s100, 0x1800000
	s_addc_u32 s101, s101, 0
	v_lshl_add_u64 v[220:221], v[56:57], 0, s[100:101]
	global_load_dwordx4 v[226:229], v[220:221], off
	s_add_u32 s100, s100, 0x1800000
	s_addc_u32 s101, s101, 0
	v_lshl_add_u64 v[218:219], v[56:57], 0, s[100:101]
	global_load_dwordx4 v[236:239], v[218:219], off
	s_add_u32 s100, s100, 0x1800000
	s_addc_u32 s101, s101, 0
	v_lshl_add_u64 v[220:221], v[56:57], 0, s[100:101]
	global_load_dwordx4 v[240:243], v[220:221], off
	s_nop 0
	v_lshrrev_b32_e32 v1, 4, v0
	v_and_b32_e32 v0, 15, v0
	v_mul_lo_u32 v1, v1, s15
	v_lshlrev_b32_e32 v2, 3, v0
	v_cvt_f32_ubyte0_e32 v0, v0
	v_add3_u32 v86, v159, v1, v2
	v_mul_f32_e32 v0, 0xbb800000, v0
	v_mul_f32_e32 v0, 0.5, v0
	v_add_u32_e32 v232, 0x800, v86
	v_add_u32_e32 v233, 0xc00, v86
	ds_read2_b64 v[166:169], v86 offset1:17
	ds_read2_b64 v[170:173], v86 offset0:34 offset1:51
	ds_read2_b64 v[174:177], v86 offset0:68 offset1:85
	ds_read2_b64 v[178:181], v86 offset0:102 offset1:119
	ds_read2_b64 v[182:185], v86 offset0:136 offset1:153
	ds_read2_b64 v[186:189], v86 offset0:170 offset1:187
	ds_read2_b64 v[190:193], v86 offset0:204 offset1:221
	ds_read2_b64 v[194:197], v86 offset0:238 offset1:255
	ds_read2_b64 v[198:201], v232 offset0:16 offset1:33
	ds_read2_b64 v[202:205], v232 offset0:50 offset1:67
	ds_read2_b64 v[208:211], v232 offset0:84 offset1:101
	ds_read2_b64 v[214:217], v232 offset0:118 offset1:135
	ds_read2_b64 v[218:221], v232 offset0:152 offset1:169
	v_sin_f32_e32 v1, v0
	v_cos_f32_e32 v0, v0
	s_waitcnt lgkmcnt(12)
	v_pk_mul_f32 v[2:3], v[166:167], v[66:67] op_sel:[1,1] op_sel_hi:[1,0]
	v_pk_fma_f32 v[4:5], v[166:167], v[66:67], v[2:3] op_sel_hi:[0,1,1] neg_hi:[1,0,0]
	v_add_u32_e32 v87, 0x800, v86
	v_pk_mul_f32 v[2:3], v[66:67], v[0:1] op_sel:[1,1] op_sel_hi:[1,0] neg_lo:[1,0]
	v_pk_fma_f32 v[8:9], v[66:67], v[0:1], v[2:3] op_sel_hi:[0,1,1]
	v_pk_mul_f32 v[10:11], v[168:169], v[8:9] op_sel:[1,1] op_sel_hi:[1,0]
	v_pk_fma_f32 v[2:3], v[168:169], v[8:9], v[10:11] op_sel_hi:[0,1,1] neg_hi:[1,0,0]
	v_pk_mul_f32 v[6:7], v[8:9], v[0:1] op_sel:[1,1] op_sel_hi:[1,0] neg_lo:[1,0]
	v_pk_fma_f32 v[12:13], v[8:9], v[0:1], v[6:7] op_sel_hi:[0,1,1]
	ds_read2_b64 v[166:169], v232 offset0:186 offset1:203
	s_waitcnt lgkmcnt(12)
; #define SINCOSPI(x, s, c) do { const float hx_ = 0.5f * (x); *(s) = __builtin_amdgcn_sinf(hx_); *(c) = __builtin_amdgcn_cosf(hx_); } while (0)
; DEV void fft_i2(LAS cf* buf, int t8) {
;     ...
;     float sn, cs; SINCOSPI(-(float)(t8 & 15) * (2.0f / 512.0f), &sn, &cs);
;     const cf w = cf{cs, sn}; cf wp = cf{1.f, 0.f};
;     cf v[32];
; #pragma unroll
;     for (int p = 0; p < 32; ++p) { v[p] = cmulc(pb[17 * p], wp); wp = cmul(wp, w); }
	v_pk_mul_f32 v[14:15], v[170:171], v[12:13] op_sel:[1,1] op_sel_hi:[1,0]
	v_pk_fma_f32 v[10:11], v[170:171], v[12:13], v[14:15] op_sel_hi:[0,1,1] neg_hi:[1,0,0]
	v_pk_mul_f32 v[6:7], v[12:13], v[0:1] op_sel:[1,1] op_sel_hi:[1,0] neg_lo:[1,0]
	v_pk_fma_f32 v[12:13], v[12:13], v[0:1], v[6:7] op_sel_hi:[0,1,1]
	v_pk_mul_f32 v[14:15], v[172:173], v[12:13] op_sel:[1,1] op_sel_hi:[1,0]
	v_pk_fma_f32 v[6:7], v[172:173], v[12:13], v[14:15] op_sel_hi:[0,1,1] neg_hi:[1,0,0]
	v_pk_mul_f32 v[8:9], v[12:13], v[0:1] op_sel:[1,1] op_sel_hi:[1,0] neg_lo:[1,0]
	v_pk_fma_f32 v[16:17], v[12:13], v[0:1], v[8:9] op_sel_hi:[0,1,1]
	ds_read2_b64 v[170:173], v232 offset0:220 offset1:237
	s_waitcnt lgkmcnt(12)
	v_pk_mul_f32 v[8:9], v[174:175], v[16:17] op_sel:[1,1] op_sel_hi:[1,0]
	v_pk_fma_f32 v[12:13], v[174:175], v[16:17], v[8:9] op_sel_hi:[0,1,1] neg_hi:[1,0,0]
	s_nop 0
	v_pk_mul_f32 v[8:9], v[16:17], v[0:1] op_sel:[1,1] op_sel_hi:[1,0] neg_lo:[1,0]
	v_pk_fma_f32 v[16:17], v[16:17], v[0:1], v[8:9] op_sel_hi:[0,1,1]
	v_pk_mul_f32 v[18:19], v[176:177], v[16:17] op_sel:[1,1] op_sel_hi:[1,0]
	v_pk_fma_f32 v[8:9], v[176:177], v[16:17], v[18:19] op_sel_hi:[0,1,1] neg_hi:[1,0,0]
	v_pk_mul_f32 v[14:15], v[16:17], v[0:1] op_sel:[1,1] op_sel_hi:[1,0] neg_lo:[1,0]
	v_pk_fma_f32 v[68:69], v[16:17], v[0:1], v[14:15] op_sel_hi:[0,1,1]
	ds_read2_b64 v[174:177], v233 offset0:126 offset1:143
	s_waitcnt lgkmcnt(12)
	v_pk_mul_f32 v[14:15], v[178:179], v[68:69] op_sel:[1,1] op_sel_hi:[1,0]
	v_pk_fma_f32 v[16:17], v[178:179], v[68:69], v[14:15] op_sel_hi:[0,1,1] neg_hi:[1,0,0]
	s_nop 0
	v_pk_mul_f32 v[14:15], v[68:69], v[0:1] op_sel:[1,1] op_sel_hi:[1,0] neg_lo:[1,0]
	v_pk_fma_f32 v[68:69], v[68:69], v[0:1], v[14:15] op_sel_hi:[0,1,1]
	v_pk_mul_f32 v[70:71], v[180:181], v[68:69] op_sel:[1,1] op_sel_hi:[1,0]
	v_pk_fma_f32 v[14:15], v[180:181], v[68:69], v[70:71] op_sel_hi:[0,1,1] neg_hi:[1,0,0]
	v_pk_mul_f32 v[18:19], v[68:69], v[0:1] op_sel:[1,1] op_sel_hi:[1,0] neg_lo:[1,0]
	v_pk_fma_f32 v[72:73], v[68:69], v[0:1], v[18:19] op_sel_hi:[0,1,1]
	s_waitcnt lgkmcnt(11)
	v_pk_mul_f32 v[18:19], v[182:183], v[72:73] op_sel:[1,1] op_sel_hi:[1,0]
	v_pk_fma_f32 v[68:69], v[182:183], v[72:73], v[18:19] op_sel_hi:[0,1,1] neg_hi:[1,0,0]
	s_nop 0
	v_pk_mul_f32 v[18:19], v[72:73], v[0:1] op_sel:[1,1] op_sel_hi:[1,0] neg_lo:[1,0]
	v_pk_fma_f32 v[72:73], v[72:73], v[0:1], v[18:19] op_sel_hi:[0,1,1]
	v_pk_mul_f32 v[74:75], v[184:185], v[72:73] op_sel:[1,1] op_sel_hi:[1,0]
	v_pk_fma_f32 v[18:19], v[184:185], v[72:73], v[74:75] op_sel_hi:[0,1,1] neg_hi:[1,0,0]
	v_pk_mul_f32 v[70:71], v[72:73], v[0:1] op_sel:[1,1] op_sel_hi:[1,0] neg_lo:[1,0]
	v_pk_fma_f32 v[76:77], v[72:73], v[0:1], v[70:71] op_sel_hi:[0,1,1]
	s_waitcnt lgkmcnt(10)
	v_pk_mul_f32 v[70:71], v[186:187], v[76:77] op_sel:[1,1] op_sel_hi:[1,0]
	v_pk_fma_f32 v[72:73], v[186:187], v[76:77], v[70:71] op_sel_hi:[0,1,1] neg_hi:[1,0,0]
	s_nop 0
	v_pk_mul_f32 v[70:71], v[76:77], v[0:1] op_sel:[1,1] op_sel_hi:[1,0] neg_lo:[1,0]
	v_pk_fma_f32 v[76:77], v[76:77], v[0:1], v[70:71] op_sel_hi:[0,1,1]
	v_pk_mul_f32 v[78:79], v[188:189], v[76:77] op_sel:[1,1] op_sel_hi:[1,0]
	v_pk_fma_f32 v[70:71], v[188:189], v[76:77], v[78:79] op_sel_hi:[0,1,1] neg_hi:[1,0,0]
	v_pk_mul_f32 v[74:75], v[76:77], v[0:1] op_sel:[1,1] op_sel_hi:[1,0] neg_lo:[1,0]
	v_pk_fma_f32 v[80:81], v[76:77], v[0:1], v[74:75] op_sel_hi:[0,1,1]
	s_waitcnt lgkmcnt(9)
	v_pk_mul_f32 v[74:75], v[190:191], v[80:81] op_sel:[1,1] op_sel_hi:[1,0]
	v_pk_fma_f32 v[76:77], v[190:191], v[80:81], v[74:75] op_sel_hi:[0,1,1] neg_hi:[1,0,0]
	s_nop 0
	v_pk_mul_f32 v[74:75], v[80:81], v[0:1] op_sel:[1,1] op_sel_hi:[1,0] neg_lo:[1,0]
	v_pk_fma_f32 v[80:81], v[80:81], v[0:1], v[74:75] op_sel_hi:[0,1,1]
	v_pk_mul_f32 v[82:83], v[192:193], v[80:81] op_sel:[1,1] op_sel_hi:[1,0]
	v_pk_fma_f32 v[74:75], v[192:193], v[80:81], v[82:83] op_sel_hi:[0,1,1] neg_hi:[1,0,0]
	v_pk_mul_f32 v[78:79], v[80:81], v[0:1] op_sel:[1,1] op_sel_hi:[1,0] neg_lo:[1,0]
	v_pk_fma_f32 v[84:85], v[80:81], v[0:1], v[78:79] op_sel_hi:[0,1,1]
	s_waitcnt lgkmcnt(8)
	v_pk_mul_f32 v[78:79], v[194:195], v[84:85] op_sel:[1,1] op_sel_hi:[1,0]
	v_pk_fma_f32 v[80:81], v[194:195], v[84:85], v[78:79] op_sel_hi:[0,1,1] neg_hi:[1,0,0]
	s_nop 0
	v_pk_mul_f32 v[78:79], v[84:85], v[0:1] op_sel:[1,1] op_sel_hi:[1,0] neg_lo:[1,0]
	v_pk_fma_f32 v[84:85], v[84:85], v[0:1], v[78:79] op_sel_hi:[0,1,1]
	v_pk_mul_f32 v[88:89], v[196:197], v[84:85] op_sel:[1,1] op_sel_hi:[1,0]
	v_pk_fma_f32 v[78:79], v[196:197], v[84:85], v[88:89] op_sel_hi:[0,1,1] neg_hi:[1,0,0]
	v_pk_mul_f32 v[82:83], v[84:85], v[0:1] op_sel:[1,1] op_sel_hi:[1,0] neg_lo:[1,0]
	v_pk_fma_f32 v[92:93], v[84:85], v[0:1], v[82:83] op_sel_hi:[0,1,1]
	s_waitcnt lgkmcnt(7)
	v_pk_mul_f32 v[82:83], v[198:199], v[92:93] op_sel:[1,1] op_sel_hi:[1,0]
	v_pk_fma_f32 v[84:85], v[198:199], v[92:93], v[82:83] op_sel_hi:[0,1,1] neg_hi:[1,0,0]
	s_nop 0
	v_pk_mul_f32 v[82:83], v[92:93], v[0:1] op_sel:[1,1] op_sel_hi:[1,0] neg_lo:[1,0]
	v_pk_fma_f32 v[88:89], v[92:93], v[0:1], v[82:83] op_sel_hi:[0,1,1]
	v_pk_mul_f32 v[92:93], v[200:201], v[88:89] op_sel:[1,1] op_sel_hi:[1,0]
	v_pk_fma_f32 v[82:83], v[200:201], v[88:89], v[92:93] op_sel_hi:[0,1,1] neg_hi:[1,0,0]
	s_nop 0
	v_pk_mul_f32 v[90:91], v[88:89], v[0:1] op_sel:[1,1] op_sel_hi:[1,0] neg_lo:[1,0]
	v_pk_fma_f32 v[92:93], v[88:89], v[0:1], v[90:91] op_sel_hi:[0,1,1]
	s_waitcnt lgkmcnt(6)
; #define SINCOSPI(x, s, c) do { const float hx_ = 0.5f * (x); *(s) = __builtin_amdgcn_sinf(hx_); *(c) = __builtin_amdgcn_cosf(hx_); } while (0)
; template <int R, bool INV> DEV void dft_regs(cf (&v)[R]) {
; #pragma unroll
;     for (int s = R; s >= 2; s >>= 1) {
;         const int h = s >> 1;
; #pragma unroll
;         for (int b = 0; b < R; b += s) {
; #pragma unroll
;             for (int k = 0; k < h; ++k) {
;                 const cf a = v[b + k], c = v[b + k + h];
;                 v[b + k] = a + c;
;                 const cf d = a - c;
;                 const int m = k * (32 / s);
;                 const float wr = tw_cos(m), wi = INV ? tw_sin(m) : -tw_sin(m);
;                 v[b + k + h] = cf{d.x * wr - d.y * wi, d.x * wi + d.y * wr};
;             }
;         }
;     }
; }
; DEV void fft_i2(LAS cf* buf, int t8) {
;     ...
;     float sn, cs; SINCOSPI(-(float)(t8 & 15) * (2.0f / 512.0f), &sn, &cs);
;     const cf w = cf{cs, sn}; cf wp = cf{1.f, 0.f};
;     cf v[32];
; #pragma unroll
;     for (int p = 0; p < 32; ++p) { v[p] = cmulc(pb[17 * p], wp); wp = cmul(wp, w); }
;     dft_regs<32, true>(v);
	v_pk_mul_f32 v[96:97], v[202:203], v[92:93] op_sel:[1,1] op_sel_hi:[1,0]
	v_pk_fma_f32 v[94:95], v[202:203], v[92:93], v[96:97] op_sel_hi:[0,1,1] neg_hi:[1,0,0]
	v_pk_mul_f32 v[88:89], v[92:93], v[0:1] op_sel:[1,1] op_sel_hi:[1,0] neg_lo:[1,0]
	v_pk_fma_f32 v[92:93], v[92:93], v[0:1], v[88:89] op_sel_hi:[0,1,1]
	v_pk_mul_f32 v[88:89], v[204:205], v[92:93] op_sel:[1,1] op_sel_hi:[1,0]
	v_pk_fma_f32 v[96:97], v[204:205], v[92:93], v[88:89] op_sel_hi:[0,1,1] neg_hi:[1,0,0]
	s_nop 0
	v_pk_mul_f32 v[88:89], v[92:93], v[0:1] op_sel:[1,1] op_sel_hi:[1,0] neg_lo:[1,0]
	v_pk_fma_f32 v[92:93], v[92:93], v[0:1], v[88:89] op_sel_hi:[0,1,1]
	s_waitcnt lgkmcnt(5)
	v_pk_mul_f32 v[100:101], v[208:209], v[92:93] op_sel:[1,1] op_sel_hi:[1,0]
	v_pk_fma_f32 v[98:99], v[208:209], v[92:93], v[100:101] op_sel_hi:[0,1,1] neg_hi:[1,0,0]
	v_pk_mul_f32 v[88:89], v[92:93], v[0:1] op_sel:[1,1] op_sel_hi:[1,0] neg_lo:[1,0]
	v_pk_fma_f32 v[92:93], v[92:93], v[0:1], v[88:89] op_sel_hi:[0,1,1]
	v_pk_mul_f32 v[88:89], v[210:211], v[92:93] op_sel:[1,1] op_sel_hi:[1,0]
	v_pk_fma_f32 v[100:101], v[210:211], v[92:93], v[88:89] op_sel_hi:[0,1,1] neg_hi:[1,0,0]
	s_nop 0
	v_pk_mul_f32 v[88:89], v[92:93], v[0:1] op_sel:[1,1] op_sel_hi:[1,0] neg_lo:[1,0]
	v_pk_fma_f32 v[92:93], v[92:93], v[0:1], v[88:89] op_sel_hi:[0,1,1]
	s_waitcnt lgkmcnt(4)
	v_pk_mul_f32 v[104:105], v[214:215], v[92:93] op_sel:[1,1] op_sel_hi:[1,0]
	v_pk_fma_f32 v[102:103], v[214:215], v[92:93], v[104:105] op_sel_hi:[0,1,1] neg_hi:[1,0,0]
	v_pk_mul_f32 v[88:89], v[92:93], v[0:1] op_sel:[1,1] op_sel_hi:[1,0] neg_lo:[1,0]
	v_pk_fma_f32 v[92:93], v[92:93], v[0:1], v[88:89] op_sel_hi:[0,1,1]
	v_pk_mul_f32 v[88:89], v[216:217], v[92:93] op_sel:[1,1] op_sel_hi:[1,0]
	v_pk_fma_f32 v[104:105], v[216:217], v[92:93], v[88:89] op_sel_hi:[0,1,1] neg_hi:[1,0,0]
	s_nop 0
	v_pk_mul_f32 v[88:89], v[92:93], v[0:1] op_sel:[1,1] op_sel_hi:[1,0] neg_lo:[1,0]
	v_pk_fma_f32 v[92:93], v[92:93], v[0:1], v[88:89] op_sel_hi:[0,1,1]
	s_waitcnt lgkmcnt(3)
	v_pk_mul_f32 v[108:109], v[218:219], v[92:93] op_sel:[1,1] op_sel_hi:[1,0]
	v_pk_fma_f32 v[106:107], v[218:219], v[92:93], v[108:109] op_sel_hi:[0,1,1] neg_hi:[1,0,0]
	v_pk_mul_f32 v[88:89], v[92:93], v[0:1] op_sel:[1,1] op_sel_hi:[1,0] neg_lo:[1,0]
	v_pk_fma_f32 v[92:93], v[92:93], v[0:1], v[88:89] op_sel_hi:[0,1,1]
	v_pk_mul_f32 v[88:89], v[220:221], v[92:93] op_sel:[1,1] op_sel_hi:[1,0]
	v_pk_fma_f32 v[108:109], v[220:221], v[92:93], v[88:89] op_sel_hi:[0,1,1] neg_hi:[1,0,0]
	s_nop 0
	v_pk_mul_f32 v[88:89], v[92:93], v[0:1] op_sel:[1,1] op_sel_hi:[1,0] neg_lo:[1,0]
	v_pk_fma_f32 v[92:93], v[92:93], v[0:1], v[88:89] op_sel_hi:[0,1,1]
	s_waitcnt lgkmcnt(2)
	v_pk_mul_f32 v[112:113], v[166:167], v[92:93] op_sel:[1,1] op_sel_hi:[1,0]
	v_pk_fma_f32 v[110:111], v[166:167], v[92:93], v[112:113] op_sel_hi:[0,1,1] neg_hi:[1,0,0]
	v_pk_mul_f32 v[88:89], v[92:93], v[0:1] op_sel:[1,1] op_sel_hi:[1,0] neg_lo:[1,0]
	v_pk_fma_f32 v[92:93], v[92:93], v[0:1], v[88:89] op_sel_hi:[0,1,1]
	v_pk_mul_f32 v[88:89], v[168:169], v[92:93] op_sel:[1,1] op_sel_hi:[1,0]
	v_pk_fma_f32 v[112:113], v[168:169], v[92:93], v[88:89] op_sel_hi:[0,1,1] neg_hi:[1,0,0]
	s_nop 0
	v_pk_mul_f32 v[88:89], v[92:93], v[0:1] op_sel:[1,1] op_sel_hi:[1,0] neg_lo:[1,0]
	v_pk_fma_f32 v[92:93], v[92:93], v[0:1], v[88:89] op_sel_hi:[0,1,1]
	s_waitcnt lgkmcnt(1)
	v_pk_mul_f32 v[116:117], v[170:171], v[92:93] op_sel:[1,1] op_sel_hi:[1,0]
	v_pk_fma_f32 v[114:115], v[170:171], v[92:93], v[116:117] op_sel_hi:[0,1,1] neg_hi:[1,0,0]
	v_pk_mul_f32 v[88:89], v[92:93], v[0:1] op_sel:[1,1] op_sel_hi:[1,0] neg_lo:[1,0]
	v_pk_fma_f32 v[92:93], v[92:93], v[0:1], v[88:89] op_sel_hi:[0,1,1]
	v_pk_mul_f32 v[88:89], v[172:173], v[92:93] op_sel:[1,1] op_sel_hi:[1,0]
	v_pk_fma_f32 v[116:117], v[172:173], v[92:93], v[88:89] op_sel_hi:[0,1,1] neg_hi:[1,0,0]
	s_nop 0
	v_pk_mul_f32 v[88:89], v[92:93], v[0:1] op_sel:[1,1] op_sel_hi:[1,0] neg_lo:[1,0]
	v_pk_fma_f32 v[118:119], v[92:93], v[0:1], v[88:89] op_sel_hi:[0,1,1]
	s_nop 0
	v_add_u32_e32 v88, 0xc00, v86
	v_pk_mul_f32 v[120:121], v[118:119], v[0:1] op_sel:[1,1] op_sel_hi:[1,0] neg_lo:[1,0]
	v_pk_fma_f32 v[0:1], v[118:119], v[0:1], v[120:121] op_sel_hi:[0,1,1]
	s_waitcnt lgkmcnt(0)
	v_pk_mul_f32 v[120:121], v[174:175], v[118:119] op_sel:[1,1] op_sel_hi:[1,0]
	v_pk_fma_f32 v[90:91], v[174:175], v[118:119], v[120:121] op_sel_hi:[0,1,1] neg_hi:[1,0,0]
	v_pk_mul_f32 v[118:119], v[176:177], v[0:1] op_sel:[1,1] op_sel_hi:[1,0]
	v_pk_fma_f32 v[0:1], v[176:177], v[0:1], v[118:119] op_sel_hi:[0,1,1] neg_hi:[1,0,0]
	v_pk_add_f32 v[92:93], v[4:5], v[84:85]
	v_pk_add_f32 v[4:5], v[4:5], v[84:85] neg_lo:[0,1] neg_hi:[0,1]
	v_mov_b32_e32 v118, v4
	v_mov_b32_e32 v119, v5
	v_pk_add_f32 v[4:5], v[2:3], v[82:83]
	v_pk_add_f32 v[2:3], v[2:3], v[82:83] neg_lo:[0,1] neg_hi:[0,1]
	v_pk_mul_f32 v[82:83], v[2:3], s[82:83] op_sel_hi:[1,0]
	v_pk_fma_f32 v[84:85], v[2:3], s[94:95], v[82:83] op_sel:[0,0,1] op_sel_hi:[1,0,0] neg_lo:[0,0,1] neg_hi:[0,0,1]
	v_pk_fma_f32 v[2:3], v[2:3], s[94:95], v[82:83] op_sel:[0,0,1] op_sel_hi:[1,0,0]
	v_mov_b32_e32 v85, v3
	v_pk_add_f32 v[2:3], v[10:11], v[94:95]
	v_pk_add_f32 v[10:11], v[10:11], v[94:95] neg_lo:[0,1] neg_hi:[0,1]
	v_pk_mul_f32 v[82:83], v[10:11], s[84:85] op_sel_hi:[1,0]
	v_pk_fma_f32 v[94:95], v[10:11], s[16:17], v[82:83] op_sel:[0,0,1] op_sel_hi:[1,0,0] neg_lo:[0,0,1] neg_hi:[0,0,1]
	v_pk_fma_f32 v[10:11], v[10:11], s[16:17], v[82:83] op_sel:[0,0,1] op_sel_hi:[1,0,0]
	v_mov_b32_e32 v95, v11
	v_pk_add_f32 v[10:11], v[6:7], v[96:97]
	v_pk_add_f32 v[6:7], v[6:7], v[96:97] neg_lo:[0,1] neg_hi:[0,1]
	v_pk_mul_f32 v[82:83], v[6:7], s[4:5] op_sel_hi:[1,0]
; template <int R, bool INV> DEV void dft_regs(cf (&v)[R]) {
; #pragma unroll
;     for (int s = R; s >= 2; s >>= 1) {
;         const int h = s >> 1;
; #pragma unroll
;         for (int b = 0; b < R; b += s) {
; #pragma unroll
;             for (int k = 0; k < h; ++k) {
;                 const cf a = v[b + k], c = v[b + k + h];
;                 v[b + k] = a + c;
;                 const cf d = a - c;
;                 const int m = k * (32 / s);
;                 const float wr = tw_cos(m), wi = INV ? tw_sin(m) : -tw_sin(m);
;                 v[b + k + h] = cf{d.x * wr - d.y * wi, d.x * wi + d.y * wr};
;             }
;         }
;     }
; }
	v_pk_fma_f32 v[96:97], v[6:7], s[86:87], v[82:83] op_sel:[0,0,1] op_sel_hi:[1,0,0] neg_lo:[0,0,1] neg_hi:[0,0,1]
	v_pk_fma_f32 v[6:7], v[6:7], s[86:87], v[82:83] op_sel:[0,0,1] op_sel_hi:[1,0,0]
	v_mov_b32_e32 v97, v7
	v_pk_add_f32 v[6:7], v[12:13], v[98:99]
	v_pk_add_f32 v[12:13], v[12:13], v[98:99] neg_lo:[0,1] neg_hi:[0,1]
	v_pk_mul_f32 v[82:83], v[12:13], s[18:19] op_sel_hi:[1,0]
	v_pk_fma_f32 v[98:99], v[12:13], s[18:19], v[82:83] op_sel:[0,0,1] op_sel_hi:[1,0,0] neg_lo:[0,0,1] neg_hi:[0,0,1]
	v_pk_fma_f32 v[12:13], v[12:13], s[18:19], v[82:83] op_sel_hi:[1,0,0]
	v_mov_b32_e32 v99, v13
	v_pk_add_f32 v[12:13], v[8:9], v[100:101]
	v_pk_add_f32 v[8:9], v[8:9], v[100:101] neg_lo:[0,1] neg_hi:[0,1]
	v_pk_mul_f32 v[82:83], v[8:9], s[86:87] op_sel_hi:[1,0]
	v_pk_fma_f32 v[100:101], v[8:9], s[4:5], v[82:83] op_sel:[0,0,1] op_sel_hi:[1,0,0] neg_lo:[0,0,1] neg_hi:[0,0,1]
	v_pk_fma_f32 v[8:9], v[8:9], s[4:5], v[82:83] op_sel:[0,0,1] op_sel_hi:[1,0,0]
	v_mov_b32_e32 v101, v9
	v_pk_add_f32 v[8:9], v[16:17], v[102:103]
	v_pk_add_f32 v[16:17], v[16:17], v[102:103] neg_lo:[0,1] neg_hi:[0,1]
	v_pk_mul_f32 v[82:83], v[16:17], s[16:17] op_sel_hi:[1,0]
	v_pk_fma_f32 v[102:103], v[16:17], s[84:85], v[82:83] op_sel:[0,0,1] op_sel_hi:[1,0,0] neg_lo:[0,0,1] neg_hi:[0,0,1]
	v_pk_fma_f32 v[16:17], v[16:17], s[84:85], v[82:83] op_sel:[0,0,1] op_sel_hi:[1,0,0]
	v_mov_b32_e32 v103, v17
	v_pk_add_f32 v[16:17], v[14:15], v[104:105]
	v_pk_add_f32 v[14:15], v[14:15], v[104:105] neg_lo:[0,1] neg_hi:[0,1]
	v_pk_mul_f32 v[82:83], v[14:15], s[94:95] op_sel_hi:[1,0]
	v_pk_fma_f32 v[104:105], v[14:15], s[82:83], v[82:83] op_sel:[0,0,1] op_sel_hi:[1,0,0] neg_lo:[0,0,1] neg_hi:[0,0,1]
	v_pk_fma_f32 v[14:15], v[14:15], s[82:83], v[82:83] op_sel:[0,0,1] op_sel_hi:[1,0,0]
	v_mov_b32_e32 v105, v15
	v_pk_add_f32 v[14:15], v[68:69], v[106:107]
	v_pk_add_f32 v[68:69], v[68:69], v[106:107] neg_lo:[0,1] neg_hi:[0,1]
	v_pk_add_f32 v[82:83], v[68:69], 0 op_sel:[1,0] op_sel_hi:[0,0] neg_lo:[1,0]
	v_pk_add_f32 v[68:69], v[18:19], v[108:109]
	v_pk_add_f32 v[18:19], v[18:19], v[108:109] neg_lo:[0,1] neg_hi:[0,1]
	v_pk_mul_f32 v[106:107], v[18:19], s[6:7] op_sel:[1,0]
	s_mov_b32 s6, s87
	v_pk_fma_f32 v[18:19], v[18:19], s[28:29], v[106:107] op_sel_hi:[0,1,1] neg_lo:[0,0,1] neg_hi:[0,0,1]
	v_pk_add_f32 v[106:107], v[72:73], v[110:111]
	v_pk_add_f32 v[72:73], v[72:73], v[110:111] neg_lo:[0,1] neg_hi:[0,1]
	s_mov_b32 s7, s86
	v_pk_mul_f32 v[108:109], v[72:73], s[24:25] op_sel:[1,0]
	v_pk_fma_f32 v[72:73], v[72:73], s[0:1], v[108:109] op_sel_hi:[0,1,1] neg_lo:[0,0,1] neg_hi:[0,0,1]
	v_pk_add_f32 v[108:109], v[70:71], v[112:113]
	v_pk_add_f32 v[70:71], v[70:71], v[112:113] neg_lo:[0,1] neg_hi:[0,1]
	v_pk_mul_f32 v[110:111], v[70:71], s[2:3] op_sel:[1,0]
	s_mov_b32 s2, s11
	v_pk_fma_f32 v[70:71], v[70:71], s[6:7], v[110:111] op_sel_hi:[0,1,1] neg_lo:[0,0,1] neg_hi:[0,0,1]
	v_pk_add_f32 v[110:111], v[76:77], v[114:115]
	v_pk_add_f32 v[76:77], v[76:77], v[114:115] neg_lo:[0,1] neg_hi:[0,1]
	v_mul_f32_e32 v112, 0x3f3504f3, v77
	v_pk_fma_f32 v[76:77], v[76:77], s[96:97], v[112:113] op_sel_hi:[0,1,0] neg_lo:[0,0,1] neg_hi:[0,0,1]
	v_pk_add_f32 v[112:113], v[74:75], v[116:117]
	v_pk_add_f32 v[74:75], v[74:75], v[116:117] neg_lo:[0,1] neg_hi:[0,1]
	v_pk_mul_f32 v[114:115], v[74:75], s[4:5] op_sel:[1,0]
	s_lshl_b32 s5, s19, 10
	v_pk_fma_f32 v[74:75], v[74:75], s[2:3], v[114:115] op_sel_hi:[0,1,1] neg_lo:[0,0,1] neg_hi:[0,0,1]
	v_pk_add_f32 v[114:115], v[80:81], v[90:91]
	v_pk_add_f32 v[80:81], v[80:81], v[90:91] neg_lo:[0,1] neg_hi:[0,1]
	s_mov_b32 s2, s9
	v_pk_mul_f32 v[90:91], v[80:81], s[84:85] op_sel:[1,0]
	s_mov_b32 s3, s82
	v_pk_fma_f32 v[80:81], v[80:81], s[88:89], v[90:91] op_sel_hi:[0,1,1] neg_lo:[0,0,1] neg_hi:[0,0,1]
	v_pk_add_f32 v[90:91], v[78:79], v[0:1]
	v_pk_add_f32 v[0:1], v[78:79], v[0:1] neg_lo:[0,1] neg_hi:[0,1]
	s_add_i32 s6, s79, s5
	v_pk_mul_f32 v[78:79], v[0:1], s[82:83] op_sel:[1,0]
	s_ashr_i32 s7, s6, 31
	v_pk_fma_f32 v[0:1], v[0:1], s[2:3], v[78:79] op_sel_hi:[0,1,1] neg_lo:[0,0,1] neg_hi:[0,0,1]
	v_pk_add_f32 v[78:79], v[92:93], v[14:15]
	v_pk_add_f32 v[14:15], v[92:93], v[14:15] neg_lo:[0,1] neg_hi:[0,1]
	s_lshl_b64 s[2:3], s[6:7], 13
	v_mov_b32_e32 v116, v14
	v_mov_b32_e32 v117, v15
	v_pk_add_f32 v[14:15], v[4:5], v[68:69]
	v_pk_add_f32 v[4:5], v[4:5], v[68:69] neg_lo:[0,1] neg_hi:[0,1]
	v_pk_mul_f32 v[68:69], v[4:5], s[84:85] op_sel_hi:[1,0]
	v_pk_fma_f32 v[92:93], v[4:5], s[16:17], v[68:69] op_sel:[0,0,1] op_sel_hi:[1,0,0] neg_lo:[0,0,1] neg_hi:[0,0,1]
	v_pk_fma_f32 v[4:5], v[4:5], s[16:17], v[68:69] op_sel:[0,0,1] op_sel_hi:[1,0,0]
	v_mov_b32_e32 v93, v5
	v_pk_add_f32 v[4:5], v[2:3], v[106:107]
	v_pk_add_f32 v[2:3], v[2:3], v[106:107] neg_lo:[0,1] neg_hi:[0,1]
	v_pk_mul_f32 v[68:69], v[2:3], s[18:19] op_sel_hi:[1,0]
	v_pk_fma_f32 v[106:107], v[2:3], s[18:19], v[68:69] op_sel:[0,0,1] op_sel_hi:[1,0,0] neg_lo:[0,0,1] neg_hi:[0,0,1]
	v_pk_fma_f32 v[2:3], v[2:3], s[18:19], v[68:69] op_sel_hi:[1,0,0]
	v_mov_b32_e32 v107, v3
	v_pk_add_f32 v[2:3], v[10:11], v[108:109]
	v_pk_add_f32 v[10:11], v[10:11], v[108:109] neg_lo:[0,1] neg_hi:[0,1]
	v_pk_mul_f32 v[68:69], v[10:11], s[16:17] op_sel_hi:[1,0]
	v_pk_fma_f32 v[108:109], v[10:11], s[84:85], v[68:69] op_sel:[0,0,1] op_sel_hi:[1,0,0] neg_lo:[0,0,1] neg_hi:[0,0,1]
	v_pk_fma_f32 v[10:11], v[10:11], s[84:85], v[68:69] op_sel:[0,0,1] op_sel_hi:[1,0,0]
	v_mov_b32_e32 v109, v11
	v_pk_add_f32 v[10:11], v[6:7], v[110:111]
	v_pk_add_f32 v[6:7], v[6:7], v[110:111] neg_lo:[0,1] neg_hi:[0,1]
	v_pk_add_f32 v[68:69], v[6:7], 0 op_sel:[1,0] op_sel_hi:[0,0] neg_lo:[1,0]
	v_pk_add_f32 v[6:7], v[12:13], v[112:113]
; template <int R, bool INV> DEV void dft_regs(cf (&v)[R]) {
; #pragma unroll
;     for (int s = R; s >= 2; s >>= 1) {
;         const int h = s >> 1;
; #pragma unroll
;         for (int b = 0; b < R; b += s) {
; #pragma unroll
;             for (int k = 0; k < h; ++k) {
;                 const cf a = v[b + k], c = v[b + k + h];
;                 v[b + k] = a + c;
;                 const cf d = a - c;
;                 const int m = k * (32 / s);
;                 const float wr = tw_cos(m), wi = INV ? tw_sin(m) : -tw_sin(m);
;                 v[b + k + h] = cf{d.x * wr - d.y * wi, d.x * wi + d.y * wr};
;             }
;         }
;     }
; }
	v_pk_add_f32 v[12:13], v[12:13], v[112:113] neg_lo:[0,1] neg_hi:[0,1]
	v_pk_mul_f32 v[110:111], v[12:13], s[24:25] op_sel:[1,0]
	v_pk_fma_f32 v[12:13], v[12:13], s[0:1], v[110:111] op_sel_hi:[0,1,1] neg_lo:[0,0,1] neg_hi:[0,0,1]
	v_pk_add_f32 v[110:111], v[8:9], v[114:115]
	v_pk_add_f32 v[8:9], v[8:9], v[114:115] neg_lo:[0,1] neg_hi:[0,1]
	v_mul_f32_e32 v112, 0x3f3504f3, v9
	v_pk_fma_f32 v[8:9], v[8:9], s[96:97], v[112:113] op_sel_hi:[0,1,0] neg_lo:[0,0,1] neg_hi:[0,0,1]
	v_pk_add_f32 v[112:113], v[16:17], v[90:91]
	v_pk_add_f32 v[16:17], v[16:17], v[90:91] neg_lo:[0,1] neg_hi:[0,1]
	v_pk_mul_f32 v[90:91], v[16:17], s[84:85] op_sel:[1,0]
	v_pk_fma_f32 v[16:17], v[16:17], s[88:89], v[90:91] op_sel_hi:[0,1,1] neg_lo:[0,0,1] neg_hi:[0,0,1]
	v_pk_add_f32 v[90:91], v[118:119], v[82:83]
	v_pk_add_f32 v[82:83], v[118:119], v[82:83] neg_lo:[0,1] neg_hi:[0,1]
	v_mov_b32_e32 v118, v82
	v_mov_b32_e32 v119, v83
	v_pk_add_f32 v[82:83], v[84:85], v[18:19]
	v_pk_add_f32 v[18:19], v[84:85], v[18:19] neg_lo:[0,1] neg_hi:[0,1]
	v_pk_mul_f32 v[84:85], v[18:19], s[84:85] op_sel_hi:[1,0]
	v_pk_fma_f32 v[114:115], v[18:19], s[16:17], v[84:85] op_sel:[0,0,1] op_sel_hi:[1,0,0] neg_lo:[0,0,1] neg_hi:[0,0,1]
	v_pk_fma_f32 v[18:19], v[18:19], s[16:17], v[84:85] op_sel:[0,0,1] op_sel_hi:[1,0,0]
	v_mov_b32_e32 v115, v19
	v_pk_add_f32 v[18:19], v[94:95], v[72:73]
	v_pk_add_f32 v[72:73], v[94:95], v[72:73] neg_lo:[0,1] neg_hi:[0,1]
	v_pk_mul_f32 v[84:85], v[72:73], s[18:19] op_sel_hi:[1,0]
	v_pk_fma_f32 v[94:95], v[72:73], s[18:19], v[84:85] op_sel:[0,0,1] op_sel_hi:[1,0,0] neg_lo:[0,0,1] neg_hi:[0,0,1]
	v_pk_fma_f32 v[72:73], v[72:73], s[18:19], v[84:85] op_sel_hi:[1,0,0]
	v_mov_b32_e32 v95, v73
	v_pk_add_f32 v[72:73], v[96:97], v[70:71]
	v_pk_add_f32 v[70:71], v[96:97], v[70:71] neg_lo:[0,1] neg_hi:[0,1]
	v_pk_mul_f32 v[84:85], v[70:71], s[16:17] op_sel_hi:[1,0]
	v_pk_fma_f32 v[96:97], v[70:71], s[84:85], v[84:85] op_sel:[0,0,1] op_sel_hi:[1,0,0] neg_lo:[0,0,1] neg_hi:[0,0,1]
	v_pk_fma_f32 v[70:71], v[70:71], s[84:85], v[84:85] op_sel:[0,0,1] op_sel_hi:[1,0,0]
	v_mov_b32_e32 v97, v71
	v_pk_add_f32 v[70:71], v[98:99], v[76:77]
	v_pk_add_f32 v[76:77], v[98:99], v[76:77] neg_lo:[0,1] neg_hi:[0,1]
	v_pk_add_f32 v[84:85], v[76:77], 0 op_sel:[1,0] op_sel_hi:[0,0] neg_lo:[1,0]
	v_pk_add_f32 v[76:77], v[100:101], v[74:75]
	v_pk_add_f32 v[74:75], v[100:101], v[74:75] neg_lo:[0,1] neg_hi:[0,1]
	v_pk_mul_f32 v[98:99], v[74:75], s[24:25] op_sel:[1,0]
	v_pk_fma_f32 v[74:75], v[74:75], s[0:1], v[98:99] op_sel_hi:[0,1,1] neg_lo:[0,0,1] neg_hi:[0,0,1]
	v_pk_add_f32 v[98:99], v[102:103], v[80:81]
	v_pk_add_f32 v[80:81], v[102:103], v[80:81] neg_lo:[0,1] neg_hi:[0,1]
	v_mul_f32_e32 v100, 0x3f3504f3, v81
	v_pk_fma_f32 v[80:81], v[80:81], s[96:97], v[100:101] op_sel_hi:[0,1,0] neg_lo:[0,0,1] neg_hi:[0,0,1]
	v_pk_add_f32 v[100:101], v[104:105], v[0:1]
	v_pk_add_f32 v[0:1], v[104:105], v[0:1] neg_lo:[0,1] neg_hi:[0,1]
	v_pk_mul_f32 v[102:103], v[0:1], s[84:85] op_sel:[1,0]
	v_pk_fma_f32 v[0:1], v[0:1], s[88:89], v[102:103] op_sel_hi:[0,1,1] neg_lo:[0,0,1] neg_hi:[0,0,1]
	v_pk_add_f32 v[102:103], v[78:79], v[10:11]
	v_pk_add_f32 v[10:11], v[78:79], v[10:11] neg_lo:[0,1] neg_hi:[0,1]
	v_mov_b32_e32 v104, v10
	v_mov_b32_e32 v105, v11
	v_pk_add_f32 v[10:11], v[14:15], v[6:7]
	v_pk_add_f32 v[6:7], v[14:15], v[6:7] neg_lo:[0,1] neg_hi:[0,1]
	v_pk_mul_f32 v[14:15], v[6:7], s[18:19] op_sel_hi:[1,0]
	v_pk_fma_f32 v[78:79], v[6:7], s[18:19], v[14:15] op_sel:[0,0,1] op_sel_hi:[1,0,0] neg_lo:[0,0,1] neg_hi:[0,0,1]
	v_pk_fma_f32 v[6:7], v[6:7], s[18:19], v[14:15] op_sel_hi:[1,0,0]
	v_mov_b32_e32 v79, v7
	v_pk_add_f32 v[6:7], v[4:5], v[110:111]
	v_pk_add_f32 v[4:5], v[4:5], v[110:111] neg_lo:[0,1] neg_hi:[0,1]
	v_pk_add_f32 v[14:15], v[4:5], 0 op_sel:[1,0] op_sel_hi:[0,0] neg_lo:[1,0]
	v_pk_add_f32 v[4:5], v[2:3], v[112:113]
	v_pk_add_f32 v[2:3], v[2:3], v[112:113] neg_lo:[0,1] neg_hi:[0,1]
	v_mul_f32_e32 v110, 0x3f3504f3, v3
	v_pk_fma_f32 v[2:3], v[2:3], s[96:97], v[110:111] op_sel_hi:[0,1,0] neg_lo:[0,0,1] neg_hi:[0,0,1]
	v_pk_add_f32 v[110:111], v[116:117], v[68:69]
	v_pk_add_f32 v[68:69], v[116:117], v[68:69] neg_lo:[0,1] neg_hi:[0,1]
	v_mov_b32_e32 v116, v68
	v_mov_b32_e32 v117, v69
	v_pk_add_f32 v[68:69], v[92:93], v[12:13]
	v_pk_add_f32 v[12:13], v[92:93], v[12:13] neg_lo:[0,1] neg_hi:[0,1]
	v_pk_mul_f32 v[92:93], v[12:13], s[18:19] op_sel_hi:[1,0]
	v_pk_fma_f32 v[112:113], v[12:13], s[18:19], v[92:93] op_sel:[0,0,1] op_sel_hi:[1,0,0] neg_lo:[0,0,1] neg_hi:[0,0,1]
	v_pk_fma_f32 v[12:13], v[12:13], s[18:19], v[92:93] op_sel_hi:[1,0,0]
	v_mov_b32_e32 v113, v13
	v_pk_add_f32 v[12:13], v[106:107], v[8:9]
	v_pk_add_f32 v[8:9], v[106:107], v[8:9] neg_lo:[0,1] neg_hi:[0,1]
	v_pk_add_f32 v[92:93], v[8:9], 0 op_sel:[1,0] op_sel_hi:[0,0] neg_lo:[1,0]
	v_pk_add_f32 v[8:9], v[108:109], v[16:17]
	v_pk_add_f32 v[16:17], v[108:109], v[16:17] neg_lo:[0,1] neg_hi:[0,1]
	v_mul_f32_e32 v106, 0x3f3504f3, v17
	v_pk_fma_f32 v[16:17], v[16:17], s[96:97], v[106:107] op_sel_hi:[0,1,0] neg_lo:[0,0,1] neg_hi:[0,0,1]
	v_pk_add_f32 v[106:107], v[90:91], v[70:71]
	v_pk_add_f32 v[70:71], v[90:91], v[70:71] neg_lo:[0,1] neg_hi:[0,1]
	v_mov_b32_e32 v108, v70
	v_mov_b32_e32 v109, v71
	v_pk_add_f32 v[70:71], v[82:83], v[76:77]
	v_pk_add_f32 v[76:77], v[82:83], v[76:77] neg_lo:[0,1] neg_hi:[0,1]
	v_pk_mul_f32 v[82:83], v[76:77], s[18:19] op_sel_hi:[1,0]
	v_pk_fma_f32 v[90:91], v[76:77], s[18:19], v[82:83] op_sel:[0,0,1] op_sel_hi:[1,0,0] neg_lo:[0,0,1] neg_hi:[0,0,1]
	v_pk_fma_f32 v[76:77], v[76:77], s[18:19], v[82:83] op_sel_hi:[1,0,0]
	v_mov_b32_e32 v91, v77
	v_pk_add_f32 v[76:77], v[18:19], v[98:99]
; template <int R, bool INV> DEV void dft_regs(cf (&v)[R]) {
; #pragma unroll
;     for (int s = R; s >= 2; s >>= 1) {
;         const int h = s >> 1;
; #pragma unroll
;         for (int b = 0; b < R; b += s) {
; #pragma unroll
;             for (int k = 0; k < h; ++k) {
;                 const cf a = v[b + k], c = v[b + k + h];
;                 v[b + k] = a + c;
;                 const cf d = a - c;
;                 const int m = k * (32 / s);
;                 const float wr = tw_cos(m), wi = INV ? tw_sin(m) : -tw_sin(m);
;                 v[b + k + h] = cf{d.x * wr - d.y * wi, d.x * wi + d.y * wr};
;             }
;         }
;     }
; }
	v_pk_add_f32 v[18:19], v[18:19], v[98:99] neg_lo:[0,1] neg_hi:[0,1]
	v_pk_add_f32 v[82:83], v[18:19], 0 op_sel:[1,0] op_sel_hi:[0,0] neg_lo:[1,0]
	v_pk_add_f32 v[18:19], v[72:73], v[100:101]
	v_pk_add_f32 v[72:73], v[72:73], v[100:101] neg_lo:[0,1] neg_hi:[0,1]
	v_mul_f32_e32 v98, 0x3f3504f3, v73
	v_pk_fma_f32 v[72:73], v[72:73], s[96:97], v[98:99] op_sel_hi:[0,1,0] neg_lo:[0,0,1] neg_hi:[0,0,1]
	v_pk_add_f32 v[98:99], v[118:119], v[84:85]
	v_pk_add_f32 v[84:85], v[118:119], v[84:85] neg_lo:[0,1] neg_hi:[0,1]
	v_mov_b32_e32 v118, v84
	v_mov_b32_e32 v119, v85
	v_pk_add_f32 v[84:85], v[114:115], v[74:75]
	v_pk_add_f32 v[74:75], v[114:115], v[74:75] neg_lo:[0,1] neg_hi:[0,1]
	v_pk_mul_f32 v[100:101], v[74:75], s[18:19] op_sel_hi:[1,0]
	v_pk_fma_f32 v[114:115], v[74:75], s[18:19], v[100:101] op_sel:[0,0,1] op_sel_hi:[1,0,0] neg_lo:[0,0,1] neg_hi:[0,0,1]
	v_pk_fma_f32 v[74:75], v[74:75], s[18:19], v[100:101] op_sel_hi:[1,0,0]
	v_mov_b32_e32 v115, v75
	v_pk_add_f32 v[74:75], v[94:95], v[80:81]
	v_pk_add_f32 v[80:81], v[94:95], v[80:81] neg_lo:[0,1] neg_hi:[0,1]
	v_pk_add_f32 v[94:95], v[80:81], 0 op_sel:[1,0] op_sel_hi:[0,0] neg_lo:[1,0]
	v_pk_add_f32 v[80:81], v[96:97], v[0:1]
	v_pk_add_f32 v[0:1], v[96:97], v[0:1] neg_lo:[0,1] neg_hi:[0,1]
	v_mul_f32_e32 v96, 0x3f3504f3, v1
	v_pk_fma_f32 v[0:1], v[0:1], s[96:97], v[96:97] op_sel_hi:[0,1,0] neg_lo:[0,0,1] neg_hi:[0,0,1]
	v_pk_add_f32 v[96:97], v[102:103], v[6:7]
	v_pk_add_f32 v[6:7], v[102:103], v[6:7] neg_lo:[0,1] neg_hi:[0,1]
	v_mov_b32_e32 v102, v6
	v_mov_b32_e32 v103, v7
	v_pk_add_f32 v[6:7], v[10:11], v[4:5]
	v_pk_add_f32 v[4:5], v[10:11], v[4:5] neg_lo:[0,1] neg_hi:[0,1]
	v_pk_add_f32 v[10:11], v[4:5], 0 op_sel:[1,0] op_sel_hi:[0,0] neg_lo:[1,0]
	v_pk_add_f32 v[4:5], v[104:105], v[14:15]
	v_pk_add_f32 v[14:15], v[104:105], v[14:15] neg_lo:[0,1] neg_hi:[0,1]
	v_mov_b32_e32 v104, v14
	v_mov_b32_e32 v105, v15
	v_pk_add_f32 v[14:15], v[78:79], v[2:3]
	v_pk_add_f32 v[2:3], v[78:79], v[2:3] neg_lo:[0,1] neg_hi:[0,1]
	v_pk_add_f32 v[78:79], v[2:3], 0 op_sel:[1,0] op_sel_hi:[0,0] neg_lo:[1,0]
	v_pk_add_f32 v[2:3], v[110:111], v[12:13]
	v_pk_add_f32 v[12:13], v[110:111], v[12:13] neg_lo:[0,1] neg_hi:[0,1]
	v_mov_b32_e32 v110, v12
	v_mov_b32_e32 v111, v13
	v_pk_add_f32 v[12:13], v[68:69], v[8:9]
	v_pk_add_f32 v[8:9], v[68:69], v[8:9] neg_lo:[0,1] neg_hi:[0,1]
	v_pk_add_f32 v[68:69], v[8:9], 0 op_sel:[1,0] op_sel_hi:[0,0] neg_lo:[1,0]
	v_pk_add_f32 v[8:9], v[116:117], v[92:93]
	v_pk_add_f32 v[92:93], v[116:117], v[92:93] neg_lo:[0,1] neg_hi:[0,1]
	v_mov_b32_e32 v116, v92
	v_mov_b32_e32 v117, v93
	v_pk_add_f32 v[92:93], v[112:113], v[16:17]
	v_pk_add_f32 v[16:17], v[112:113], v[16:17] neg_lo:[0,1] neg_hi:[0,1]
	v_pk_add_f32 v[100:101], v[16:17], 0 op_sel:[1,0] op_sel_hi:[0,0] neg_lo:[1,0]
	v_pk_add_f32 v[16:17], v[106:107], v[76:77]
	v_pk_add_f32 v[76:77], v[106:107], v[76:77] neg_lo:[0,1] neg_hi:[0,1]
	v_mov_b32_e32 v112, v76
	v_mov_b32_e32 v113, v77
	v_pk_add_f32 v[76:77], v[70:71], v[18:19]
	v_pk_add_f32 v[18:19], v[70:71], v[18:19] neg_lo:[0,1] neg_hi:[0,1]
	v_pk_add_f32 v[70:71], v[18:19], 0 op_sel:[1,0] op_sel_hi:[0,0] neg_lo:[1,0]
	v_pk_add_f32 v[18:19], v[108:109], v[82:83]
	v_pk_add_f32 v[82:83], v[108:109], v[82:83] neg_lo:[0,1] neg_hi:[0,1]
	v_mov_b32_e32 v108, v82
	v_mov_b32_e32 v109, v83
	v_pk_add_f32 v[82:83], v[90:91], v[72:73]
	v_pk_add_f32 v[72:73], v[90:91], v[72:73] neg_lo:[0,1] neg_hi:[0,1]
	v_pk_add_f32 v[90:91], v[72:73], 0 op_sel:[1,0] op_sel_hi:[0,0] neg_lo:[1,0]
	v_pk_add_f32 v[72:73], v[98:99], v[74:75]
	v_pk_add_f32 v[74:75], v[98:99], v[74:75] neg_lo:[0,1] neg_hi:[0,1]
	v_mov_b32_e32 v106, v74
	v_mov_b32_e32 v107, v75
	v_pk_add_f32 v[74:75], v[84:85], v[80:81]
	v_pk_add_f32 v[80:81], v[84:85], v[80:81] neg_lo:[0,1] neg_hi:[0,1]
	v_pk_add_f32 v[84:85], v[80:81], 0 op_sel:[1,0] op_sel_hi:[0,0] neg_lo:[1,0]
	v_pk_add_f32 v[80:81], v[118:119], v[94:95]
	v_pk_add_f32 v[94:95], v[118:119], v[94:95] neg_lo:[0,1] neg_hi:[0,1]
	v_mov_b32_e32 v118, v94
	v_mov_b32_e32 v119, v95
	v_pk_add_f32 v[94:95], v[114:115], v[0:1]
	v_pk_add_f32 v[0:1], v[114:115], v[0:1] neg_lo:[0,1] neg_hi:[0,1]
	v_pk_add_f32 v[98:99], v[0:1], 0 op_sel:[1,0] op_sel_hi:[0,0] neg_lo:[1,0]
	v_pk_add_f32 v[0:1], v[96:97], v[6:7]
	v_pk_add_f32 v[6:7], v[96:97], v[6:7] neg_lo:[0,1] neg_hi:[0,1]
	v_mov_b32_e32 v114, v6
	v_mov_b32_e32 v115, v7
	v_pk_add_f32 v[6:7], v[102:103], v[10:11]
	v_pk_add_f32 v[10:11], v[102:103], v[10:11] neg_lo:[0,1] neg_hi:[0,1]
	v_mov_b32_e32 v102, v10
	v_mov_b32_e32 v103, v11
	v_pk_add_f32 v[10:11], v[4:5], v[14:15]
	v_pk_add_f32 v[4:5], v[4:5], v[14:15] neg_lo:[0,1] neg_hi:[0,1]
	v_mov_b32_e32 v96, v4
	v_mov_b32_e32 v97, v5
	v_pk_add_f32 v[14:15], v[104:105], v[78:79] neg_lo:[0,1] neg_hi:[0,1]
	v_pk_add_f32 v[4:5], v[104:105], v[78:79]
	v_mov_b32_e32 v104, v14
	v_mov_b32_e32 v105, v15
	v_pk_add_f32 v[14:15], v[2:3], v[12:13]
	v_pk_add_f32 v[2:3], v[2:3], v[12:13] neg_lo:[0,1] neg_hi:[0,1]
	v_mov_b32_e32 v78, v2
	v_mov_b32_e32 v79, v3
	v_pk_add_f32 v[12:13], v[110:111], v[68:69] neg_lo:[0,1] neg_hi:[0,1]
	v_pk_add_f32 v[2:3], v[110:111], v[68:69]
	v_mov_b32_e32 v110, v12
	v_mov_b32_e32 v111, v13
	v_pk_add_f32 v[12:13], v[8:9], v[92:93]
	v_pk_add_f32 v[8:9], v[8:9], v[92:93] neg_lo:[0,1] neg_hi:[0,1]
	v_mov_b32_e32 v92, v8
	v_mov_b32_e32 v93, v9
	v_pk_add_f32 v[68:69], v[116:117], v[100:101] neg_lo:[0,1] neg_hi:[0,1]
	v_pk_add_f32 v[8:9], v[116:117], v[100:101]
	v_mov_b32_e32 v116, v68
	v_mov_b32_e32 v117, v69
	v_pk_add_f32 v[68:69], v[16:17], v[76:77]
	v_pk_add_f32 v[16:17], v[16:17], v[76:77] neg_lo:[0,1] neg_hi:[0,1]
	v_mov_b32_e32 v100, v16
	v_mov_b32_e32 v101, v17
; #define LAS __attribute__((address_space(3)))
; #define SINCOSPI(x, s, c) do { const float hx_ = 0.5f * (x); *(s) = __builtin_amdgcn_sinf(hx_); *(c) = __builtin_amdgcn_cosf(hx_); } while (0)
; #define OPAQUE_I(x) asm volatile("" : "+v"(x))
; template <int R, bool INV> DEV void dft_regs(cf (&v)[R]) {
; #pragma unroll
;     for (int s = R; s >= 2; s >>= 1) {
;         const int h = s >> 1;
; #pragma unroll
;         for (int b = 0; b < R; b += s) {
; #pragma unroll
;             for (int k = 0; k < h; ++k) {
;                 const cf a = v[b + k], c = v[b + k + h];
;                 v[b + k] = a + c;
;                 const cf d = a - c;
;                 const int m = k * (32 / s);
;                 const float wr = tw_cos(m), wi = INV ? tw_sin(m) : -tw_sin(m);
;                 v[b + k + h] = cf{d.x * wr - d.y * wi, d.x * wi + d.y * wr};
;             }
;         }
;     }
; }
; DEV void fft_i1x2(LAS cf* buf0, LAS cf* buf1, cf (&y0)[8], cf (&y1)[8], int tid) {
;     OPAQUE_I(tid);
;     float sn, cs; SINCOSPI(-(float)tid * (2.0f / 8192.0f), &sn, &cs);
;     const cf w = cf{cs, sn}; cf wp = cf{1.f, 0.f};
;     cf v[16], u[16];
;     const LAS cf* p0 = buf0 + PADI(tid); const LAS cf* p1 = buf1 + PADI(tid);
; #pragma unroll
;     for (int p = 0; p < 16; ++p) { v[p] = cmulc(p0[544 * p], wp); u[p] = cmulc(p1[544 * p], wp); wp = cmul(wp, w); }
; DEV void fft_i2(LAS cf* buf, int t8) {
;     ...
;     dft_regs<32, true>(v);
; #pragma unroll
;     for (int q = 0; q < 32; ++q) pb[17 * q] = v[BR32[q]];
	v_pk_add_f32 v[16:17], v[112:113], v[70:71]
	v_pk_add_f32 v[70:71], v[112:113], v[70:71] neg_lo:[0,1] neg_hi:[0,1]
	v_mov_b32_e32 v112, v70
	v_mov_b32_e32 v113, v71
	v_pk_add_f32 v[70:71], v[18:19], v[82:83]
	v_pk_add_f32 v[18:19], v[18:19], v[82:83] neg_lo:[0,1] neg_hi:[0,1]
	v_mov_b32_e32 v82, v18
	v_mov_b32_e32 v83, v19
	v_pk_add_f32 v[76:77], v[108:109], v[90:91] neg_lo:[0,1] neg_hi:[0,1]
	v_pk_add_f32 v[18:19], v[108:109], v[90:91]
	v_mov_b32_e32 v108, v76
	v_mov_b32_e32 v109, v77
	v_pk_add_f32 v[76:77], v[72:73], v[74:75]
	v_pk_add_f32 v[72:73], v[72:73], v[74:75] neg_lo:[0,1] neg_hi:[0,1]
	v_mov_b32_e32 v90, v72
	v_mov_b32_e32 v91, v73
	v_pk_add_f32 v[74:75], v[106:107], v[84:85] neg_lo:[0,1] neg_hi:[0,1]
	v_pk_add_f32 v[72:73], v[106:107], v[84:85]
	v_mov_b32_e32 v106, v74
	v_mov_b32_e32 v107, v75
	v_pk_add_f32 v[74:75], v[80:81], v[94:95]
	v_pk_add_f32 v[80:81], v[80:81], v[94:95] neg_lo:[0,1] neg_hi:[0,1]
	v_mov_b32_e32 v94, v80
	v_mov_b32_e32 v95, v81
	v_pk_add_f32 v[84:85], v[118:119], v[98:99] neg_lo:[0,1] neg_hi:[0,1]
	v_pk_add_f32 v[80:81], v[118:119], v[98:99]
	v_mov_b32_e32 v118, v84
	v_mov_b32_e32 v119, v85
	ds_write2_b64 v86, v[0:1], v[68:69] offset1:17
	ds_write2_b64 v86, v[14:15], v[76:77] offset0:34 offset1:51
	ds_write2_b64 v86, v[10:11], v[70:71] offset0:68 offset1:85
	ds_write2_b64 v86, v[12:13], v[74:75] offset0:102 offset1:119
	ds_write2_b64 v86, v[6:7], v[16:17] offset0:136 offset1:153
	ds_write2_b64 v86, v[2:3], v[72:73] offset0:170 offset1:187
	ds_write2_b64 v86, v[4:5], v[18:19] offset0:204 offset1:221
	ds_write2_b64 v86, v[8:9], v[80:81] offset0:238 offset1:255
	ds_write2_b64 v87, v[114:115], v[100:101] offset0:16 offset1:33
	ds_write2_b64 v87, v[78:79], v[90:91] offset0:50 offset1:67
	ds_write2_b64 v87, v[96:97], v[82:83] offset0:84 offset1:101
	ds_write2_b64 v87, v[92:93], v[94:95] offset0:118 offset1:135
	ds_write2_b64 v87, v[102:103], v[112:113] offset0:152 offset1:169
	ds_write2_b64 v87, v[110:111], v[106:107] offset0:186 offset1:203
	ds_write2_b64 v87, v[104:105], v[108:109] offset0:220 offset1:237
	ds_write2_b64 v88, v[116:117], v[118:119] offset0:126 offset1:143
	s_mov_b32 s2, 0x1800000
	s_mov_b32 s2, 0x3000000
	s_nop 0
	s_mov_b32 s2, 0x4800000
	s_nop 0
	s_waitcnt lgkmcnt(0)
	s_barrier
	s_nop 0
	v_mov_b32_e32 v16, v21
	s_andn2_b64 vcc, exec, s[26:27]
	v_cvt_f32_i32_e32 v17, v16
	v_mul_f32_e32 v17, 0xb9800000, v17
	v_mul_f32_e32 v17, 0.5, v17
	v_sin_f32_e32 v93, v17
	v_cos_f32_e32 v92, v17
	v_ashrrev_i32_e32 v17, 4, v16
	v_add_lshl_u32 v16, v17, v16, 3
	v_add_u32_e32 v163, 0, v16
	v_add_u32_e32 v164, s33, v16
	ds_read_b64 v[166:167], v163
	ds_read_b64 v[168:169], v164
	ds_read_b64 v[170:171], v163 offset:4352
	ds_read_b64 v[172:173], v164 offset:4352
	ds_read_b64 v[174:175], v163 offset:8704
	ds_read_b64 v[176:177], v164 offset:8704
	ds_read_b64 v[178:179], v163 offset:13056
	ds_read_b64 v[180:181], v164 offset:13056
	ds_read_b64 v[182:183], v163 offset:17408
	ds_read_b64 v[184:185], v164 offset:17408
	ds_read_b64 v[186:187], v163 offset:21760
	ds_read_b64 v[188:189], v164 offset:21760
	ds_read_b64 v[190:191], v163 offset:26112
	s_waitcnt lgkmcnt(12)
	v_pk_mul_f32 v[18:19], v[166:167], v[66:67] op_sel:[1,1] op_sel_hi:[1,0]
	v_pk_fma_f32 v[76:77], v[166:167], v[66:67], v[18:19] op_sel_hi:[0,1,1] neg_hi:[1,0,0]
	ds_read_b64 v[166:167], v164 offset:26112
	s_waitcnt lgkmcnt(12)
	v_pk_mul_f32 v[18:19], v[168:169], v[66:67] op_sel:[1,1] op_sel_hi:[1,0]
	v_pk_fma_f32 v[16:17], v[168:169], v[66:67], v[18:19] op_sel_hi:[0,1,1] neg_hi:[1,0,0]
	s_nop 0
	v_pk_mul_f32 v[18:19], v[66:67], v[92:93] op_sel:[1,1] op_sel_hi:[1,0] neg_lo:[1,0]
	v_pk_fma_f32 v[66:67], v[66:67], v[92:93], v[18:19] op_sel_hi:[0,1,1]
	ds_read_b64 v[168:169], v163 offset:30464
	s_waitcnt lgkmcnt(12)
	v_pk_mul_f32 v[68:69], v[170:171], v[66:67] op_sel:[1,1] op_sel_hi:[1,0]
	v_pk_fma_f32 v[78:79], v[170:171], v[66:67], v[68:69] op_sel_hi:[0,1,1] neg_hi:[1,0,0]
	ds_read_b64 v[170:171], v164 offset:30464
	s_waitcnt lgkmcnt(12)
	v_pk_mul_f32 v[68:69], v[172:173], v[66:67] op_sel:[1,1] op_sel_hi:[1,0]
	v_pk_fma_f32 v[18:19], v[172:173], v[66:67], v[68:69] op_sel_hi:[0,1,1] neg_hi:[1,0,0]
	s_nop 0
	v_pk_mul_f32 v[68:69], v[66:67], v[92:93] op_sel:[1,1] op_sel_hi:[1,0] neg_lo:[1,0]
	v_pk_fma_f32 v[70:71], v[66:67], v[92:93], v[68:69] op_sel_hi:[0,1,1]
	ds_read_b64 v[172:173], v163 offset:34816
	s_waitcnt lgkmcnt(12)
	v_pk_mul_f32 v[68:69], v[174:175], v[70:71] op_sel:[1,1] op_sel_hi:[1,0]
	v_pk_fma_f32 v[82:83], v[174:175], v[70:71], v[68:69] op_sel_hi:[0,1,1] neg_hi:[1,0,0]
	ds_read_b64 v[174:175], v164 offset:34816
	s_waitcnt lgkmcnt(12)
	v_pk_mul_f32 v[68:69], v[176:177], v[70:71] op_sel:[1,1] op_sel_hi:[1,0]
	v_pk_fma_f32 v[66:67], v[176:177], v[70:71], v[68:69] op_sel_hi:[0,1,1] neg_hi:[1,0,0]
	s_nop 0
	v_pk_mul_f32 v[68:69], v[70:71], v[92:93] op_sel:[1,1] op_sel_hi:[1,0] neg_lo:[1,0]
	v_pk_fma_f32 v[70:71], v[70:71], v[92:93], v[68:69] op_sel_hi:[0,1,1]
	ds_read_b64 v[176:177], v163 offset:39168
	s_waitcnt lgkmcnt(12)
	v_pk_mul_f32 v[72:73], v[178:179], v[70:71] op_sel:[1,1] op_sel_hi:[1,0]
	v_pk_fma_f32 v[84:85], v[178:179], v[70:71], v[72:73] op_sel_hi:[0,1,1] neg_hi:[1,0,0]
	ds_read_b64 v[178:179], v164 offset:39168
	s_waitcnt lgkmcnt(12)
	v_pk_mul_f32 v[72:73], v[180:181], v[70:71] op_sel:[1,1] op_sel_hi:[1,0]
	v_pk_fma_f32 v[68:69], v[180:181], v[70:71], v[72:73] op_sel_hi:[0,1,1] neg_hi:[1,0,0]
	s_nop 0
	v_pk_mul_f32 v[72:73], v[70:71], v[92:93] op_sel:[1,1] op_sel_hi:[1,0] neg_lo:[1,0]
	v_pk_fma_f32 v[74:75], v[70:71], v[92:93], v[72:73] op_sel_hi:[0,1,1]
	ds_read_b64 v[180:181], v163 offset:43520
	s_waitcnt lgkmcnt(12)
; #define LAS __attribute__((address_space(3)))
; #define SINCOSPI(x, s, c) do { const float hx_ = 0.5f * (x); *(s) = __builtin_amdgcn_sinf(hx_); *(c) = __builtin_amdgcn_cosf(hx_); } while (0)
; DEV void fft_i1x2(LAS cf* buf0, LAS cf* buf1, cf (&y0)[8], cf (&y1)[8], int tid) {
;     ...
;     float sn, cs; SINCOSPI(-(float)tid * (2.0f / 8192.0f), &sn, &cs);
;     const cf w = cf{cs, sn}; cf wp = cf{1.f, 0.f};
;     cf v[16], u[16];
;     const LAS cf* p0 = buf0 + PADI(tid); const LAS cf* p1 = buf1 + PADI(tid);
; #pragma unroll
;     for (int p = 0; p < 16; ++p) { v[p] = cmulc(p0[544 * p], wp); u[p] = cmulc(p1[544 * p], wp); wp = cmul(wp, w); }
	v_pk_mul_f32 v[72:73], v[182:183], v[74:75] op_sel:[1,1] op_sel_hi:[1,0]
	v_pk_fma_f32 v[86:87], v[182:183], v[74:75], v[72:73] op_sel_hi:[0,1,1] neg_hi:[1,0,0]
	ds_read_b64 v[182:183], v164 offset:43520
	s_waitcnt lgkmcnt(12)
	v_pk_mul_f32 v[72:73], v[184:185], v[74:75] op_sel:[1,1] op_sel_hi:[1,0]
	v_pk_fma_f32 v[70:71], v[184:185], v[74:75], v[72:73] op_sel_hi:[0,1,1] neg_hi:[1,0,0]
	s_nop 0
	v_pk_mul_f32 v[72:73], v[74:75], v[92:93] op_sel:[1,1] op_sel_hi:[1,0] neg_lo:[1,0]
	v_pk_fma_f32 v[74:75], v[74:75], v[92:93], v[72:73] op_sel_hi:[0,1,1]
	ds_read_b64 v[184:185], v163 offset:47872
	s_waitcnt lgkmcnt(12)
	v_pk_mul_f32 v[80:81], v[186:187], v[74:75] op_sel:[1,1] op_sel_hi:[1,0]
	v_pk_fma_f32 v[90:91], v[186:187], v[74:75], v[80:81] op_sel_hi:[0,1,1] neg_hi:[1,0,0]
	ds_read_b64 v[186:187], v164 offset:47872
	s_waitcnt lgkmcnt(12)
	v_pk_mul_f32 v[80:81], v[188:189], v[74:75] op_sel:[1,1] op_sel_hi:[1,0]
	v_pk_fma_f32 v[72:73], v[188:189], v[74:75], v[80:81] op_sel_hi:[0,1,1] neg_hi:[1,0,0]
	s_nop 0
	v_pk_mul_f32 v[80:81], v[74:75], v[92:93] op_sel:[1,1] op_sel_hi:[1,0] neg_lo:[1,0]
	v_pk_fma_f32 v[88:89], v[74:75], v[92:93], v[80:81] op_sel_hi:[0,1,1]
	ds_read_b64 v[188:189], v163 offset:52224
	s_waitcnt lgkmcnt(12)
	v_pk_mul_f32 v[80:81], v[190:191], v[88:89] op_sel:[1,1] op_sel_hi:[1,0]
	v_pk_fma_f32 v[94:95], v[190:191], v[88:89], v[80:81] op_sel_hi:[0,1,1] neg_hi:[1,0,0]
	ds_read_b64 v[190:191], v164 offset:52224
	s_waitcnt lgkmcnt(12)
	v_pk_mul_f32 v[80:81], v[166:167], v[88:89] op_sel:[1,1] op_sel_hi:[1,0]
	v_pk_fma_f32 v[74:75], v[166:167], v[88:89], v[80:81] op_sel_hi:[0,1,1] neg_hi:[1,0,0]
	s_nop 0
	v_pk_mul_f32 v[80:81], v[88:89], v[92:93] op_sel:[1,1] op_sel_hi:[1,0] neg_lo:[1,0]
	v_pk_fma_f32 v[88:89], v[88:89], v[92:93], v[80:81] op_sel_hi:[0,1,1]
	ds_read_b64 v[166:167], v163 offset:56576
	s_waitcnt lgkmcnt(12)
	v_pk_mul_f32 v[96:97], v[168:169], v[88:89] op_sel:[1,1] op_sel_hi:[1,0]
	v_pk_fma_f32 v[98:99], v[168:169], v[88:89], v[96:97] op_sel_hi:[0,1,1] neg_hi:[1,0,0]
	ds_read_b64 v[168:169], v164 offset:56576
	s_waitcnt lgkmcnt(12)
	v_pk_mul_f32 v[96:97], v[170:171], v[88:89] op_sel:[1,1] op_sel_hi:[1,0]
	v_pk_fma_f32 v[80:81], v[170:171], v[88:89], v[96:97] op_sel_hi:[0,1,1] neg_hi:[1,0,0]
	s_nop 0
	v_pk_mul_f32 v[96:97], v[88:89], v[92:93] op_sel:[1,1] op_sel_hi:[1,0] neg_lo:[1,0]
	v_pk_fma_f32 v[102:103], v[88:89], v[92:93], v[96:97] op_sel_hi:[0,1,1]
	ds_read_b64 v[170:171], v163 offset:60928
	s_waitcnt lgkmcnt(12)
	v_pk_mul_f32 v[96:97], v[172:173], v[102:103] op_sel:[1,1] op_sel_hi:[1,0]
	v_pk_fma_f32 v[100:101], v[172:173], v[102:103], v[96:97] op_sel_hi:[0,1,1] neg_hi:[1,0,0]
	ds_read_b64 v[172:173], v164 offset:60928
	s_waitcnt lgkmcnt(12)
	v_pk_mul_f32 v[96:97], v[174:175], v[102:103] op_sel:[1,1] op_sel_hi:[1,0]
	v_pk_fma_f32 v[88:89], v[174:175], v[102:103], v[96:97] op_sel_hi:[0,1,1] neg_hi:[1,0,0]
	s_nop 0
	v_pk_mul_f32 v[96:97], v[102:103], v[92:93] op_sel:[1,1] op_sel_hi:[1,0] neg_lo:[1,0]
	v_pk_fma_f32 v[102:103], v[102:103], v[92:93], v[96:97] op_sel_hi:[0,1,1]
	ds_read_b64 v[174:175], v163 offset:65280
	s_waitcnt lgkmcnt(12)
	v_pk_mul_f32 v[104:105], v[176:177], v[102:103] op_sel:[1,1] op_sel_hi:[1,0]
	v_pk_fma_f32 v[112:113], v[176:177], v[102:103], v[104:105] op_sel_hi:[0,1,1] neg_hi:[1,0,0]
	ds_read_b64 v[176:177], v164 offset:65280
	s_waitcnt lgkmcnt(12)
	v_pk_mul_f32 v[104:105], v[178:179], v[102:103] op_sel:[1,1] op_sel_hi:[1,0]
	v_pk_fma_f32 v[96:97], v[178:179], v[102:103], v[104:105] op_sel_hi:[0,1,1] neg_hi:[1,0,0]
	s_nop 0
	v_pk_mul_f32 v[104:105], v[102:103], v[92:93] op_sel:[1,1] op_sel_hi:[1,0] neg_lo:[1,0]
	v_pk_fma_f32 v[106:107], v[102:103], v[92:93], v[104:105] op_sel_hi:[0,1,1]
	s_waitcnt lgkmcnt(11)
	v_pk_mul_f32 v[104:105], v[180:181], v[106:107] op_sel:[1,1] op_sel_hi:[1,0]
	v_pk_fma_f32 v[116:117], v[180:181], v[106:107], v[104:105] op_sel_hi:[0,1,1] neg_hi:[1,0,0]
	s_waitcnt lgkmcnt(10)
	v_pk_mul_f32 v[104:105], v[182:183], v[106:107] op_sel:[1,1] op_sel_hi:[1,0]
	v_pk_fma_f32 v[102:103], v[182:183], v[106:107], v[104:105] op_sel_hi:[0,1,1] neg_hi:[1,0,0]
	s_nop 0
	v_pk_mul_f32 v[104:105], v[106:107], v[92:93] op_sel:[1,1] op_sel_hi:[1,0] neg_lo:[1,0]
	v_pk_fma_f32 v[106:107], v[106:107], v[92:93], v[104:105] op_sel_hi:[0,1,1]
	s_waitcnt lgkmcnt(9)
	v_pk_mul_f32 v[108:109], v[184:185], v[106:107] op_sel:[1,1] op_sel_hi:[1,0]
	v_pk_fma_f32 v[118:119], v[184:185], v[106:107], v[108:109] op_sel_hi:[0,1,1] neg_hi:[1,0,0]
	s_waitcnt lgkmcnt(8)
	v_pk_mul_f32 v[108:109], v[186:187], v[106:107] op_sel:[1,1] op_sel_hi:[1,0]
	v_pk_fma_f32 v[104:105], v[186:187], v[106:107], v[108:109] op_sel_hi:[0,1,1] neg_hi:[1,0,0]
	s_nop 0
	v_pk_mul_f32 v[108:109], v[106:107], v[92:93] op_sel:[1,1] op_sel_hi:[1,0] neg_lo:[1,0]
	v_pk_fma_f32 v[110:111], v[106:107], v[92:93], v[108:109] op_sel_hi:[0,1,1]
	s_waitcnt lgkmcnt(7)
	v_pk_mul_f32 v[108:109], v[188:189], v[110:111] op_sel:[1,1] op_sel_hi:[1,0]
	v_pk_fma_f32 v[120:121], v[188:189], v[110:111], v[108:109] op_sel_hi:[0,1,1] neg_hi:[1,0,0]
	s_waitcnt lgkmcnt(6)
	v_pk_mul_f32 v[108:109], v[190:191], v[110:111] op_sel:[1,1] op_sel_hi:[1,0]
	v_pk_fma_f32 v[106:107], v[190:191], v[110:111], v[108:109] op_sel_hi:[0,1,1] neg_hi:[1,0,0]
	s_nop 0
	v_pk_mul_f32 v[108:109], v[110:111], v[92:93] op_sel:[1,1] op_sel_hi:[1,0] neg_lo:[1,0]
	v_pk_fma_f32 v[110:111], v[110:111], v[92:93], v[108:109] op_sel_hi:[0,1,1]
	s_waitcnt lgkmcnt(5)
	v_pk_mul_f32 v[114:115], v[166:167], v[110:111] op_sel:[1,1] op_sel_hi:[1,0]
	v_pk_fma_f32 v[122:123], v[166:167], v[110:111], v[114:115] op_sel_hi:[0,1,1] neg_hi:[1,0,0]
	s_waitcnt lgkmcnt(4)
	v_pk_mul_f32 v[114:115], v[168:169], v[110:111] op_sel:[1,1] op_sel_hi:[1,0]
	v_pk_fma_f32 v[108:109], v[168:169], v[110:111], v[114:115] op_sel_hi:[0,1,1] neg_hi:[1,0,0]
	s_nop 0
	v_pk_mul_f32 v[114:115], v[110:111], v[92:93] op_sel:[1,1] op_sel_hi:[1,0] neg_lo:[1,0]
	v_pk_fma_f32 v[126:127], v[110:111], v[92:93], v[114:115] op_sel_hi:[0,1,1]
	s_waitcnt lgkmcnt(3)
	v_pk_mul_f32 v[114:115], v[170:171], v[126:127] op_sel:[1,1] op_sel_hi:[1,0]
	v_pk_fma_f32 v[124:125], v[170:171], v[126:127], v[114:115] op_sel_hi:[0,1,1] neg_hi:[1,0,0]
	s_waitcnt lgkmcnt(2)
	v_pk_mul_f32 v[114:115], v[172:173], v[126:127] op_sel:[1,1] op_sel_hi:[1,0]
	v_pk_fma_f32 v[110:111], v[172:173], v[126:127], v[114:115] op_sel_hi:[0,1,1] neg_hi:[1,0,0]
	s_nop 0
	v_pk_mul_f32 v[114:115], v[126:127], v[92:93] op_sel:[1,1] op_sel_hi:[1,0] neg_lo:[1,0]
	v_pk_fma_f32 v[126:127], v[126:127], v[92:93], v[114:115] op_sel_hi:[0,1,1]
	s_waitcnt lgkmcnt(1)
	v_pk_mul_f32 v[114:115], v[174:175], v[126:127] op_sel:[1,1] op_sel_hi:[1,0]
	v_pk_fma_f32 v[92:93], v[174:175], v[126:127], v[114:115] op_sel_hi:[0,1,1] neg_hi:[1,0,0]
	s_waitcnt lgkmcnt(0)
	v_pk_mul_f32 v[164:165], v[176:177], v[126:127] op_sel:[1,1] op_sel_hi:[1,0]
	v_pk_fma_f32 v[114:115], v[176:177], v[126:127], v[164:165] op_sel_hi:[0,1,1] neg_hi:[1,0,0]
	s_barrier
; #define LAS __attribute__((address_space(3)))
; DEV void hyena_commit_rows(LAS unsigned char* lds, const u32x4 (&r)[4], int tid) {
; #pragma unroll
;     for (int b = 0; b < 4; ++b) *(LAS u32x4*)(lds + b * 8192 + tid * 16) = r[b];
; }
; DEV void hyena_units(int c0, int cstride, const bf16_t* UT, bf16_t* YHT, const unsigned* KF, const float* convw  , const float* convb  , const float* hyb  , LAS unsigned char* lds, int tid, bool abl = false) {
;     ...
;             hyena_commit_rows(lds, r, tid);
;             if (o == 1 && c + cstride < 1024) hyena_issue_rows(UT, 0, c + cstride, r, tid);
	s_waitcnt vmcnt(3)
	ds_write_b128 v128, v[222:225]
	s_waitcnt vmcnt(2)
	ds_write_b128 v128, v[226:229] offset:8192
	s_waitcnt vmcnt(1)
	ds_write_b128 v128, v[236:239] offset:16384
	s_waitcnt vmcnt(0)
	ds_write_b128 v128, v[240:243] offset:24576
	s_cbranch_vccnz .LBB0_518
	s_andn2_b64 vcc, exec, s[20:21]
	s_cbranch_vccnz .LBB0_518
	global_load_dwordx4 v[0:3], v[58:59], off
	global_load_dwordx4 v[4:7], v[60:61], off
	global_load_dwordx4 v[8:11], v[62:63], off
	global_load_dwordx4 v[12:15], v[64:65], off
	s_branch .LBB0_518
